# DSA attention: no gather / Q fetch / final wait after a wave's last query (the never-consumed prefetch of the next K batch and its drain are gone)
# baseline (speedup 1.0000x reference)
.Lattn_q8:
	s_add_i32 s18, s14, 64
	s_mov_b64 s[16:17], s[2:3]
	v_add_u32_e32 v161, s18, v156
	ds_read_u16 v0, v161 offset:0
	ds_read_u16 v1, v161 offset:8
	ds_read_u16 v2, v161 offset:16
	ds_read_u16 v3, v161 offset:24
	ds_read_u16 v4, v161 offset:32
	ds_read_u16 v5, v161 offset:40
	ds_read_u16 v6, v161 offset:48
	ds_read_u16 v7, v161 offset:56
	s_waitcnt lgkmcnt(7)
	s_add_i32 m0, s8, 0x2000
	v_lshl_add_u32 v8, v0, 8, v10
	global_load_lds_dwordx4 v8, s[16:17]
	s_waitcnt lgkmcnt(6)
	s_add_i32 m0, s8, 0x2400
	v_lshl_add_u32 v9, v1, 8, v11
	global_load_lds_dwordx4 v9, s[16:17]
	s_waitcnt lgkmcnt(5)
	s_add_i32 m0, s8, 0x2800
	v_lshl_add_u32 v8, v2, 8, v12
	global_load_lds_dwordx4 v8, s[16:17]
	s_waitcnt lgkmcnt(4)
	s_add_i32 m0, s8, 0x2c00
	v_lshl_add_u32 v9, v3, 8, v13
	global_load_lds_dwordx4 v9, s[16:17]
	s_waitcnt lgkmcnt(3)
	s_add_i32 m0, s8, 0x3000
	v_lshl_add_u32 v8, v4, 8, v10
	global_load_lds_dwordx4 v8, s[16:17]
	s_waitcnt lgkmcnt(2)
	s_add_i32 m0, s8, 0x3400
	v_lshl_add_u32 v9, v5, 8, v11
	global_load_lds_dwordx4 v9, s[16:17]
	s_waitcnt lgkmcnt(1)
	s_add_i32 m0, s8, 0x3800
	v_lshl_add_u32 v8, v6, 8, v12
	global_load_lds_dwordx4 v8, s[16:17]
	s_waitcnt lgkmcnt(0)
	s_add_i32 m0, s8, 0x3c00
	v_lshl_add_u32 v9, v7, 8, v13
	global_load_lds_dwordx4 v9, s[16:17]
	s_waitcnt vmcnt(8)
	ds_read_b128 v[104:107], v18 offset:0
	ds_read_b128 v[108:111], v19 offset:0
	ds_read_b128 v[112:115], v20 offset:0
	ds_read_b128 v[116:119], v21 offset:0
	ds_read_b128 v[120:123], v18 offset:4096
	ds_read_b128 v[124:127], v19 offset:4096
	ds_read_b128 v[128:131], v20 offset:4096
	ds_read_b128 v[132:135], v21 offset:4096
	s_waitcnt lgkmcnt(7)
	v_mfma_f32_16x16x32_bf16 v[136:139], v[104:107], v[88:91], 0
	s_waitcnt lgkmcnt(6)
	v_mfma_f32_16x16x32_bf16 v[136:139], v[108:111], v[92:95], v[136:139]
	s_waitcnt lgkmcnt(5)
	v_mfma_f32_16x16x32_bf16 v[136:139], v[112:115], v[96:99], v[136:139]
	s_waitcnt lgkmcnt(4)
	v_mfma_f32_16x16x32_bf16 v[136:139], v[116:119], v[100:103], v[136:139]
	s_waitcnt lgkmcnt(3)
	v_mfma_f32_16x16x32_bf16 v[140:143], v[120:123], v[88:91], 0
	s_waitcnt lgkmcnt(2)
	v_mfma_f32_16x16x32_bf16 v[140:143], v[124:127], v[92:95], v[140:143]
	s_waitcnt lgkmcnt(1)
	v_mfma_f32_16x16x32_bf16 v[140:143], v[128:131], v[96:99], v[140:143]
	s_waitcnt lgkmcnt(0)
	v_mfma_f32_16x16x32_bf16 v[140:143], v[132:135], v[100:103], v[140:143]
	v_mul_f32_e32 v24, 0x3db504f3, v136
	v_mul_f32_e32 v25, 0x3db504f3, v137
	v_mul_f32_e32 v26, 0x3db504f3, v138
	v_mul_f32_e32 v27, 0x3db504f3, v139
	s_nop 3
	v_mul_f32_e32 v28, 0x3db504f3, v140
	v_mul_f32_e32 v29, 0x3db504f3, v141
	v_mul_f32_e32 v30, 0x3db504f3, v142
	v_mul_f32_e32 v31, 0x3db504f3, v143
	s_add_i32 s18, s14, 128
	s_mov_b64 s[16:17], s[2:3]
	v_add_u32_e32 v161, s18, v156
	ds_read_u16 v0, v161 offset:0
	ds_read_u16 v1, v161 offset:8
	ds_read_u16 v2, v161 offset:16
	ds_read_u16 v3, v161 offset:24
	ds_read_u16 v4, v161 offset:32
	ds_read_u16 v5, v161 offset:40
	ds_read_u16 v6, v161 offset:48
	ds_read_u16 v7, v161 offset:56
	s_waitcnt lgkmcnt(7)
	s_add_i32 m0, s8, 0x0
	v_lshl_add_u32 v8, v0, 8, v10
	global_load_lds_dwordx4 v8, s[16:17]
	s_waitcnt lgkmcnt(6)
	s_add_i32 m0, s8, 0x400
	v_lshl_add_u32 v9, v1, 8, v11
	global_load_lds_dwordx4 v9, s[16:17]
	s_waitcnt lgkmcnt(5)
	s_add_i32 m0, s8, 0x800
	v_lshl_add_u32 v8, v2, 8, v12
	global_load_lds_dwordx4 v8, s[16:17]
	s_waitcnt lgkmcnt(4)
	s_add_i32 m0, s8, 0xc00
	v_lshl_add_u32 v9, v3, 8, v13
	global_load_lds_dwordx4 v9, s[16:17]
	s_waitcnt lgkmcnt(3)
	s_add_i32 m0, s8, 0x1000
	v_lshl_add_u32 v8, v4, 8, v10
	global_load_lds_dwordx4 v8, s[16:17]
	s_waitcnt lgkmcnt(2)
	s_add_i32 m0, s8, 0x1400
	v_lshl_add_u32 v9, v5, 8, v11
	global_load_lds_dwordx4 v9, s[16:17]
	s_waitcnt lgkmcnt(1)
	s_add_i32 m0, s8, 0x1800
	v_lshl_add_u32 v8, v6, 8, v12
	global_load_lds_dwordx4 v8, s[16:17]
	s_waitcnt lgkmcnt(0)
	s_add_i32 m0, s8, 0x1c00
	v_lshl_add_u32 v9, v7, 8, v13
	global_load_lds_dwordx4 v9, s[16:17]
	s_waitcnt vmcnt(8)
	ds_read_b128 v[104:107], v18 offset:8192
	ds_read_b128 v[108:111], v19 offset:8192
	ds_read_b128 v[112:115], v20 offset:8192
	ds_read_b128 v[116:119], v21 offset:8192
	ds_read_b128 v[120:123], v18 offset:12288
	ds_read_b128 v[124:127], v19 offset:12288
	ds_read_b128 v[128:131], v20 offset:12288
	ds_read_b128 v[132:135], v21 offset:12288
	s_waitcnt lgkmcnt(7)
	v_mfma_f32_16x16x32_bf16 v[136:139], v[104:107], v[88:91], 0
	s_waitcnt lgkmcnt(6)
	v_mfma_f32_16x16x32_bf16 v[136:139], v[108:111], v[92:95], v[136:139]
	s_waitcnt lgkmcnt(5)
	v_mfma_f32_16x16x32_bf16 v[136:139], v[112:115], v[96:99], v[136:139]
	s_waitcnt lgkmcnt(4)
	v_mfma_f32_16x16x32_bf16 v[136:139], v[116:119], v[100:103], v[136:139]
	s_waitcnt lgkmcnt(3)
	v_mfma_f32_16x16x32_bf16 v[140:143], v[120:123], v[88:91], 0
	s_waitcnt lgkmcnt(2)
	v_mfma_f32_16x16x32_bf16 v[140:143], v[124:127], v[92:95], v[140:143]
	s_waitcnt lgkmcnt(1)
	v_mfma_f32_16x16x32_bf16 v[140:143], v[128:131], v[96:99], v[140:143]
	s_waitcnt lgkmcnt(0)
	v_mfma_f32_16x16x32_bf16 v[140:143], v[132:135], v[100:103], v[140:143]
	v_mul_f32_e32 v32, 0x3db504f3, v136
	v_mul_f32_e32 v33, 0x3db504f3, v137
	v_mul_f32_e32 v34, 0x3db504f3, v138
	v_mul_f32_e32 v35, 0x3db504f3, v139
	s_nop 3
	v_mul_f32_e32 v36, 0x3db504f3, v140
	v_mul_f32_e32 v37, 0x3db504f3, v141
	v_mul_f32_e32 v38, 0x3db504f3, v142
	v_mul_f32_e32 v39, 0x3db504f3, v143
	s_add_i32 s18, s14, 192
	s_mov_b64 s[16:17], s[2:3]
	v_add_u32_e32 v161, s18, v156
	ds_read_u16 v0, v161 offset:0
	ds_read_u16 v1, v161 offset:8
	ds_read_u16 v2, v161 offset:16
	ds_read_u16 v3, v161 offset:24
	ds_read_u16 v4, v161 offset:32
	ds_read_u16 v5, v161 offset:40
	ds_read_u16 v6, v161 offset:48
	ds_read_u16 v7, v161 offset:56
	s_waitcnt lgkmcnt(7)
	s_add_i32 m0, s8, 0x2000
	v_lshl_add_u32 v8, v0, 8, v10
	global_load_lds_dwordx4 v8, s[16:17]
	s_waitcnt lgkmcnt(6)
	s_add_i32 m0, s8, 0x2400
	v_lshl_add_u32 v9, v1, 8, v11
	global_load_lds_dwordx4 v9, s[16:17]
	s_waitcnt lgkmcnt(5)
	s_add_i32 m0, s8, 0x2800
	v_lshl_add_u32 v8, v2, 8, v12
	global_load_lds_dwordx4 v8, s[16:17]
	s_waitcnt lgkmcnt(4)
	s_add_i32 m0, s8, 0x2c00
	v_lshl_add_u32 v9, v3, 8, v13
	global_load_lds_dwordx4 v9, s[16:17]
	s_waitcnt lgkmcnt(3)
	s_add_i32 m0, s8, 0x3000
	v_lshl_add_u32 v8, v4, 8, v10
	global_load_lds_dwordx4 v8, s[16:17]
	s_waitcnt lgkmcnt(2)
	s_add_i32 m0, s8, 0x3400
	v_lshl_add_u32 v9, v5, 8, v11
	global_load_lds_dwordx4 v9, s[16:17]
	s_waitcnt lgkmcnt(1)
	s_add_i32 m0, s8, 0x3800
	v_lshl_add_u32 v8, v6, 8, v12
	global_load_lds_dwordx4 v8, s[16:17]
	s_waitcnt lgkmcnt(0)
	s_add_i32 m0, s8, 0x3c00
	v_lshl_add_u32 v9, v7, 8, v13
	global_load_lds_dwordx4 v9, s[16:17]
	s_waitcnt vmcnt(8)
	ds_read_b128 v[104:107], v18 offset:0
	ds_read_b128 v[108:111], v19 offset:0
	ds_read_b128 v[112:115], v20 offset:0
	ds_read_b128 v[116:119], v21 offset:0
	ds_read_b128 v[120:123], v18 offset:4096
	ds_read_b128 v[124:127], v19 offset:4096
	ds_read_b128 v[128:131], v20 offset:4096
	ds_read_b128 v[132:135], v21 offset:4096
	s_waitcnt lgkmcnt(7)
	v_mfma_f32_16x16x32_bf16 v[136:139], v[104:107], v[88:91], 0
	s_waitcnt lgkmcnt(6)
	v_mfma_f32_16x16x32_bf16 v[136:139], v[108:111], v[92:95], v[136:139]
	s_waitcnt lgkmcnt(5)
	v_mfma_f32_16x16x32_bf16 v[136:139], v[112:115], v[96:99], v[136:139]
	s_waitcnt lgkmcnt(4)
	v_mfma_f32_16x16x32_bf16 v[136:139], v[116:119], v[100:103], v[136:139]
	s_waitcnt lgkmcnt(3)
	v_mfma_f32_16x16x32_bf16 v[140:143], v[120:123], v[88:91], 0
	s_waitcnt lgkmcnt(2)
	v_mfma_f32_16x16x32_bf16 v[140:143], v[124:127], v[92:95], v[140:143]
	s_waitcnt lgkmcnt(1)
	v_mfma_f32_16x16x32_bf16 v[140:143], v[128:131], v[96:99], v[140:143]
	s_waitcnt lgkmcnt(0)
	v_mfma_f32_16x16x32_bf16 v[140:143], v[132:135], v[100:103], v[140:143]
	v_mul_f32_e32 v40, 0x3db504f3, v136
	v_mul_f32_e32 v41, 0x3db504f3, v137
	v_mul_f32_e32 v42, 0x3db504f3, v138
	v_mul_f32_e32 v43, 0x3db504f3, v139
	s_nop 3
	v_mul_f32_e32 v44, 0x3db504f3, v140
	v_mul_f32_e32 v45, 0x3db504f3, v141
	v_mul_f32_e32 v46, 0x3db504f3, v142
	v_mul_f32_e32 v47, 0x3db504f3, v143
	s_add_i32 s18, s14, 256
	s_mov_b64 s[16:17], s[2:3]
	v_add_u32_e32 v161, s18, v156
	ds_read_u16 v0, v161 offset:0
	ds_read_u16 v1, v161 offset:8
	ds_read_u16 v2, v161 offset:16
	ds_read_u16 v3, v161 offset:24
	ds_read_u16 v4, v161 offset:32
	ds_read_u16 v5, v161 offset:40
	ds_read_u16 v6, v161 offset:48
	ds_read_u16 v7, v161 offset:56
	s_waitcnt lgkmcnt(7)
	s_add_i32 m0, s8, 0x0
	v_lshl_add_u32 v8, v0, 8, v10
	global_load_lds_dwordx4 v8, s[16:17]
	s_waitcnt lgkmcnt(6)
	s_add_i32 m0, s8, 0x400
	v_lshl_add_u32 v9, v1, 8, v11
	global_load_lds_dwordx4 v9, s[16:17]
	s_waitcnt lgkmcnt(5)
	s_add_i32 m0, s8, 0x800
	v_lshl_add_u32 v8, v2, 8, v12
	global_load_lds_dwordx4 v8, s[16:17]
	s_waitcnt lgkmcnt(4)
	s_add_i32 m0, s8, 0xc00
	v_lshl_add_u32 v9, v3, 8, v13
	global_load_lds_dwordx4 v9, s[16:17]
	s_waitcnt lgkmcnt(3)
	s_add_i32 m0, s8, 0x1000
	v_lshl_add_u32 v8, v4, 8, v10
	global_load_lds_dwordx4 v8, s[16:17]
	s_waitcnt lgkmcnt(2)
	s_add_i32 m0, s8, 0x1400
	v_lshl_add_u32 v9, v5, 8, v11
	global_load_lds_dwordx4 v9, s[16:17]
	s_waitcnt lgkmcnt(1)
	s_add_i32 m0, s8, 0x1800
	v_lshl_add_u32 v8, v6, 8, v12
	global_load_lds_dwordx4 v8, s[16:17]
	s_waitcnt lgkmcnt(0)
	s_add_i32 m0, s8, 0x1c00
	v_lshl_add_u32 v9, v7, 8, v13
	global_load_lds_dwordx4 v9, s[16:17]
	s_waitcnt vmcnt(8)
	ds_read_b128 v[104:107], v18 offset:8192
	ds_read_b128 v[108:111], v19 offset:8192
	ds_read_b128 v[112:115], v20 offset:8192
	ds_read_b128 v[116:119], v21 offset:8192
	ds_read_b128 v[120:123], v18 offset:12288
	ds_read_b128 v[124:127], v19 offset:12288
	ds_read_b128 v[128:131], v20 offset:12288
	ds_read_b128 v[132:135], v21 offset:12288
	s_waitcnt lgkmcnt(7)
	v_mfma_f32_16x16x32_bf16 v[136:139], v[104:107], v[88:91], 0
	s_waitcnt lgkmcnt(6)
	v_mfma_f32_16x16x32_bf16 v[136:139], v[108:111], v[92:95], v[136:139]
	s_waitcnt lgkmcnt(5)
	v_mfma_f32_16x16x32_bf16 v[136:139], v[112:115], v[96:99], v[136:139]
	s_waitcnt lgkmcnt(4)
	v_mfma_f32_16x16x32_bf16 v[136:139], v[116:119], v[100:103], v[136:139]
	s_waitcnt lgkmcnt(3)
	v_mfma_f32_16x16x32_bf16 v[140:143], v[120:123], v[88:91], 0
	s_waitcnt lgkmcnt(2)
	v_mfma_f32_16x16x32_bf16 v[140:143], v[124:127], v[92:95], v[140:143]
	s_waitcnt lgkmcnt(1)
	v_mfma_f32_16x16x32_bf16 v[140:143], v[128:131], v[96:99], v[140:143]
	s_waitcnt lgkmcnt(0)
	v_mfma_f32_16x16x32_bf16 v[140:143], v[132:135], v[100:103], v[140:143]
	v_mul_f32_e32 v48, 0x3db504f3, v136
	v_mul_f32_e32 v49, 0x3db504f3, v137
	v_mul_f32_e32 v50, 0x3db504f3, v138
	v_mul_f32_e32 v51, 0x3db504f3, v139
	s_nop 3
	v_mul_f32_e32 v52, 0x3db504f3, v140
	v_mul_f32_e32 v53, 0x3db504f3, v141
	v_mul_f32_e32 v54, 0x3db504f3, v142
	v_mul_f32_e32 v55, 0x3db504f3, v143
	s_add_i32 s18, s14, 320
	s_mov_b64 s[16:17], s[2:3]
	v_add_u32_e32 v161, s18, v156
	ds_read_u16 v0, v161 offset:0
	ds_read_u16 v1, v161 offset:8
	ds_read_u16 v2, v161 offset:16
	ds_read_u16 v3, v161 offset:24
	ds_read_u16 v4, v161 offset:32
	ds_read_u16 v5, v161 offset:40
	ds_read_u16 v6, v161 offset:48
	ds_read_u16 v7, v161 offset:56
	s_waitcnt lgkmcnt(7)
	s_add_i32 m0, s8, 0x2000
	v_lshl_add_u32 v8, v0, 8, v10
	global_load_lds_dwordx4 v8, s[16:17]
	s_waitcnt lgkmcnt(6)
	s_add_i32 m0, s8, 0x2400
	v_lshl_add_u32 v9, v1, 8, v11
	global_load_lds_dwordx4 v9, s[16:17]
	s_waitcnt lgkmcnt(5)
	s_add_i32 m0, s8, 0x2800
	v_lshl_add_u32 v8, v2, 8, v12
	global_load_lds_dwordx4 v8, s[16:17]
	s_waitcnt lgkmcnt(4)
	s_add_i32 m0, s8, 0x2c00
	v_lshl_add_u32 v9, v3, 8, v13
	global_load_lds_dwordx4 v9, s[16:17]
	s_waitcnt lgkmcnt(3)
	s_add_i32 m0, s8, 0x3000
	v_lshl_add_u32 v8, v4, 8, v10
	global_load_lds_dwordx4 v8, s[16:17]
	s_waitcnt lgkmcnt(2)
	s_add_i32 m0, s8, 0x3400
	v_lshl_add_u32 v9, v5, 8, v11
	global_load_lds_dwordx4 v9, s[16:17]
	s_waitcnt lgkmcnt(1)
	s_add_i32 m0, s8, 0x3800
	v_lshl_add_u32 v8, v6, 8, v12
	global_load_lds_dwordx4 v8, s[16:17]
	s_waitcnt lgkmcnt(0)
	s_add_i32 m0, s8, 0x3c00
	v_lshl_add_u32 v9, v7, 8, v13
	global_load_lds_dwordx4 v9, s[16:17]
	s_waitcnt vmcnt(8)
	ds_read_b128 v[104:107], v18 offset:0
	ds_read_b128 v[108:111], v19 offset:0
	ds_read_b128 v[112:115], v20 offset:0
	ds_read_b128 v[116:119], v21 offset:0
	ds_read_b128 v[120:123], v18 offset:4096
	ds_read_b128 v[124:127], v19 offset:4096
	ds_read_b128 v[128:131], v20 offset:4096
	ds_read_b128 v[132:135], v21 offset:4096
	s_waitcnt lgkmcnt(7)
	v_mfma_f32_16x16x32_bf16 v[136:139], v[104:107], v[88:91], 0
	s_waitcnt lgkmcnt(6)
	v_mfma_f32_16x16x32_bf16 v[136:139], v[108:111], v[92:95], v[136:139]
	s_waitcnt lgkmcnt(5)
	v_mfma_f32_16x16x32_bf16 v[136:139], v[112:115], v[96:99], v[136:139]
	s_waitcnt lgkmcnt(4)
	v_mfma_f32_16x16x32_bf16 v[136:139], v[116:119], v[100:103], v[136:139]
	s_waitcnt lgkmcnt(3)
	v_mfma_f32_16x16x32_bf16 v[140:143], v[120:123], v[88:91], 0
	s_waitcnt lgkmcnt(2)
	v_mfma_f32_16x16x32_bf16 v[140:143], v[124:127], v[92:95], v[140:143]
	s_waitcnt lgkmcnt(1)
	v_mfma_f32_16x16x32_bf16 v[140:143], v[128:131], v[96:99], v[140:143]
	s_waitcnt lgkmcnt(0)
	v_mfma_f32_16x16x32_bf16 v[140:143], v[132:135], v[100:103], v[140:143]
	v_mul_f32_e32 v56, 0x3db504f3, v136
	v_mul_f32_e32 v57, 0x3db504f3, v137
	v_mul_f32_e32 v58, 0x3db504f3, v138
	v_mul_f32_e32 v59, 0x3db504f3, v139
	s_nop 3
	v_mul_f32_e32 v60, 0x3db504f3, v140
	v_mul_f32_e32 v61, 0x3db504f3, v141
	v_mul_f32_e32 v62, 0x3db504f3, v142
	v_mul_f32_e32 v63, 0x3db504f3, v143
	s_add_i32 s18, s14, 384
	s_mov_b64 s[16:17], s[2:3]
	v_add_u32_e32 v161, s18, v156
	ds_read_u16 v0, v161 offset:0
	ds_read_u16 v1, v161 offset:8
	ds_read_u16 v2, v161 offset:16
	ds_read_u16 v3, v161 offset:24
	ds_read_u16 v4, v161 offset:32
	ds_read_u16 v5, v161 offset:40
	ds_read_u16 v6, v161 offset:48
	ds_read_u16 v7, v161 offset:56
	s_waitcnt lgkmcnt(7)
	s_add_i32 m0, s8, 0x0
	v_lshl_add_u32 v8, v0, 8, v10
	global_load_lds_dwordx4 v8, s[16:17]
	s_waitcnt lgkmcnt(6)
	s_add_i32 m0, s8, 0x400
	v_lshl_add_u32 v9, v1, 8, v11
	global_load_lds_dwordx4 v9, s[16:17]
	s_waitcnt lgkmcnt(5)
	s_add_i32 m0, s8, 0x800
	v_lshl_add_u32 v8, v2, 8, v12
	global_load_lds_dwordx4 v8, s[16:17]
	s_waitcnt lgkmcnt(4)
	s_add_i32 m0, s8, 0xc00
	v_lshl_add_u32 v9, v3, 8, v13
	global_load_lds_dwordx4 v9, s[16:17]
	s_waitcnt lgkmcnt(3)
	s_add_i32 m0, s8, 0x1000
	v_lshl_add_u32 v8, v4, 8, v10
	global_load_lds_dwordx4 v8, s[16:17]
	s_waitcnt lgkmcnt(2)
	s_add_i32 m0, s8, 0x1400
	v_lshl_add_u32 v9, v5, 8, v11
	global_load_lds_dwordx4 v9, s[16:17]
	s_waitcnt lgkmcnt(1)
	s_add_i32 m0, s8, 0x1800
	v_lshl_add_u32 v8, v6, 8, v12
	global_load_lds_dwordx4 v8, s[16:17]
	s_waitcnt lgkmcnt(0)
	s_add_i32 m0, s8, 0x1c00
	v_lshl_add_u32 v9, v7, 8, v13
	global_load_lds_dwordx4 v9, s[16:17]
	s_waitcnt vmcnt(8)
	ds_read_b128 v[104:107], v18 offset:8192
	ds_read_b128 v[108:111], v19 offset:8192
	ds_read_b128 v[112:115], v20 offset:8192
	ds_read_b128 v[116:119], v21 offset:8192
	ds_read_b128 v[120:123], v18 offset:12288
	ds_read_b128 v[124:127], v19 offset:12288
	ds_read_b128 v[128:131], v20 offset:12288
	ds_read_b128 v[132:135], v21 offset:12288
	s_waitcnt lgkmcnt(7)
	v_mfma_f32_16x16x32_bf16 v[136:139], v[104:107], v[88:91], 0
	s_waitcnt lgkmcnt(6)
	v_mfma_f32_16x16x32_bf16 v[136:139], v[108:111], v[92:95], v[136:139]
	s_waitcnt lgkmcnt(5)
	v_mfma_f32_16x16x32_bf16 v[136:139], v[112:115], v[96:99], v[136:139]
	s_waitcnt lgkmcnt(4)
	v_mfma_f32_16x16x32_bf16 v[136:139], v[116:119], v[100:103], v[136:139]
	s_waitcnt lgkmcnt(3)
	v_mfma_f32_16x16x32_bf16 v[140:143], v[120:123], v[88:91], 0
	s_waitcnt lgkmcnt(2)
	v_mfma_f32_16x16x32_bf16 v[140:143], v[124:127], v[92:95], v[140:143]
	s_waitcnt lgkmcnt(1)
	v_mfma_f32_16x16x32_bf16 v[140:143], v[128:131], v[96:99], v[140:143]
	s_waitcnt lgkmcnt(0)
	v_mfma_f32_16x16x32_bf16 v[140:143], v[132:135], v[100:103], v[140:143]
	v_mul_f32_e32 v64, 0x3db504f3, v136
	v_mul_f32_e32 v65, 0x3db504f3, v137
	v_mul_f32_e32 v66, 0x3db504f3, v138
	v_mul_f32_e32 v67, 0x3db504f3, v139
	s_nop 3
	v_mul_f32_e32 v68, 0x3db504f3, v140
	v_mul_f32_e32 v69, 0x3db504f3, v141
	v_mul_f32_e32 v70, 0x3db504f3, v142
	v_mul_f32_e32 v71, 0x3db504f3, v143
	s_add_i32 s18, s14, 448
	s_mov_b64 s[16:17], s[2:3]
	v_add_u32_e32 v161, s18, v156
	ds_read_u16 v0, v161 offset:0
	ds_read_u16 v1, v161 offset:8
	ds_read_u16 v2, v161 offset:16
	ds_read_u16 v3, v161 offset:24
	ds_read_u16 v4, v161 offset:32
	ds_read_u16 v5, v161 offset:40
	ds_read_u16 v6, v161 offset:48
	ds_read_u16 v7, v161 offset:56
	s_waitcnt lgkmcnt(7)
	s_add_i32 m0, s8, 0x2000
	v_lshl_add_u32 v8, v0, 8, v10
	global_load_lds_dwordx4 v8, s[16:17]
	s_waitcnt lgkmcnt(6)
	s_add_i32 m0, s8, 0x2400
	v_lshl_add_u32 v9, v1, 8, v11
	global_load_lds_dwordx4 v9, s[16:17]
	s_waitcnt lgkmcnt(5)
	s_add_i32 m0, s8, 0x2800
	v_lshl_add_u32 v8, v2, 8, v12
	global_load_lds_dwordx4 v8, s[16:17]
	s_waitcnt lgkmcnt(4)
	s_add_i32 m0, s8, 0x2c00
	v_lshl_add_u32 v9, v3, 8, v13
	global_load_lds_dwordx4 v9, s[16:17]
	s_waitcnt lgkmcnt(3)
	s_add_i32 m0, s8, 0x3000
	v_lshl_add_u32 v8, v4, 8, v10
	global_load_lds_dwordx4 v8, s[16:17]
	s_waitcnt lgkmcnt(2)
	s_add_i32 m0, s8, 0x3400
	v_lshl_add_u32 v9, v5, 8, v11
	global_load_lds_dwordx4 v9, s[16:17]
	s_waitcnt lgkmcnt(1)
	s_add_i32 m0, s8, 0x3800
	v_lshl_add_u32 v8, v6, 8, v12
	global_load_lds_dwordx4 v8, s[16:17]
	s_waitcnt lgkmcnt(0)
	s_add_i32 m0, s8, 0x3c00
	v_lshl_add_u32 v9, v7, 8, v13
	global_load_lds_dwordx4 v9, s[16:17]
	s_waitcnt vmcnt(8)
	ds_read_b128 v[104:107], v18 offset:0
	ds_read_b128 v[108:111], v19 offset:0
	ds_read_b128 v[112:115], v20 offset:0
	ds_read_b128 v[116:119], v21 offset:0
	ds_read_b128 v[120:123], v18 offset:4096
	ds_read_b128 v[124:127], v19 offset:4096
	ds_read_b128 v[128:131], v20 offset:4096
	ds_read_b128 v[132:135], v21 offset:4096
	s_waitcnt lgkmcnt(7)
	v_mfma_f32_16x16x32_bf16 v[136:139], v[104:107], v[88:91], 0
	s_waitcnt lgkmcnt(6)
	v_mfma_f32_16x16x32_bf16 v[136:139], v[108:111], v[92:95], v[136:139]
	s_waitcnt lgkmcnt(5)
	v_mfma_f32_16x16x32_bf16 v[136:139], v[112:115], v[96:99], v[136:139]
	s_waitcnt lgkmcnt(4)
	v_mfma_f32_16x16x32_bf16 v[136:139], v[116:119], v[100:103], v[136:139]
	s_waitcnt lgkmcnt(3)
	v_mfma_f32_16x16x32_bf16 v[140:143], v[120:123], v[88:91], 0
	s_waitcnt lgkmcnt(2)
	v_mfma_f32_16x16x32_bf16 v[140:143], v[124:127], v[92:95], v[140:143]
	s_waitcnt lgkmcnt(1)
	v_mfma_f32_16x16x32_bf16 v[140:143], v[128:131], v[96:99], v[140:143]
	s_waitcnt lgkmcnt(0)
	v_mfma_f32_16x16x32_bf16 v[140:143], v[132:135], v[100:103], v[140:143]
	v_mul_f32_e32 v72, 0x3db504f3, v136
	v_mul_f32_e32 v73, 0x3db504f3, v137
	v_mul_f32_e32 v74, 0x3db504f3, v138
	v_mul_f32_e32 v75, 0x3db504f3, v139
	s_nop 3
	v_mul_f32_e32 v76, 0x3db504f3, v140
	v_mul_f32_e32 v77, 0x3db504f3, v141
	v_mul_f32_e32 v78, 0x3db504f3, v142
	v_mul_f32_e32 v79, 0x3db504f3, v143
	s_mov_b32 s18, s14
	s_mov_b64 s[16:17], s[4:5]
	v_add_u32_e32 v161, s18, v156
	ds_read_u16 v0, v161 offset:0
	ds_read_u16 v1, v161 offset:8
	ds_read_u16 v2, v161 offset:16
	ds_read_u16 v3, v161 offset:24
	ds_read_u16 v4, v161 offset:32
	ds_read_u16 v5, v161 offset:40
	ds_read_u16 v6, v161 offset:48
	ds_read_u16 v7, v161 offset:56
	s_waitcnt lgkmcnt(7)
	s_add_i32 m0, s8, 0x0
	v_lshl_add_u32 v8, v0, 8, v10
	global_load_lds_dwordx4 v8, s[16:17]
	s_waitcnt lgkmcnt(6)
	s_add_i32 m0, s8, 0x400
	v_lshl_add_u32 v9, v1, 8, v11
	global_load_lds_dwordx4 v9, s[16:17]
	s_waitcnt lgkmcnt(5)
	s_add_i32 m0, s8, 0x800
	v_lshl_add_u32 v8, v2, 8, v12
	global_load_lds_dwordx4 v8, s[16:17]
	s_waitcnt lgkmcnt(4)
	s_add_i32 m0, s8, 0xc00
	v_lshl_add_u32 v9, v3, 8, v13
	global_load_lds_dwordx4 v9, s[16:17]
	s_waitcnt lgkmcnt(3)
	s_add_i32 m0, s8, 0x1000
	v_lshl_add_u32 v8, v4, 8, v10
	global_load_lds_dwordx4 v8, s[16:17]
	s_waitcnt lgkmcnt(2)
	s_add_i32 m0, s8, 0x1400
	v_lshl_add_u32 v9, v5, 8, v11
	global_load_lds_dwordx4 v9, s[16:17]
	s_waitcnt lgkmcnt(1)
	s_add_i32 m0, s8, 0x1800
	v_lshl_add_u32 v8, v6, 8, v12
	global_load_lds_dwordx4 v8, s[16:17]
	s_waitcnt lgkmcnt(0)
	s_add_i32 m0, s8, 0x1c00
	v_lshl_add_u32 v9, v7, 8, v13
	global_load_lds_dwordx4 v9, s[16:17]
	s_waitcnt vmcnt(8)
	ds_read_b128 v[104:107], v18 offset:8192
	ds_read_b128 v[108:111], v19 offset:8192
	ds_read_b128 v[112:115], v20 offset:8192
	ds_read_b128 v[116:119], v21 offset:8192
	ds_read_b128 v[120:123], v18 offset:12288
	ds_read_b128 v[124:127], v19 offset:12288
	ds_read_b128 v[128:131], v20 offset:12288
	ds_read_b128 v[132:135], v21 offset:12288
	s_waitcnt lgkmcnt(7)
	v_mfma_f32_16x16x32_bf16 v[136:139], v[104:107], v[88:91], 0
	s_waitcnt lgkmcnt(6)
	v_mfma_f32_16x16x32_bf16 v[136:139], v[108:111], v[92:95], v[136:139]
	s_waitcnt lgkmcnt(5)
	v_mfma_f32_16x16x32_bf16 v[136:139], v[112:115], v[96:99], v[136:139]
	s_waitcnt lgkmcnt(4)
	v_mfma_f32_16x16x32_bf16 v[136:139], v[116:119], v[100:103], v[136:139]
	s_waitcnt lgkmcnt(3)
	v_mfma_f32_16x16x32_bf16 v[140:143], v[120:123], v[88:91], 0
	s_waitcnt lgkmcnt(2)
	v_mfma_f32_16x16x32_bf16 v[140:143], v[124:127], v[92:95], v[140:143]
	s_waitcnt lgkmcnt(1)
	v_mfma_f32_16x16x32_bf16 v[140:143], v[128:131], v[96:99], v[140:143]
	s_waitcnt lgkmcnt(0)
	v_mfma_f32_16x16x32_bf16 v[140:143], v[132:135], v[100:103], v[140:143]
	v_mul_f32_e32 v80, 0x3db504f3, v136
	v_mul_f32_e32 v81, 0x3db504f3, v137
	v_mul_f32_e32 v82, 0x3db504f3, v138
	v_mul_f32_e32 v83, 0x3db504f3, v139
	s_nop 3
	v_mul_f32_e32 v84, 0x3db504f3, v140
	v_mul_f32_e32 v85, 0x3db504f3, v141
	v_mul_f32_e32 v86, 0x3db504f3, v142
	v_mul_f32_e32 v87, 0x3db504f3, v143
	v_max3_f32 v163, v24, v25, v26
	v_max3_f32 v163, v163, v27, v28
	v_max3_f32 v163, v163, v29, v30
	v_max3_f32 v163, v163, v31, v32
	v_max3_f32 v163, v163, v33, v34
	v_max3_f32 v163, v163, v35, v36
	v_max3_f32 v163, v163, v37, v38
	v_max3_f32 v163, v163, v39, v40
	v_max3_f32 v163, v163, v41, v42
	v_max3_f32 v163, v163, v43, v44
	v_max3_f32 v163, v163, v45, v46
	v_max3_f32 v163, v163, v47, v48
	v_max3_f32 v163, v163, v49, v50
	v_max3_f32 v163, v163, v51, v52
	v_max3_f32 v163, v163, v53, v54
	v_max3_f32 v163, v163, v55, v56
	v_max3_f32 v163, v163, v57, v58
	v_max3_f32 v163, v163, v59, v60
	v_max3_f32 v163, v163, v61, v62
	v_max3_f32 v163, v163, v63, v64
	v_max3_f32 v163, v163, v65, v66
	v_max3_f32 v163, v163, v67, v68
	v_max3_f32 v163, v163, v69, v70
	v_max3_f32 v163, v163, v71, v72
	v_max3_f32 v163, v163, v73, v74
	v_max3_f32 v163, v163, v75, v76
	v_max3_f32 v163, v163, v77, v78
	v_max3_f32 v163, v163, v79, v80
	v_max3_f32 v163, v163, v81, v82
	v_max3_f32 v163, v163, v83, v84
	v_max3_f32 v163, v163, v85, v86
	v_max_f32_e32 v163, v163, v87
	s_nop 0
	ds_bpermute_b32 v165, v147, v163
	s_waitcnt lgkmcnt(0)
	v_max_f32_e32 v163, v163, v165
	s_nop 0
	ds_bpermute_b32 v165, v146, v163
	s_waitcnt lgkmcnt(0)
	v_max_f32_e32 v163, v163, v165
	v_sub_f32_e32 v165, v24, v163
	v_mul_f32_e32 v165, 0x3fb8aa3b, v165
	v_exp_f32_e32 v24, v165
	v_sub_f32_e32 v166, v25, v163
	v_mul_f32_e32 v166, 0x3fb8aa3b, v166
	v_exp_f32_e32 v25, v166
	v_sub_f32_e32 v167, v26, v163
	v_mul_f32_e32 v167, 0x3fb8aa3b, v167
	v_exp_f32_e32 v26, v167
	v_add_f32_e32 v164, 0, v24
	v_sub_f32_e32 v168, v27, v163
	v_mul_f32_e32 v168, 0x3fb8aa3b, v168
	v_exp_f32_e32 v27, v168
	v_add_f32_e32 v164, v164, v25
	v_sub_f32_e32 v165, v28, v163
	v_mul_f32_e32 v165, 0x3fb8aa3b, v165
	v_exp_f32_e32 v28, v165
	v_add_f32_e32 v164, v164, v26
	v_sub_f32_e32 v166, v29, v163
	v_mul_f32_e32 v166, 0x3fb8aa3b, v166
	v_exp_f32_e32 v29, v166
	v_add_f32_e32 v164, v164, v27
	v_sub_f32_e32 v167, v30, v163
	v_mul_f32_e32 v167, 0x3fb8aa3b, v167
	v_exp_f32_e32 v30, v167
	v_add_f32_e32 v164, v164, v28
	v_sub_f32_e32 v168, v31, v163
	v_mul_f32_e32 v168, 0x3fb8aa3b, v168
	v_exp_f32_e32 v31, v168
	v_add_f32_e32 v164, v164, v29
	v_sub_f32_e32 v165, v32, v163
	v_mul_f32_e32 v165, 0x3fb8aa3b, v165
	v_exp_f32_e32 v32, v165
	v_add_f32_e32 v164, v164, v30
	v_sub_f32_e32 v166, v33, v163
	v_mul_f32_e32 v166, 0x3fb8aa3b, v166
	v_exp_f32_e32 v33, v166
	v_add_f32_e32 v164, v164, v31
	v_sub_f32_e32 v167, v34, v163
	v_mul_f32_e32 v167, 0x3fb8aa3b, v167
	v_exp_f32_e32 v34, v167
	v_add_f32_e32 v164, v164, v32
	v_sub_f32_e32 v168, v35, v163
	v_mul_f32_e32 v168, 0x3fb8aa3b, v168
	v_exp_f32_e32 v35, v168
	v_add_f32_e32 v164, v164, v33
	v_sub_f32_e32 v165, v36, v163
	v_mul_f32_e32 v165, 0x3fb8aa3b, v165
	v_exp_f32_e32 v36, v165
	v_add_f32_e32 v164, v164, v34
	v_sub_f32_e32 v166, v37, v163
	v_mul_f32_e32 v166, 0x3fb8aa3b, v166
	v_exp_f32_e32 v37, v166
	v_add_f32_e32 v164, v164, v35
	v_sub_f32_e32 v167, v38, v163
	v_mul_f32_e32 v167, 0x3fb8aa3b, v167
	v_exp_f32_e32 v38, v167
	v_add_f32_e32 v164, v164, v36
	v_sub_f32_e32 v168, v39, v163
	v_mul_f32_e32 v168, 0x3fb8aa3b, v168
	v_exp_f32_e32 v39, v168
	v_add_f32_e32 v164, v164, v37
	v_sub_f32_e32 v165, v40, v163
	v_mul_f32_e32 v165, 0x3fb8aa3b, v165
	v_exp_f32_e32 v40, v165
	v_add_f32_e32 v164, v164, v38
	v_sub_f32_e32 v166, v41, v163
	v_mul_f32_e32 v166, 0x3fb8aa3b, v166
	v_exp_f32_e32 v41, v166
	v_add_f32_e32 v164, v164, v39
	v_sub_f32_e32 v167, v42, v163
	v_mul_f32_e32 v167, 0x3fb8aa3b, v167
	v_exp_f32_e32 v42, v167
	v_add_f32_e32 v164, v164, v40
	v_sub_f32_e32 v168, v43, v163
	v_mul_f32_e32 v168, 0x3fb8aa3b, v168
	v_exp_f32_e32 v43, v168
	v_add_f32_e32 v164, v164, v41
	v_sub_f32_e32 v165, v44, v163
	v_mul_f32_e32 v165, 0x3fb8aa3b, v165
	v_exp_f32_e32 v44, v165
	v_add_f32_e32 v164, v164, v42
	v_sub_f32_e32 v166, v45, v163
	v_mul_f32_e32 v166, 0x3fb8aa3b, v166
	v_exp_f32_e32 v45, v166
	v_add_f32_e32 v164, v164, v43
	v_sub_f32_e32 v167, v46, v163
	v_mul_f32_e32 v167, 0x3fb8aa3b, v167
	v_exp_f32_e32 v46, v167
	v_add_f32_e32 v164, v164, v44
	v_sub_f32_e32 v168, v47, v163
	v_mul_f32_e32 v168, 0x3fb8aa3b, v168
	v_exp_f32_e32 v47, v168
	v_add_f32_e32 v164, v164, v45
	v_sub_f32_e32 v165, v48, v163
	v_mul_f32_e32 v165, 0x3fb8aa3b, v165
	v_exp_f32_e32 v48, v165
	v_add_f32_e32 v164, v164, v46
	v_sub_f32_e32 v166, v49, v163
	v_mul_f32_e32 v166, 0x3fb8aa3b, v166
	v_exp_f32_e32 v49, v166
	v_add_f32_e32 v164, v164, v47
	v_sub_f32_e32 v167, v50, v163
	v_mul_f32_e32 v167, 0x3fb8aa3b, v167
	v_exp_f32_e32 v50, v167
	v_add_f32_e32 v164, v164, v48
	v_sub_f32_e32 v168, v51, v163
	v_mul_f32_e32 v168, 0x3fb8aa3b, v168
	v_exp_f32_e32 v51, v168
	v_add_f32_e32 v164, v164, v49
	v_sub_f32_e32 v165, v52, v163
	v_mul_f32_e32 v165, 0x3fb8aa3b, v165
	v_exp_f32_e32 v52, v165
	v_add_f32_e32 v164, v164, v50
	v_sub_f32_e32 v166, v53, v163
	v_mul_f32_e32 v166, 0x3fb8aa3b, v166
	v_exp_f32_e32 v53, v166
	v_add_f32_e32 v164, v164, v51
	v_sub_f32_e32 v167, v54, v163
	v_mul_f32_e32 v167, 0x3fb8aa3b, v167
	v_exp_f32_e32 v54, v167
	v_add_f32_e32 v164, v164, v52
	v_sub_f32_e32 v168, v55, v163
	v_mul_f32_e32 v168, 0x3fb8aa3b, v168
	v_exp_f32_e32 v55, v168
	v_add_f32_e32 v164, v164, v53
	v_sub_f32_e32 v165, v56, v163
	v_mul_f32_e32 v165, 0x3fb8aa3b, v165
	v_exp_f32_e32 v56, v165
	v_add_f32_e32 v164, v164, v54
	v_sub_f32_e32 v166, v57, v163
	v_mul_f32_e32 v166, 0x3fb8aa3b, v166
	v_exp_f32_e32 v57, v166
	v_add_f32_e32 v164, v164, v55
	v_sub_f32_e32 v167, v58, v163
	v_mul_f32_e32 v167, 0x3fb8aa3b, v167
	v_exp_f32_e32 v58, v167
	v_add_f32_e32 v164, v164, v56
	v_sub_f32_e32 v168, v59, v163
	v_mul_f32_e32 v168, 0x3fb8aa3b, v168
	v_exp_f32_e32 v59, v168
	v_add_f32_e32 v164, v164, v57
	v_sub_f32_e32 v165, v60, v163
	v_mul_f32_e32 v165, 0x3fb8aa3b, v165
	v_exp_f32_e32 v60, v165
	v_add_f32_e32 v164, v164, v58
	v_sub_f32_e32 v166, v61, v163
	v_mul_f32_e32 v166, 0x3fb8aa3b, v166
	v_exp_f32_e32 v61, v166
	v_add_f32_e32 v164, v164, v59
	v_sub_f32_e32 v167, v62, v163
	v_mul_f32_e32 v167, 0x3fb8aa3b, v167
	v_exp_f32_e32 v62, v167
	v_add_f32_e32 v164, v164, v60
	v_sub_f32_e32 v168, v63, v163
	v_mul_f32_e32 v168, 0x3fb8aa3b, v168
	v_exp_f32_e32 v63, v168
	v_add_f32_e32 v164, v164, v61
	v_sub_f32_e32 v165, v64, v163
	v_mul_f32_e32 v165, 0x3fb8aa3b, v165
	v_exp_f32_e32 v64, v165
	v_add_f32_e32 v164, v164, v62
	v_sub_f32_e32 v166, v65, v163
	v_mul_f32_e32 v166, 0x3fb8aa3b, v166
	v_exp_f32_e32 v65, v166
	v_add_f32_e32 v164, v164, v63
	v_sub_f32_e32 v167, v66, v163
	v_mul_f32_e32 v167, 0x3fb8aa3b, v167
	v_exp_f32_e32 v66, v167
	v_add_f32_e32 v164, v164, v64
	v_sub_f32_e32 v168, v67, v163
	v_mul_f32_e32 v168, 0x3fb8aa3b, v168
	v_exp_f32_e32 v67, v168
	v_add_f32_e32 v164, v164, v65
	v_sub_f32_e32 v165, v68, v163
	v_mul_f32_e32 v165, 0x3fb8aa3b, v165
	v_exp_f32_e32 v68, v165
	v_add_f32_e32 v164, v164, v66
	v_sub_f32_e32 v166, v69, v163
	v_mul_f32_e32 v166, 0x3fb8aa3b, v166
	v_exp_f32_e32 v69, v166
	v_add_f32_e32 v164, v164, v67
	v_sub_f32_e32 v167, v70, v163
	v_mul_f32_e32 v167, 0x3fb8aa3b, v167
	v_exp_f32_e32 v70, v167
	v_add_f32_e32 v164, v164, v68
	v_sub_f32_e32 v168, v71, v163
	v_mul_f32_e32 v168, 0x3fb8aa3b, v168
	v_exp_f32_e32 v71, v168
	v_add_f32_e32 v164, v164, v69
	v_sub_f32_e32 v165, v72, v163
	v_mul_f32_e32 v165, 0x3fb8aa3b, v165
	v_exp_f32_e32 v72, v165
	v_add_f32_e32 v164, v164, v70
	v_sub_f32_e32 v166, v73, v163
	v_mul_f32_e32 v166, 0x3fb8aa3b, v166
	v_exp_f32_e32 v73, v166
	v_add_f32_e32 v164, v164, v71
	v_sub_f32_e32 v167, v74, v163
	v_mul_f32_e32 v167, 0x3fb8aa3b, v167
	v_exp_f32_e32 v74, v167
	v_add_f32_e32 v164, v164, v72
	v_sub_f32_e32 v168, v75, v163
	v_mul_f32_e32 v168, 0x3fb8aa3b, v168
	v_exp_f32_e32 v75, v168
	v_add_f32_e32 v164, v164, v73
	v_sub_f32_e32 v165, v76, v163
	v_mul_f32_e32 v165, 0x3fb8aa3b, v165
	v_exp_f32_e32 v76, v165
	v_add_f32_e32 v164, v164, v74
	v_sub_f32_e32 v166, v77, v163
	v_mul_f32_e32 v166, 0x3fb8aa3b, v166
	v_exp_f32_e32 v77, v166
	v_add_f32_e32 v164, v164, v75
	v_sub_f32_e32 v167, v78, v163
	v_mul_f32_e32 v167, 0x3fb8aa3b, v167
	v_exp_f32_e32 v78, v167
	v_add_f32_e32 v164, v164, v76
	v_sub_f32_e32 v168, v79, v163
	v_mul_f32_e32 v168, 0x3fb8aa3b, v168
	v_exp_f32_e32 v79, v168
	v_add_f32_e32 v164, v164, v77
	v_sub_f32_e32 v165, v80, v163
	v_mul_f32_e32 v165, 0x3fb8aa3b, v165
	v_exp_f32_e32 v80, v165
	v_add_f32_e32 v164, v164, v78
	v_sub_f32_e32 v166, v81, v163
	v_mul_f32_e32 v166, 0x3fb8aa3b, v166
	v_exp_f32_e32 v81, v166
	v_add_f32_e32 v164, v164, v79
	v_sub_f32_e32 v167, v82, v163
	v_mul_f32_e32 v167, 0x3fb8aa3b, v167
	v_exp_f32_e32 v82, v167
	v_add_f32_e32 v164, v164, v80
	v_sub_f32_e32 v168, v83, v163
	v_mul_f32_e32 v168, 0x3fb8aa3b, v168
	v_exp_f32_e32 v83, v168
	v_add_f32_e32 v164, v164, v81
	v_sub_f32_e32 v165, v84, v163
	v_mul_f32_e32 v165, 0x3fb8aa3b, v165
	v_exp_f32_e32 v84, v165
	v_add_f32_e32 v164, v164, v82
	v_sub_f32_e32 v166, v85, v163
	v_mul_f32_e32 v166, 0x3fb8aa3b, v166
	v_exp_f32_e32 v85, v166
	v_add_f32_e32 v164, v164, v83
	v_sub_f32_e32 v167, v86, v163
	v_mul_f32_e32 v167, 0x3fb8aa3b, v167
	v_exp_f32_e32 v86, v167
	v_add_f32_e32 v164, v164, v84
	v_sub_f32_e32 v168, v87, v163
	v_mul_f32_e32 v168, 0x3fb8aa3b, v168
	v_exp_f32_e32 v87, v168
	v_add_f32_e32 v164, v164, v85
	s_nop 0
	v_add_f32_e32 v164, v164, v86
	v_add_f32_e32 v164, v164, v87
	s_nop 0
	ds_bpermute_b32 v165, v147, v164
	s_waitcnt lgkmcnt(0)
	v_add_f32_e32 v164, v164, v165
	s_nop 0
	ds_bpermute_b32 v165, v146, v164
	s_waitcnt lgkmcnt(0)
	v_add_f32_e32 v164, v164, v165
	v_div_scale_f32 v170, s[74:75], v164, v164, 1.0
	v_rcp_f32_e32 v171, v170
	s_nop 0
	v_fma_f32 v172, -v170, v171, 1.0
	v_fmac_f32_e32 v171, v172, v171
	v_div_scale_f32 v172, vcc, 1.0, v164, 1.0
	v_mul_f32_e32 v173, v172, v171
	v_fma_f32 v169, -v170, v173, v172
	v_fmac_f32_e32 v173, v169, v171
	v_fma_f32 v170, -v170, v173, v172
	v_div_fmas_f32 v170, v170, v171, v173
	v_div_fixup_f32 v169, v170, v164, 1.0
	v_mul_f32_e32 v165, v24, v169
	v_mul_f32_e32 v166, v25, v169
	v_cvt_pk_bf16_f32 v24, v165, v166
	v_mul_f32_e32 v167, v26, v169
	v_mul_f32_e32 v168, v27, v169
	v_cvt_pk_bf16_f32 v25, v167, v168
	v_mul_f32_e32 v165, v28, v169
	v_mul_f32_e32 v166, v29, v169
	v_cvt_pk_bf16_f32 v26, v165, v166
	v_mul_f32_e32 v167, v30, v169
	v_mul_f32_e32 v168, v31, v169
	v_cvt_pk_bf16_f32 v27, v167, v168
	v_mul_f32_e32 v165, v32, v169
	v_mul_f32_e32 v166, v33, v169
	v_cvt_pk_bf16_f32 v32, v165, v166
	v_mul_f32_e32 v167, v34, v169
	v_mul_f32_e32 v168, v35, v169
	v_cvt_pk_bf16_f32 v33, v167, v168
	v_mul_f32_e32 v165, v36, v169
	v_mul_f32_e32 v166, v37, v169
	v_cvt_pk_bf16_f32 v34, v165, v166
	v_mul_f32_e32 v167, v38, v169
	v_mul_f32_e32 v168, v39, v169
	v_cvt_pk_bf16_f32 v35, v167, v168
	v_mul_f32_e32 v165, v40, v169
	v_mul_f32_e32 v166, v41, v169
	v_cvt_pk_bf16_f32 v40, v165, v166
	v_mul_f32_e32 v167, v42, v169
	v_mul_f32_e32 v168, v43, v169
	v_cvt_pk_bf16_f32 v41, v167, v168
	v_mul_f32_e32 v165, v44, v169
	v_mul_f32_e32 v166, v45, v169
	v_cvt_pk_bf16_f32 v42, v165, v166
	v_mul_f32_e32 v167, v46, v169
	v_mul_f32_e32 v168, v47, v169
	v_cvt_pk_bf16_f32 v43, v167, v168
	v_mul_f32_e32 v165, v48, v169
	v_mul_f32_e32 v166, v49, v169
	v_cvt_pk_bf16_f32 v48, v165, v166
	v_mul_f32_e32 v167, v50, v169
	v_mul_f32_e32 v168, v51, v169
	v_cvt_pk_bf16_f32 v49, v167, v168
	v_mul_f32_e32 v165, v52, v169
	v_mul_f32_e32 v166, v53, v169
	v_cvt_pk_bf16_f32 v50, v165, v166
	v_mul_f32_e32 v167, v54, v169
	v_mul_f32_e32 v168, v55, v169
	v_cvt_pk_bf16_f32 v51, v167, v168
	v_mul_f32_e32 v165, v56, v169
	v_mul_f32_e32 v166, v57, v169
	v_cvt_pk_bf16_f32 v56, v165, v166
	v_mul_f32_e32 v167, v58, v169
	v_mul_f32_e32 v168, v59, v169
	v_cvt_pk_bf16_f32 v57, v167, v168
	v_mul_f32_e32 v165, v60, v169
	v_mul_f32_e32 v166, v61, v169
	v_cvt_pk_bf16_f32 v58, v165, v166
	v_mul_f32_e32 v167, v62, v169
	v_mul_f32_e32 v168, v63, v169
	v_cvt_pk_bf16_f32 v59, v167, v168
	v_mul_f32_e32 v165, v64, v169
	v_mul_f32_e32 v166, v65, v169
	v_cvt_pk_bf16_f32 v64, v165, v166
	v_mul_f32_e32 v167, v66, v169
	v_mul_f32_e32 v168, v67, v169
	v_cvt_pk_bf16_f32 v65, v167, v168
	v_mul_f32_e32 v165, v68, v169
	v_mul_f32_e32 v166, v69, v169
	v_cvt_pk_bf16_f32 v66, v165, v166
	v_mul_f32_e32 v167, v70, v169
	v_mul_f32_e32 v168, v71, v169
	v_cvt_pk_bf16_f32 v67, v167, v168
	v_mul_f32_e32 v165, v72, v169
	v_mul_f32_e32 v166, v73, v169
	v_cvt_pk_bf16_f32 v72, v165, v166
	v_mul_f32_e32 v167, v74, v169
	v_mul_f32_e32 v168, v75, v169
	v_cvt_pk_bf16_f32 v73, v167, v168
	v_mul_f32_e32 v165, v76, v169
	v_mul_f32_e32 v166, v77, v169
	v_cvt_pk_bf16_f32 v74, v165, v166
	v_mul_f32_e32 v167, v78, v169
	v_mul_f32_e32 v168, v79, v169
	v_cvt_pk_bf16_f32 v75, v167, v168
	v_mul_f32_e32 v165, v80, v169
	v_mul_f32_e32 v166, v81, v169
	v_cvt_pk_bf16_f32 v80, v165, v166
	v_mul_f32_e32 v167, v82, v169
	v_mul_f32_e32 v168, v83, v169
	v_cvt_pk_bf16_f32 v81, v167, v168
	v_mul_f32_e32 v165, v84, v169
	v_mul_f32_e32 v166, v85, v169
	v_cvt_pk_bf16_f32 v82, v165, v166
	v_mul_f32_e32 v167, v86, v169
	v_mul_f32_e32 v168, v87, v169
	v_cvt_pk_bf16_f32 v83, v167, v168
	s_cmp_eq_u32 s11, 1
	s_cbranch_scc1 .Lattn_noq8
	s_add_i32 s15, s12, 1
	s_lshl_b32 s13, s15, 12
	v_add_u32_e32 v162, s13, v157
	global_load_dwordx4 v[88:91], v162, s[6:7] offset:0
	global_load_dwordx4 v[92:95], v162, s[6:7] offset:64
	global_load_dwordx4 v[96:99], v162, s[6:7] offset:128
	global_load_dwordx4 v[100:103], v162, s[6:7] offset:192
.Lattn_noq8:
	s_add_i32 s18, s14, 64
	s_mov_b64 s[16:17], s[4:5]
	v_add_u32_e32 v161, s18, v156
	ds_read_u16 v0, v161 offset:0
	ds_read_u16 v1, v161 offset:8
	ds_read_u16 v2, v161 offset:16
	ds_read_u16 v3, v161 offset:24
	ds_read_u16 v4, v161 offset:32
	ds_read_u16 v5, v161 offset:40
	ds_read_u16 v6, v161 offset:48
	ds_read_u16 v7, v161 offset:56
	s_waitcnt lgkmcnt(7)
	s_add_i32 m0, s8, 0x2000
	v_lshl_add_u32 v8, v0, 8, v10
	global_load_lds_dwordx4 v8, s[16:17]
	s_waitcnt lgkmcnt(6)
	s_add_i32 m0, s8, 0x2400
	v_lshl_add_u32 v9, v1, 8, v11
	global_load_lds_dwordx4 v9, s[16:17]
	s_waitcnt lgkmcnt(5)
	s_add_i32 m0, s8, 0x2800
	v_lshl_add_u32 v8, v2, 8, v12
	global_load_lds_dwordx4 v8, s[16:17]
	s_waitcnt lgkmcnt(4)
	s_add_i32 m0, s8, 0x2c00
	v_lshl_add_u32 v9, v3, 8, v13
	global_load_lds_dwordx4 v9, s[16:17]
	s_waitcnt lgkmcnt(3)
	s_add_i32 m0, s8, 0x3000
	v_lshl_add_u32 v8, v4, 8, v10
	global_load_lds_dwordx4 v8, s[16:17]
	s_waitcnt lgkmcnt(2)
	s_add_i32 m0, s8, 0x3400
	v_lshl_add_u32 v9, v5, 8, v11
	global_load_lds_dwordx4 v9, s[16:17]
	s_waitcnt lgkmcnt(1)
	s_add_i32 m0, s8, 0x3800
	v_lshl_add_u32 v8, v6, 8, v12
	global_load_lds_dwordx4 v8, s[16:17]
	s_waitcnt lgkmcnt(0)
	s_add_i32 m0, s8, 0x3c00
	v_lshl_add_u32 v9, v7, 8, v13
	global_load_lds_dwordx4 v9, s[16:17]
	s_waitcnt vmcnt(8)
	ds_read_b64_tr_b16 v[104:105], v148 offset:0
	ds_read_b64_tr_b16 v[106:107], v148 offset:4096
	ds_read_b64_tr_b16 v[108:109], v149 offset:0
	ds_read_b64_tr_b16 v[110:111], v149 offset:4096
	ds_read_b64_tr_b16 v[112:113], v150 offset:0
	ds_read_b64_tr_b16 v[114:115], v150 offset:4096
	ds_read_b64_tr_b16 v[116:117], v151 offset:0
	ds_read_b64_tr_b16 v[118:119], v151 offset:4096
	ds_read_b64_tr_b16 v[120:121], v152 offset:0
	ds_read_b64_tr_b16 v[122:123], v152 offset:4096
	ds_read_b64_tr_b16 v[124:125], v153 offset:0
	ds_read_b64_tr_b16 v[126:127], v153 offset:4096
	ds_read_b64_tr_b16 v[128:129], v154 offset:0
	ds_read_b64_tr_b16 v[130:131], v154 offset:4096
	s_waitcnt lgkmcnt(12)
	v_mfma_f32_16x16x32_bf16 v[176:179], v[24:27], v[104:107], 0
	ds_read_b64_tr_b16 v[132:133], v155 offset:0
	ds_read_b64_tr_b16 v[134:135], v155 offset:4096
	s_waitcnt lgkmcnt(12)
	v_mfma_f32_16x16x32_bf16 v[180:183], v[24:27], v[108:111], 0
	s_waitcnt lgkmcnt(10)
	v_mfma_f32_16x16x32_bf16 v[184:187], v[24:27], v[112:115], 0
	s_waitcnt lgkmcnt(8)
	v_mfma_f32_16x16x32_bf16 v[188:191], v[24:27], v[116:119], 0
	s_waitcnt lgkmcnt(6)
	v_mfma_f32_16x16x32_bf16 v[192:195], v[24:27], v[120:123], 0
	s_waitcnt lgkmcnt(4)
	v_mfma_f32_16x16x32_bf16 v[196:199], v[24:27], v[124:127], 0
	s_waitcnt lgkmcnt(2)
	v_mfma_f32_16x16x32_bf16 v[200:203], v[24:27], v[128:131], 0
	s_waitcnt lgkmcnt(0)
	v_mfma_f32_16x16x32_bf16 v[204:207], v[24:27], v[132:135], 0
	s_add_i32 s18, s14, 128
	s_mov_b64 s[16:17], s[4:5]
	v_add_u32_e32 v161, s18, v156
	ds_read_u16 v0, v161 offset:0
	ds_read_u16 v1, v161 offset:8
	ds_read_u16 v2, v161 offset:16
	ds_read_u16 v3, v161 offset:24
	ds_read_u16 v4, v161 offset:32
	ds_read_u16 v5, v161 offset:40
	ds_read_u16 v6, v161 offset:48
	ds_read_u16 v7, v161 offset:56
	s_waitcnt lgkmcnt(7)
	s_add_i32 m0, s8, 0x0
	v_lshl_add_u32 v8, v0, 8, v10
	global_load_lds_dwordx4 v8, s[16:17]
	s_waitcnt lgkmcnt(6)
	s_add_i32 m0, s8, 0x400
	v_lshl_add_u32 v9, v1, 8, v11
	global_load_lds_dwordx4 v9, s[16:17]
	s_waitcnt lgkmcnt(5)
	s_add_i32 m0, s8, 0x800
	v_lshl_add_u32 v8, v2, 8, v12
	global_load_lds_dwordx4 v8, s[16:17]
	s_waitcnt lgkmcnt(4)
	s_add_i32 m0, s8, 0xc00
	v_lshl_add_u32 v9, v3, 8, v13
	global_load_lds_dwordx4 v9, s[16:17]
	s_waitcnt lgkmcnt(3)
	s_add_i32 m0, s8, 0x1000
	v_lshl_add_u32 v8, v4, 8, v10
	global_load_lds_dwordx4 v8, s[16:17]
	s_waitcnt lgkmcnt(2)
	s_add_i32 m0, s8, 0x1400
	v_lshl_add_u32 v9, v5, 8, v11
	global_load_lds_dwordx4 v9, s[16:17]
	s_waitcnt lgkmcnt(1)
	s_add_i32 m0, s8, 0x1800
	v_lshl_add_u32 v8, v6, 8, v12
	global_load_lds_dwordx4 v8, s[16:17]
	s_waitcnt lgkmcnt(0)
	s_add_i32 m0, s8, 0x1c00
	v_lshl_add_u32 v9, v7, 8, v13
	global_load_lds_dwordx4 v9, s[16:17]
	s_waitcnt vmcnt(8)
	ds_read_b64_tr_b16 v[104:105], v148 offset:8192
	ds_read_b64_tr_b16 v[106:107], v148 offset:12288
	ds_read_b64_tr_b16 v[108:109], v149 offset:8192
	ds_read_b64_tr_b16 v[110:111], v149 offset:12288
	ds_read_b64_tr_b16 v[112:113], v150 offset:8192
	ds_read_b64_tr_b16 v[114:115], v150 offset:12288
	ds_read_b64_tr_b16 v[116:117], v151 offset:8192
	ds_read_b64_tr_b16 v[118:119], v151 offset:12288
	ds_read_b64_tr_b16 v[120:121], v152 offset:8192
	ds_read_b64_tr_b16 v[122:123], v152 offset:12288
	ds_read_b64_tr_b16 v[124:125], v153 offset:8192
	ds_read_b64_tr_b16 v[126:127], v153 offset:12288
	ds_read_b64_tr_b16 v[128:129], v154 offset:8192
	ds_read_b64_tr_b16 v[130:131], v154 offset:12288
	s_waitcnt lgkmcnt(12)
	v_mfma_f32_16x16x32_bf16 v[176:179], v[32:35], v[104:107], v[176:179]
	ds_read_b64_tr_b16 v[132:133], v155 offset:8192
	ds_read_b64_tr_b16 v[134:135], v155 offset:12288
	s_waitcnt lgkmcnt(12)
	v_mfma_f32_16x16x32_bf16 v[180:183], v[32:35], v[108:111], v[180:183]
	s_waitcnt lgkmcnt(10)
	v_mfma_f32_16x16x32_bf16 v[184:187], v[32:35], v[112:115], v[184:187]
	s_waitcnt lgkmcnt(8)
	v_mfma_f32_16x16x32_bf16 v[188:191], v[32:35], v[116:119], v[188:191]
	s_waitcnt lgkmcnt(6)
	v_mfma_f32_16x16x32_bf16 v[192:195], v[32:35], v[120:123], v[192:195]
	s_waitcnt lgkmcnt(4)
	v_mfma_f32_16x16x32_bf16 v[196:199], v[32:35], v[124:127], v[196:199]
	s_waitcnt lgkmcnt(2)
	v_mfma_f32_16x16x32_bf16 v[200:203], v[32:35], v[128:131], v[200:203]
	s_waitcnt lgkmcnt(0)
	v_mfma_f32_16x16x32_bf16 v[204:207], v[32:35], v[132:135], v[204:207]
	s_add_i32 s18, s14, 192
	s_mov_b64 s[16:17], s[4:5]
	v_add_u32_e32 v161, s18, v156
	ds_read_u16 v0, v161 offset:0
	ds_read_u16 v1, v161 offset:8
	ds_read_u16 v2, v161 offset:16
	ds_read_u16 v3, v161 offset:24
	ds_read_u16 v4, v161 offset:32
	ds_read_u16 v5, v161 offset:40
	ds_read_u16 v6, v161 offset:48
	ds_read_u16 v7, v161 offset:56
	s_waitcnt lgkmcnt(7)
	s_add_i32 m0, s8, 0x2000
	v_lshl_add_u32 v8, v0, 8, v10
	global_load_lds_dwordx4 v8, s[16:17]
	s_waitcnt lgkmcnt(6)
	s_add_i32 m0, s8, 0x2400
	v_lshl_add_u32 v9, v1, 8, v11
	global_load_lds_dwordx4 v9, s[16:17]
	s_waitcnt lgkmcnt(5)
	s_add_i32 m0, s8, 0x2800
	v_lshl_add_u32 v8, v2, 8, v12
	global_load_lds_dwordx4 v8, s[16:17]
	s_waitcnt lgkmcnt(4)
	s_add_i32 m0, s8, 0x2c00
	v_lshl_add_u32 v9, v3, 8, v13
	global_load_lds_dwordx4 v9, s[16:17]
	s_waitcnt lgkmcnt(3)
	s_add_i32 m0, s8, 0x3000
	v_lshl_add_u32 v8, v4, 8, v10
	global_load_lds_dwordx4 v8, s[16:17]
	s_waitcnt lgkmcnt(2)
	s_add_i32 m0, s8, 0x3400
	v_lshl_add_u32 v9, v5, 8, v11
	global_load_lds_dwordx4 v9, s[16:17]
	s_waitcnt lgkmcnt(1)
	s_add_i32 m0, s8, 0x3800
	v_lshl_add_u32 v8, v6, 8, v12
	global_load_lds_dwordx4 v8, s[16:17]
	s_waitcnt lgkmcnt(0)
	s_add_i32 m0, s8, 0x3c00
	v_lshl_add_u32 v9, v7, 8, v13
	global_load_lds_dwordx4 v9, s[16:17]
	s_waitcnt vmcnt(8)
	ds_read_b64_tr_b16 v[104:105], v148 offset:0
	ds_read_b64_tr_b16 v[106:107], v148 offset:4096
	ds_read_b64_tr_b16 v[108:109], v149 offset:0
	ds_read_b64_tr_b16 v[110:111], v149 offset:4096
	ds_read_b64_tr_b16 v[112:113], v150 offset:0
	ds_read_b64_tr_b16 v[114:115], v150 offset:4096
	ds_read_b64_tr_b16 v[116:117], v151 offset:0
	ds_read_b64_tr_b16 v[118:119], v151 offset:4096
	ds_read_b64_tr_b16 v[120:121], v152 offset:0
	ds_read_b64_tr_b16 v[122:123], v152 offset:4096
	ds_read_b64_tr_b16 v[124:125], v153 offset:0
	ds_read_b64_tr_b16 v[126:127], v153 offset:4096
	ds_read_b64_tr_b16 v[128:129], v154 offset:0
	ds_read_b64_tr_b16 v[130:131], v154 offset:4096
	s_waitcnt lgkmcnt(12)
	v_mfma_f32_16x16x32_bf16 v[176:179], v[40:43], v[104:107], v[176:179]
	ds_read_b64_tr_b16 v[132:133], v155 offset:0
	ds_read_b64_tr_b16 v[134:135], v155 offset:4096
	s_waitcnt lgkmcnt(12)
	v_mfma_f32_16x16x32_bf16 v[180:183], v[40:43], v[108:111], v[180:183]
	s_waitcnt lgkmcnt(10)
	v_mfma_f32_16x16x32_bf16 v[184:187], v[40:43], v[112:115], v[184:187]
	s_waitcnt lgkmcnt(8)
	v_mfma_f32_16x16x32_bf16 v[188:191], v[40:43], v[116:119], v[188:191]
	s_waitcnt lgkmcnt(6)
	v_mfma_f32_16x16x32_bf16 v[192:195], v[40:43], v[120:123], v[192:195]
	s_waitcnt lgkmcnt(4)
	v_mfma_f32_16x16x32_bf16 v[196:199], v[40:43], v[124:127], v[196:199]
	s_waitcnt lgkmcnt(2)
	v_mfma_f32_16x16x32_bf16 v[200:203], v[40:43], v[128:131], v[200:203]
	s_waitcnt lgkmcnt(0)
	v_mfma_f32_16x16x32_bf16 v[204:207], v[40:43], v[132:135], v[204:207]
	s_add_i32 s18, s14, 256
	s_mov_b64 s[16:17], s[4:5]
	v_add_u32_e32 v161, s18, v156
	ds_read_u16 v0, v161 offset:0
	ds_read_u16 v1, v161 offset:8
	ds_read_u16 v2, v161 offset:16
	ds_read_u16 v3, v161 offset:24
	ds_read_u16 v4, v161 offset:32
	ds_read_u16 v5, v161 offset:40
	ds_read_u16 v6, v161 offset:48
	ds_read_u16 v7, v161 offset:56
	s_waitcnt lgkmcnt(7)
	s_add_i32 m0, s8, 0x0
	v_lshl_add_u32 v8, v0, 8, v10
	global_load_lds_dwordx4 v8, s[16:17]
	s_waitcnt lgkmcnt(6)
	s_add_i32 m0, s8, 0x400
	v_lshl_add_u32 v9, v1, 8, v11
	global_load_lds_dwordx4 v9, s[16:17]
	s_waitcnt lgkmcnt(5)
	s_add_i32 m0, s8, 0x800
	v_lshl_add_u32 v8, v2, 8, v12
	global_load_lds_dwordx4 v8, s[16:17]
	s_waitcnt lgkmcnt(4)
	s_add_i32 m0, s8, 0xc00
	v_lshl_add_u32 v9, v3, 8, v13
	global_load_lds_dwordx4 v9, s[16:17]
	s_waitcnt lgkmcnt(3)
	s_add_i32 m0, s8, 0x1000
	v_lshl_add_u32 v8, v4, 8, v10
	global_load_lds_dwordx4 v8, s[16:17]
	s_waitcnt lgkmcnt(2)
	s_add_i32 m0, s8, 0x1400
	v_lshl_add_u32 v9, v5, 8, v11
	global_load_lds_dwordx4 v9, s[16:17]
	s_waitcnt lgkmcnt(1)
	s_add_i32 m0, s8, 0x1800
	v_lshl_add_u32 v8, v6, 8, v12
	global_load_lds_dwordx4 v8, s[16:17]
	s_waitcnt lgkmcnt(0)
	s_add_i32 m0, s8, 0x1c00
	v_lshl_add_u32 v9, v7, 8, v13
	global_load_lds_dwordx4 v9, s[16:17]
	s_waitcnt vmcnt(8)
	ds_read_b64_tr_b16 v[104:105], v148 offset:8192
	ds_read_b64_tr_b16 v[106:107], v148 offset:12288
	ds_read_b64_tr_b16 v[108:109], v149 offset:8192
	ds_read_b64_tr_b16 v[110:111], v149 offset:12288
	ds_read_b64_tr_b16 v[112:113], v150 offset:8192
	ds_read_b64_tr_b16 v[114:115], v150 offset:12288
	ds_read_b64_tr_b16 v[116:117], v151 offset:8192
	ds_read_b64_tr_b16 v[118:119], v151 offset:12288
	ds_read_b64_tr_b16 v[120:121], v152 offset:8192
	ds_read_b64_tr_b16 v[122:123], v152 offset:12288
	ds_read_b64_tr_b16 v[124:125], v153 offset:8192
	ds_read_b64_tr_b16 v[126:127], v153 offset:12288
	ds_read_b64_tr_b16 v[128:129], v154 offset:8192
	ds_read_b64_tr_b16 v[130:131], v154 offset:12288
	s_waitcnt lgkmcnt(12)
	v_mfma_f32_16x16x32_bf16 v[176:179], v[48:51], v[104:107], v[176:179]
	ds_read_b64_tr_b16 v[132:133], v155 offset:8192
	ds_read_b64_tr_b16 v[134:135], v155 offset:12288
	s_waitcnt lgkmcnt(12)
	v_mfma_f32_16x16x32_bf16 v[180:183], v[48:51], v[108:111], v[180:183]
	s_waitcnt lgkmcnt(10)
	v_mfma_f32_16x16x32_bf16 v[184:187], v[48:51], v[112:115], v[184:187]
	s_waitcnt lgkmcnt(8)
	v_mfma_f32_16x16x32_bf16 v[188:191], v[48:51], v[116:119], v[188:191]
	s_waitcnt lgkmcnt(6)
	v_mfma_f32_16x16x32_bf16 v[192:195], v[48:51], v[120:123], v[192:195]
	s_waitcnt lgkmcnt(4)
	v_mfma_f32_16x16x32_bf16 v[196:199], v[48:51], v[124:127], v[196:199]
	s_waitcnt lgkmcnt(2)
	v_mfma_f32_16x16x32_bf16 v[200:203], v[48:51], v[128:131], v[200:203]
	s_waitcnt lgkmcnt(0)
	v_mfma_f32_16x16x32_bf16 v[204:207], v[48:51], v[132:135], v[204:207]
	s_add_i32 s18, s14, 320
	s_mov_b64 s[16:17], s[4:5]
	v_add_u32_e32 v161, s18, v156
	ds_read_u16 v0, v161 offset:0
	ds_read_u16 v1, v161 offset:8
	ds_read_u16 v2, v161 offset:16
	ds_read_u16 v3, v161 offset:24
	ds_read_u16 v4, v161 offset:32
	ds_read_u16 v5, v161 offset:40
	ds_read_u16 v6, v161 offset:48
	ds_read_u16 v7, v161 offset:56
	s_waitcnt lgkmcnt(7)
	s_add_i32 m0, s8, 0x2000
	v_lshl_add_u32 v8, v0, 8, v10
	global_load_lds_dwordx4 v8, s[16:17]
	s_waitcnt lgkmcnt(6)
	s_add_i32 m0, s8, 0x2400
	v_lshl_add_u32 v9, v1, 8, v11
	global_load_lds_dwordx4 v9, s[16:17]
	s_waitcnt lgkmcnt(5)
	s_add_i32 m0, s8, 0x2800
	v_lshl_add_u32 v8, v2, 8, v12
	global_load_lds_dwordx4 v8, s[16:17]
	s_waitcnt lgkmcnt(4)
	s_add_i32 m0, s8, 0x2c00
	v_lshl_add_u32 v9, v3, 8, v13
	global_load_lds_dwordx4 v9, s[16:17]
	s_waitcnt lgkmcnt(3)
	s_add_i32 m0, s8, 0x3000
	v_lshl_add_u32 v8, v4, 8, v10
	global_load_lds_dwordx4 v8, s[16:17]
	s_waitcnt lgkmcnt(2)
	s_add_i32 m0, s8, 0x3400
	v_lshl_add_u32 v9, v5, 8, v11
	global_load_lds_dwordx4 v9, s[16:17]
	s_waitcnt lgkmcnt(1)
	s_add_i32 m0, s8, 0x3800
	v_lshl_add_u32 v8, v6, 8, v12
	global_load_lds_dwordx4 v8, s[16:17]
	s_waitcnt lgkmcnt(0)
	s_add_i32 m0, s8, 0x3c00
	v_lshl_add_u32 v9, v7, 8, v13
	global_load_lds_dwordx4 v9, s[16:17]
	s_waitcnt vmcnt(8)
	ds_read_b64_tr_b16 v[104:105], v148 offset:0
	ds_read_b64_tr_b16 v[106:107], v148 offset:4096
	ds_read_b64_tr_b16 v[108:109], v149 offset:0
	ds_read_b64_tr_b16 v[110:111], v149 offset:4096
	ds_read_b64_tr_b16 v[112:113], v150 offset:0
	ds_read_b64_tr_b16 v[114:115], v150 offset:4096
	ds_read_b64_tr_b16 v[116:117], v151 offset:0
	ds_read_b64_tr_b16 v[118:119], v151 offset:4096
	ds_read_b64_tr_b16 v[120:121], v152 offset:0
	ds_read_b64_tr_b16 v[122:123], v152 offset:4096
	ds_read_b64_tr_b16 v[124:125], v153 offset:0
	ds_read_b64_tr_b16 v[126:127], v153 offset:4096
	ds_read_b64_tr_b16 v[128:129], v154 offset:0
	ds_read_b64_tr_b16 v[130:131], v154 offset:4096
	s_waitcnt lgkmcnt(12)
	v_mfma_f32_16x16x32_bf16 v[176:179], v[56:59], v[104:107], v[176:179]
	ds_read_b64_tr_b16 v[132:133], v155 offset:0
	ds_read_b64_tr_b16 v[134:135], v155 offset:4096
	s_waitcnt lgkmcnt(12)
	v_mfma_f32_16x16x32_bf16 v[180:183], v[56:59], v[108:111], v[180:183]
	s_waitcnt lgkmcnt(10)
	v_mfma_f32_16x16x32_bf16 v[184:187], v[56:59], v[112:115], v[184:187]
	s_waitcnt lgkmcnt(8)
	v_mfma_f32_16x16x32_bf16 v[188:191], v[56:59], v[116:119], v[188:191]
	s_waitcnt lgkmcnt(6)
	v_mfma_f32_16x16x32_bf16 v[192:195], v[56:59], v[120:123], v[192:195]
	s_waitcnt lgkmcnt(4)
	v_mfma_f32_16x16x32_bf16 v[196:199], v[56:59], v[124:127], v[196:199]
	s_waitcnt lgkmcnt(2)
	v_mfma_f32_16x16x32_bf16 v[200:203], v[56:59], v[128:131], v[200:203]
	s_waitcnt lgkmcnt(0)
	v_mfma_f32_16x16x32_bf16 v[204:207], v[56:59], v[132:135], v[204:207]
	s_add_i32 s18, s14, 384
	s_mov_b64 s[16:17], s[4:5]
	v_add_u32_e32 v161, s18, v156
	ds_read_u16 v0, v161 offset:0
	ds_read_u16 v1, v161 offset:8
	ds_read_u16 v2, v161 offset:16
	ds_read_u16 v3, v161 offset:24
	ds_read_u16 v4, v161 offset:32
	ds_read_u16 v5, v161 offset:40
	ds_read_u16 v6, v161 offset:48
	ds_read_u16 v7, v161 offset:56
	s_waitcnt lgkmcnt(7)
	s_add_i32 m0, s8, 0x0
	v_lshl_add_u32 v8, v0, 8, v10
	global_load_lds_dwordx4 v8, s[16:17]
	s_waitcnt lgkmcnt(6)
	s_add_i32 m0, s8, 0x400
	v_lshl_add_u32 v9, v1, 8, v11
	global_load_lds_dwordx4 v9, s[16:17]
	s_waitcnt lgkmcnt(5)
	s_add_i32 m0, s8, 0x800
	v_lshl_add_u32 v8, v2, 8, v12
	global_load_lds_dwordx4 v8, s[16:17]
	s_waitcnt lgkmcnt(4)
	s_add_i32 m0, s8, 0xc00
	v_lshl_add_u32 v9, v3, 8, v13
	global_load_lds_dwordx4 v9, s[16:17]
	s_waitcnt lgkmcnt(3)
	s_add_i32 m0, s8, 0x1000
	v_lshl_add_u32 v8, v4, 8, v10
	global_load_lds_dwordx4 v8, s[16:17]
	s_waitcnt lgkmcnt(2)
	s_add_i32 m0, s8, 0x1400
	v_lshl_add_u32 v9, v5, 8, v11
	global_load_lds_dwordx4 v9, s[16:17]
	s_waitcnt lgkmcnt(1)
	s_add_i32 m0, s8, 0x1800
	v_lshl_add_u32 v8, v6, 8, v12
	global_load_lds_dwordx4 v8, s[16:17]
	s_waitcnt lgkmcnt(0)
	s_add_i32 m0, s8, 0x1c00
	v_lshl_add_u32 v9, v7, 8, v13
	global_load_lds_dwordx4 v9, s[16:17]
	s_waitcnt vmcnt(8)
	ds_read_b64_tr_b16 v[104:105], v148 offset:8192
	ds_read_b64_tr_b16 v[106:107], v148 offset:12288
	ds_read_b64_tr_b16 v[108:109], v149 offset:8192
	ds_read_b64_tr_b16 v[110:111], v149 offset:12288
	ds_read_b64_tr_b16 v[112:113], v150 offset:8192
	ds_read_b64_tr_b16 v[114:115], v150 offset:12288
	ds_read_b64_tr_b16 v[116:117], v151 offset:8192
	ds_read_b64_tr_b16 v[118:119], v151 offset:12288
	ds_read_b64_tr_b16 v[120:121], v152 offset:8192
	ds_read_b64_tr_b16 v[122:123], v152 offset:12288
	ds_read_b64_tr_b16 v[124:125], v153 offset:8192
	ds_read_b64_tr_b16 v[126:127], v153 offset:12288
	ds_read_b64_tr_b16 v[128:129], v154 offset:8192
	ds_read_b64_tr_b16 v[130:131], v154 offset:12288
	s_waitcnt lgkmcnt(12)
	v_mfma_f32_16x16x32_bf16 v[176:179], v[64:67], v[104:107], v[176:179]
	ds_read_b64_tr_b16 v[132:133], v155 offset:8192
	ds_read_b64_tr_b16 v[134:135], v155 offset:12288
	s_waitcnt lgkmcnt(12)
	v_mfma_f32_16x16x32_bf16 v[180:183], v[64:67], v[108:111], v[180:183]
	s_waitcnt lgkmcnt(10)
	v_mfma_f32_16x16x32_bf16 v[184:187], v[64:67], v[112:115], v[184:187]
	s_waitcnt lgkmcnt(8)
	v_mfma_f32_16x16x32_bf16 v[188:191], v[64:67], v[116:119], v[188:191]
	s_waitcnt lgkmcnt(6)
	v_mfma_f32_16x16x32_bf16 v[192:195], v[64:67], v[120:123], v[192:195]
	s_waitcnt lgkmcnt(4)
	v_mfma_f32_16x16x32_bf16 v[196:199], v[64:67], v[124:127], v[196:199]
	s_waitcnt lgkmcnt(2)
	v_mfma_f32_16x16x32_bf16 v[200:203], v[64:67], v[128:131], v[200:203]
	s_waitcnt lgkmcnt(0)
	v_mfma_f32_16x16x32_bf16 v[204:207], v[64:67], v[132:135], v[204:207]
	s_add_i32 s18, s14, 448
	s_mov_b64 s[16:17], s[4:5]
	v_add_u32_e32 v161, s18, v156
	ds_read_u16 v0, v161 offset:0
	ds_read_u16 v1, v161 offset:8
	ds_read_u16 v2, v161 offset:16
	ds_read_u16 v3, v161 offset:24
	ds_read_u16 v4, v161 offset:32
	ds_read_u16 v5, v161 offset:40
	ds_read_u16 v6, v161 offset:48
	ds_read_u16 v7, v161 offset:56
	s_waitcnt lgkmcnt(7)
	s_add_i32 m0, s8, 0x2000
	v_lshl_add_u32 v8, v0, 8, v10
	global_load_lds_dwordx4 v8, s[16:17]
	s_waitcnt lgkmcnt(6)
	s_add_i32 m0, s8, 0x2400
	v_lshl_add_u32 v9, v1, 8, v11
	global_load_lds_dwordx4 v9, s[16:17]
	s_waitcnt lgkmcnt(5)
	s_add_i32 m0, s8, 0x2800
	v_lshl_add_u32 v8, v2, 8, v12
	global_load_lds_dwordx4 v8, s[16:17]
	s_waitcnt lgkmcnt(4)
	s_add_i32 m0, s8, 0x2c00
	v_lshl_add_u32 v9, v3, 8, v13
	global_load_lds_dwordx4 v9, s[16:17]
	s_waitcnt lgkmcnt(3)
	s_add_i32 m0, s8, 0x3000
	v_lshl_add_u32 v8, v4, 8, v10
	global_load_lds_dwordx4 v8, s[16:17]
	s_waitcnt lgkmcnt(2)
	s_add_i32 m0, s8, 0x3400
	v_lshl_add_u32 v9, v5, 8, v11
	global_load_lds_dwordx4 v9, s[16:17]
	s_waitcnt lgkmcnt(1)
	s_add_i32 m0, s8, 0x3800
	v_lshl_add_u32 v8, v6, 8, v12
	global_load_lds_dwordx4 v8, s[16:17]
	s_waitcnt lgkmcnt(0)
	s_add_i32 m0, s8, 0x3c00
	v_lshl_add_u32 v9, v7, 8, v13
	global_load_lds_dwordx4 v9, s[16:17]
	s_waitcnt vmcnt(8)
	ds_read_b64_tr_b16 v[104:105], v148 offset:0
	ds_read_b64_tr_b16 v[106:107], v148 offset:4096
	ds_read_b64_tr_b16 v[108:109], v149 offset:0
	ds_read_b64_tr_b16 v[110:111], v149 offset:4096
	ds_read_b64_tr_b16 v[112:113], v150 offset:0
	ds_read_b64_tr_b16 v[114:115], v150 offset:4096
	ds_read_b64_tr_b16 v[116:117], v151 offset:0
	ds_read_b64_tr_b16 v[118:119], v151 offset:4096
	ds_read_b64_tr_b16 v[120:121], v152 offset:0
	ds_read_b64_tr_b16 v[122:123], v152 offset:4096
	ds_read_b64_tr_b16 v[124:125], v153 offset:0
	ds_read_b64_tr_b16 v[126:127], v153 offset:4096
	ds_read_b64_tr_b16 v[128:129], v154 offset:0
	ds_read_b64_tr_b16 v[130:131], v154 offset:4096
	s_waitcnt lgkmcnt(12)
	v_mfma_f32_16x16x32_bf16 v[176:179], v[72:75], v[104:107], v[176:179]
	ds_read_b64_tr_b16 v[132:133], v155 offset:0
	ds_read_b64_tr_b16 v[134:135], v155 offset:4096
	s_waitcnt lgkmcnt(12)
	v_mfma_f32_16x16x32_bf16 v[180:183], v[72:75], v[108:111], v[180:183]
	s_waitcnt lgkmcnt(10)
	v_mfma_f32_16x16x32_bf16 v[184:187], v[72:75], v[112:115], v[184:187]
	s_waitcnt lgkmcnt(8)
	v_mfma_f32_16x16x32_bf16 v[188:191], v[72:75], v[116:119], v[188:191]
	s_waitcnt lgkmcnt(6)
	v_mfma_f32_16x16x32_bf16 v[192:195], v[72:75], v[120:123], v[192:195]
	s_waitcnt lgkmcnt(4)
	v_mfma_f32_16x16x32_bf16 v[196:199], v[72:75], v[124:127], v[196:199]
	s_waitcnt lgkmcnt(2)
	v_mfma_f32_16x16x32_bf16 v[200:203], v[72:75], v[128:131], v[200:203]
	s_waitcnt lgkmcnt(0)
	v_mfma_f32_16x16x32_bf16 v[204:207], v[72:75], v[132:135], v[204:207]
	s_cmp_eq_u32 s11, 1
	s_cbranch_scc1 .Lattn_lastv8
	s_add_i32 s18, s14, 512
	s_mov_b64 s[16:17], s[2:3]
	v_add_u32_e32 v161, s18, v156
	ds_read_u16 v0, v161 offset:0
	ds_read_u16 v1, v161 offset:8
	ds_read_u16 v2, v161 offset:16
	ds_read_u16 v3, v161 offset:24
	ds_read_u16 v4, v161 offset:32
	ds_read_u16 v5, v161 offset:40
	ds_read_u16 v6, v161 offset:48
	ds_read_u16 v7, v161 offset:56
	s_waitcnt lgkmcnt(7)
	s_add_i32 m0, s8, 0x0
	v_lshl_add_u32 v8, v0, 8, v10
	global_load_lds_dwordx4 v8, s[16:17]
	s_waitcnt lgkmcnt(6)
	s_add_i32 m0, s8, 0x400
	v_lshl_add_u32 v9, v1, 8, v11
	global_load_lds_dwordx4 v9, s[16:17]
	s_waitcnt lgkmcnt(5)
	s_add_i32 m0, s8, 0x800
	v_lshl_add_u32 v8, v2, 8, v12
	global_load_lds_dwordx4 v8, s[16:17]
	s_waitcnt lgkmcnt(4)
	s_add_i32 m0, s8, 0xc00
	v_lshl_add_u32 v9, v3, 8, v13
	global_load_lds_dwordx4 v9, s[16:17]
	s_waitcnt lgkmcnt(3)
	s_add_i32 m0, s8, 0x1000
	v_lshl_add_u32 v8, v4, 8, v10
	global_load_lds_dwordx4 v8, s[16:17]
	s_waitcnt lgkmcnt(2)
	s_add_i32 m0, s8, 0x1400
	v_lshl_add_u32 v9, v5, 8, v11
	global_load_lds_dwordx4 v9, s[16:17]
	s_waitcnt lgkmcnt(1)
	s_add_i32 m0, s8, 0x1800
	v_lshl_add_u32 v8, v6, 8, v12
	global_load_lds_dwordx4 v8, s[16:17]
	s_waitcnt lgkmcnt(0)
	s_add_i32 m0, s8, 0x1c00
	v_lshl_add_u32 v9, v7, 8, v13
	global_load_lds_dwordx4 v9, s[16:17]
	s_waitcnt vmcnt(8)
	s_branch .Lattn_lastj8

.Lattn_lastj8:
	ds_read_b64_tr_b16 v[104:105], v148 offset:8192
	ds_read_b64_tr_b16 v[106:107], v148 offset:12288
	ds_read_b64_tr_b16 v[108:109], v149 offset:8192
	ds_read_b64_tr_b16 v[110:111], v149 offset:12288
	ds_read_b64_tr_b16 v[112:113], v150 offset:8192
	ds_read_b64_tr_b16 v[114:115], v150 offset:12288
	ds_read_b64_tr_b16 v[116:117], v151 offset:8192
	ds_read_b64_tr_b16 v[118:119], v151 offset:12288
	ds_read_b64_tr_b16 v[120:121], v152 offset:8192
	ds_read_b64_tr_b16 v[122:123], v152 offset:12288
	ds_read_b64_tr_b16 v[124:125], v153 offset:8192
	ds_read_b64_tr_b16 v[126:127], v153 offset:12288
	ds_read_b64_tr_b16 v[128:129], v154 offset:8192
	ds_read_b64_tr_b16 v[130:131], v154 offset:12288
	s_waitcnt lgkmcnt(12)
	v_mfma_f32_16x16x32_bf16 v[176:179], v[80:83], v[104:107], v[176:179]
	ds_read_b64_tr_b16 v[132:133], v155 offset:8192
	ds_read_b64_tr_b16 v[134:135], v155 offset:12288
	s_waitcnt lgkmcnt(12)
	v_mfma_f32_16x16x32_bf16 v[180:183], v[80:83], v[108:111], v[180:183]
	s_waitcnt lgkmcnt(10)
	v_mfma_f32_16x16x32_bf16 v[184:187], v[80:83], v[112:115], v[184:187]
	s_waitcnt lgkmcnt(8)
	v_mfma_f32_16x16x32_bf16 v[188:191], v[80:83], v[116:119], v[188:191]
	s_waitcnt lgkmcnt(6)
	v_mfma_f32_16x16x32_bf16 v[192:195], v[80:83], v[120:123], v[192:195]
	s_waitcnt lgkmcnt(4)
	v_mfma_f32_16x16x32_bf16 v[196:199], v[80:83], v[124:127], v[196:199]
	s_waitcnt lgkmcnt(2)
	v_mfma_f32_16x16x32_bf16 v[200:203], v[80:83], v[128:131], v[200:203]
	s_waitcnt lgkmcnt(0)
	v_mfma_f32_16x16x32_bf16 v[204:207], v[80:83], v[132:135], v[204:207]
	s_nop 7
	s_mov_b32 exec_lo, -1
	s_mov_b32 exec_hi, 0
	v_cvt_pk_bf16_f32 v165, v176, 0
	ds_write_b16 v158, v165 offset:0
	v_cvt_pk_bf16_f32 v166, v177, 0
	ds_write_b16 v158, v166 offset:256
	v_cvt_pk_bf16_f32 v167, v178, 0
	ds_write_b16 v158, v167 offset:512
	v_cvt_pk_bf16_f32 v168, v179, 0
	ds_write_b16 v158, v168 offset:768
	v_cvt_pk_bf16_f32 v165, v180, 0
	ds_write_b16 v158, v165 offset:32
	v_cvt_pk_bf16_f32 v166, v181, 0
	ds_write_b16 v158, v166 offset:288
	v_cvt_pk_bf16_f32 v167, v182, 0
	ds_write_b16 v158, v167 offset:544
	v_cvt_pk_bf16_f32 v168, v183, 0
	ds_write_b16 v158, v168 offset:800
	v_cvt_pk_bf16_f32 v165, v184, 0
	ds_write_b16 v158, v165 offset:64
	v_cvt_pk_bf16_f32 v166, v185, 0
	ds_write_b16 v158, v166 offset:320
	v_cvt_pk_bf16_f32 v167, v186, 0
	ds_write_b16 v158, v167 offset:576
	v_cvt_pk_bf16_f32 v168, v187, 0
	ds_write_b16 v158, v168 offset:832
	v_cvt_pk_bf16_f32 v165, v188, 0
	ds_write_b16 v158, v165 offset:96
	v_cvt_pk_bf16_f32 v166, v189, 0
	ds_write_b16 v158, v166 offset:352
	v_cvt_pk_bf16_f32 v167, v190, 0
	ds_write_b16 v158, v167 offset:608
	v_cvt_pk_bf16_f32 v168, v191, 0
	ds_write_b16 v158, v168 offset:864
	v_cvt_pk_bf16_f32 v165, v192, 0
	ds_write_b16 v158, v165 offset:128
	v_cvt_pk_bf16_f32 v166, v193, 0
	ds_write_b16 v158, v166 offset:384
	v_cvt_pk_bf16_f32 v167, v194, 0
	ds_write_b16 v158, v167 offset:640
	v_cvt_pk_bf16_f32 v168, v195, 0
	ds_write_b16 v158, v168 offset:896
	v_cvt_pk_bf16_f32 v165, v196, 0
	ds_write_b16 v158, v165 offset:160
	v_cvt_pk_bf16_f32 v166, v197, 0
	ds_write_b16 v158, v166 offset:416
	v_cvt_pk_bf16_f32 v167, v198, 0
	ds_write_b16 v158, v167 offset:672
	v_cvt_pk_bf16_f32 v168, v199, 0
	ds_write_b16 v158, v168 offset:928
	v_cvt_pk_bf16_f32 v165, v200, 0
	ds_write_b16 v158, v165 offset:192
	v_cvt_pk_bf16_f32 v166, v201, 0
	ds_write_b16 v158, v166 offset:448
	v_cvt_pk_bf16_f32 v167, v202, 0
	ds_write_b16 v158, v167 offset:704
	v_cvt_pk_bf16_f32 v168, v203, 0
	ds_write_b16 v158, v168 offset:960
	v_cvt_pk_bf16_f32 v165, v204, 0
	ds_write_b16 v158, v165 offset:224
	v_cvt_pk_bf16_f32 v166, v205, 0
	ds_write_b16 v158, v166 offset:480
	v_cvt_pk_bf16_f32 v167, v206, 0
	ds_write_b16 v158, v167 offset:736
	v_cvt_pk_bf16_f32 v168, v207, 0
	ds_write_b16 v158, v168 offset:992
	s_mov_b64 exec, -1
	s_waitcnt lgkmcnt(0)
	ds_read_b128 v[104:107], v159
	ds_read_b128 v[108:111], v159 offset:1024
	s_lshl_b32 s13, s12, 12
	v_add_u32_e32 v162, s13, v160
	s_waitcnt lgkmcnt(1)
	global_store_dwordx4 v162, v[104:107], s[6:7]
	s_waitcnt lgkmcnt(0)
	global_store_dwordx4 v162, v[108:111], s[6:7] offset:1024
	s_add_i32 s11, s11, 1
	s_add_i32 s12, s12, 1
	s_addk_i32 s14, 0x200
	s_cmp_lt_u32 s11, 2
	s_cbranch_scc1 .Lattn_q8
	s_branch .Lattn_done

.Lattn_q6:
	s_add_i32 s18, s14, 64
	s_mov_b64 s[16:17], s[2:3]
	v_add_u32_e32 v161, s18, v156
	ds_read_u16 v0, v161 offset:0
	ds_read_u16 v1, v161 offset:8
	ds_read_u16 v2, v161 offset:16
	ds_read_u16 v3, v161 offset:24
	ds_read_u16 v4, v161 offset:32
	ds_read_u16 v5, v161 offset:40
	ds_read_u16 v6, v161 offset:48
	ds_read_u16 v7, v161 offset:56
	s_waitcnt lgkmcnt(7)
	s_add_i32 m0, s8, 0x2000
	v_lshl_add_u32 v8, v0, 8, v10
	global_load_lds_dwordx4 v8, s[16:17]
	s_waitcnt lgkmcnt(6)
	s_add_i32 m0, s8, 0x2400
	v_lshl_add_u32 v9, v1, 8, v11
	global_load_lds_dwordx4 v9, s[16:17]
	s_waitcnt lgkmcnt(5)
	s_add_i32 m0, s8, 0x2800
	v_lshl_add_u32 v8, v2, 8, v12
	global_load_lds_dwordx4 v8, s[16:17]
	s_waitcnt lgkmcnt(4)
	s_add_i32 m0, s8, 0x2c00
	v_lshl_add_u32 v9, v3, 8, v13
	global_load_lds_dwordx4 v9, s[16:17]
	s_waitcnt lgkmcnt(3)
	s_add_i32 m0, s8, 0x3000
	v_lshl_add_u32 v8, v4, 8, v10
	global_load_lds_dwordx4 v8, s[16:17]
	s_waitcnt lgkmcnt(2)
	s_add_i32 m0, s8, 0x3400
	v_lshl_add_u32 v9, v5, 8, v11
	global_load_lds_dwordx4 v9, s[16:17]
	s_waitcnt lgkmcnt(1)
	s_add_i32 m0, s8, 0x3800
	v_lshl_add_u32 v8, v6, 8, v12
	global_load_lds_dwordx4 v8, s[16:17]
	s_waitcnt lgkmcnt(0)
	s_add_i32 m0, s8, 0x3c00
	v_lshl_add_u32 v9, v7, 8, v13
	global_load_lds_dwordx4 v9, s[16:17]
	s_waitcnt vmcnt(8)
	ds_read_b128 v[104:107], v18 offset:0
	ds_read_b128 v[108:111], v19 offset:0
	ds_read_b128 v[112:115], v20 offset:0
	ds_read_b128 v[116:119], v21 offset:0
	ds_read_b128 v[120:123], v18 offset:4096
	ds_read_b128 v[124:127], v19 offset:4096
	ds_read_b128 v[128:131], v20 offset:4096
	ds_read_b128 v[132:135], v21 offset:4096
	s_waitcnt lgkmcnt(7)
	v_mfma_f32_16x16x32_bf16 v[136:139], v[104:107], v[88:91], 0
	s_waitcnt lgkmcnt(6)
	v_mfma_f32_16x16x32_bf16 v[136:139], v[108:111], v[92:95], v[136:139]
	s_waitcnt lgkmcnt(5)
	v_mfma_f32_16x16x32_bf16 v[136:139], v[112:115], v[96:99], v[136:139]
	s_waitcnt lgkmcnt(4)
	v_mfma_f32_16x16x32_bf16 v[136:139], v[116:119], v[100:103], v[136:139]
	s_waitcnt lgkmcnt(3)
	v_mfma_f32_16x16x32_bf16 v[140:143], v[120:123], v[88:91], 0
	s_waitcnt lgkmcnt(2)
	v_mfma_f32_16x16x32_bf16 v[140:143], v[124:127], v[92:95], v[140:143]
	s_waitcnt lgkmcnt(1)
	v_mfma_f32_16x16x32_bf16 v[140:143], v[128:131], v[96:99], v[140:143]
	s_waitcnt lgkmcnt(0)
	v_mfma_f32_16x16x32_bf16 v[140:143], v[132:135], v[100:103], v[140:143]
	v_mul_f32_e32 v24, 0x3db504f3, v136
	v_mul_f32_e32 v25, 0x3db504f3, v137
	v_mul_f32_e32 v26, 0x3db504f3, v138
	v_mul_f32_e32 v27, 0x3db504f3, v139
	s_nop 3
	v_mul_f32_e32 v28, 0x3db504f3, v140
	v_mul_f32_e32 v29, 0x3db504f3, v141
	v_mul_f32_e32 v30, 0x3db504f3, v142
	v_mul_f32_e32 v31, 0x3db504f3, v143
	s_add_i32 s18, s14, 128
	s_mov_b64 s[16:17], s[2:3]
	v_add_u32_e32 v161, s18, v156
	ds_read_u16 v0, v161 offset:0
	ds_read_u16 v1, v161 offset:8
	ds_read_u16 v2, v161 offset:16
	ds_read_u16 v3, v161 offset:24
	ds_read_u16 v4, v161 offset:32
	ds_read_u16 v5, v161 offset:40
	ds_read_u16 v6, v161 offset:48
	ds_read_u16 v7, v161 offset:56
	s_waitcnt lgkmcnt(7)
	s_add_i32 m0, s8, 0x0
	v_lshl_add_u32 v8, v0, 8, v10
	global_load_lds_dwordx4 v8, s[16:17]
	s_waitcnt lgkmcnt(6)
	s_add_i32 m0, s8, 0x400
	v_lshl_add_u32 v9, v1, 8, v11
	global_load_lds_dwordx4 v9, s[16:17]
	s_waitcnt lgkmcnt(5)
	s_add_i32 m0, s8, 0x800
	v_lshl_add_u32 v8, v2, 8, v12
	global_load_lds_dwordx4 v8, s[16:17]
	s_waitcnt lgkmcnt(4)
	s_add_i32 m0, s8, 0xc00
	v_lshl_add_u32 v9, v3, 8, v13
	global_load_lds_dwordx4 v9, s[16:17]
	s_waitcnt lgkmcnt(3)
	s_add_i32 m0, s8, 0x1000
	v_lshl_add_u32 v8, v4, 8, v10
	global_load_lds_dwordx4 v8, s[16:17]
	s_waitcnt lgkmcnt(2)
	s_add_i32 m0, s8, 0x1400
	v_lshl_add_u32 v9, v5, 8, v11
	global_load_lds_dwordx4 v9, s[16:17]
	s_waitcnt lgkmcnt(1)
	s_add_i32 m0, s8, 0x1800
	v_lshl_add_u32 v8, v6, 8, v12
	global_load_lds_dwordx4 v8, s[16:17]
	s_waitcnt lgkmcnt(0)
	s_add_i32 m0, s8, 0x1c00
	v_lshl_add_u32 v9, v7, 8, v13
	global_load_lds_dwordx4 v9, s[16:17]
	s_waitcnt vmcnt(8)
	ds_read_b128 v[104:107], v18 offset:8192
	ds_read_b128 v[108:111], v19 offset:8192
	ds_read_b128 v[112:115], v20 offset:8192
	ds_read_b128 v[116:119], v21 offset:8192
	ds_read_b128 v[120:123], v18 offset:12288
	ds_read_b128 v[124:127], v19 offset:12288
	ds_read_b128 v[128:131], v20 offset:12288
	ds_read_b128 v[132:135], v21 offset:12288
	s_waitcnt lgkmcnt(7)
	v_mfma_f32_16x16x32_bf16 v[136:139], v[104:107], v[88:91], 0
	s_waitcnt lgkmcnt(6)
	v_mfma_f32_16x16x32_bf16 v[136:139], v[108:111], v[92:95], v[136:139]
	s_waitcnt lgkmcnt(5)
	v_mfma_f32_16x16x32_bf16 v[136:139], v[112:115], v[96:99], v[136:139]
	s_waitcnt lgkmcnt(4)
	v_mfma_f32_16x16x32_bf16 v[136:139], v[116:119], v[100:103], v[136:139]
	s_waitcnt lgkmcnt(3)
	v_mfma_f32_16x16x32_bf16 v[140:143], v[120:123], v[88:91], 0
	s_waitcnt lgkmcnt(2)
	v_mfma_f32_16x16x32_bf16 v[140:143], v[124:127], v[92:95], v[140:143]
	s_waitcnt lgkmcnt(1)
	v_mfma_f32_16x16x32_bf16 v[140:143], v[128:131], v[96:99], v[140:143]
	s_waitcnt lgkmcnt(0)
	v_mfma_f32_16x16x32_bf16 v[140:143], v[132:135], v[100:103], v[140:143]
	v_mul_f32_e32 v32, 0x3db504f3, v136
	v_mul_f32_e32 v33, 0x3db504f3, v137
	v_mul_f32_e32 v34, 0x3db504f3, v138
	v_mul_f32_e32 v35, 0x3db504f3, v139
	s_nop 3
	v_mul_f32_e32 v36, 0x3db504f3, v140
	v_mul_f32_e32 v37, 0x3db504f3, v141
	v_mul_f32_e32 v38, 0x3db504f3, v142
	v_mul_f32_e32 v39, 0x3db504f3, v143
	s_add_i32 s18, s14, 192
	s_mov_b64 s[16:17], s[2:3]
	v_add_u32_e32 v161, s18, v156
	ds_read_u16 v0, v161 offset:0
	ds_read_u16 v1, v161 offset:8
	ds_read_u16 v2, v161 offset:16
	ds_read_u16 v3, v161 offset:24
	ds_read_u16 v4, v161 offset:32
	ds_read_u16 v5, v161 offset:40
	ds_read_u16 v6, v161 offset:48
	ds_read_u16 v7, v161 offset:56
	s_waitcnt lgkmcnt(7)
	s_add_i32 m0, s8, 0x2000
	v_lshl_add_u32 v8, v0, 8, v10
	global_load_lds_dwordx4 v8, s[16:17]
	s_waitcnt lgkmcnt(6)
	s_add_i32 m0, s8, 0x2400
	v_lshl_add_u32 v9, v1, 8, v11
	global_load_lds_dwordx4 v9, s[16:17]
	s_waitcnt lgkmcnt(5)
	s_add_i32 m0, s8, 0x2800
	v_lshl_add_u32 v8, v2, 8, v12
	global_load_lds_dwordx4 v8, s[16:17]
	s_waitcnt lgkmcnt(4)
	s_add_i32 m0, s8, 0x2c00
	v_lshl_add_u32 v9, v3, 8, v13
	global_load_lds_dwordx4 v9, s[16:17]
	s_waitcnt lgkmcnt(3)
	s_add_i32 m0, s8, 0x3000
	v_lshl_add_u32 v8, v4, 8, v10
	global_load_lds_dwordx4 v8, s[16:17]
	s_waitcnt lgkmcnt(2)
	s_add_i32 m0, s8, 0x3400
	v_lshl_add_u32 v9, v5, 8, v11
	global_load_lds_dwordx4 v9, s[16:17]
	s_waitcnt lgkmcnt(1)
	s_add_i32 m0, s8, 0x3800
	v_lshl_add_u32 v8, v6, 8, v12
	global_load_lds_dwordx4 v8, s[16:17]
	s_waitcnt lgkmcnt(0)
	s_add_i32 m0, s8, 0x3c00
	v_lshl_add_u32 v9, v7, 8, v13
	global_load_lds_dwordx4 v9, s[16:17]
	s_waitcnt vmcnt(8)
	ds_read_b128 v[104:107], v18 offset:0
	ds_read_b128 v[108:111], v19 offset:0
	ds_read_b128 v[112:115], v20 offset:0
	ds_read_b128 v[116:119], v21 offset:0
	ds_read_b128 v[120:123], v18 offset:4096
	ds_read_b128 v[124:127], v19 offset:4096
	ds_read_b128 v[128:131], v20 offset:4096
	ds_read_b128 v[132:135], v21 offset:4096
	s_waitcnt lgkmcnt(7)
	v_mfma_f32_16x16x32_bf16 v[136:139], v[104:107], v[88:91], 0
	s_waitcnt lgkmcnt(6)
	v_mfma_f32_16x16x32_bf16 v[136:139], v[108:111], v[92:95], v[136:139]
	s_waitcnt lgkmcnt(5)
	v_mfma_f32_16x16x32_bf16 v[136:139], v[112:115], v[96:99], v[136:139]
	s_waitcnt lgkmcnt(4)
	v_mfma_f32_16x16x32_bf16 v[136:139], v[116:119], v[100:103], v[136:139]
	s_waitcnt lgkmcnt(3)
	v_mfma_f32_16x16x32_bf16 v[140:143], v[120:123], v[88:91], 0
	s_waitcnt lgkmcnt(2)
	v_mfma_f32_16x16x32_bf16 v[140:143], v[124:127], v[92:95], v[140:143]
	s_waitcnt lgkmcnt(1)
	v_mfma_f32_16x16x32_bf16 v[140:143], v[128:131], v[96:99], v[140:143]
	s_waitcnt lgkmcnt(0)
	v_mfma_f32_16x16x32_bf16 v[140:143], v[132:135], v[100:103], v[140:143]
	v_mul_f32_e32 v40, 0x3db504f3, v136
	v_mul_f32_e32 v41, 0x3db504f3, v137
	v_mul_f32_e32 v42, 0x3db504f3, v138
	v_mul_f32_e32 v43, 0x3db504f3, v139
	s_nop 3
	v_mul_f32_e32 v44, 0x3db504f3, v140
	v_mul_f32_e32 v45, 0x3db504f3, v141
	v_mul_f32_e32 v46, 0x3db504f3, v142
	v_mul_f32_e32 v47, 0x3db504f3, v143
	s_add_i32 s18, s14, 256
	s_mov_b64 s[16:17], s[2:3]
	v_add_u32_e32 v161, s18, v156
	ds_read_u16 v0, v161 offset:0
	ds_read_u16 v1, v161 offset:8
	ds_read_u16 v2, v161 offset:16
	ds_read_u16 v3, v161 offset:24
	ds_read_u16 v4, v161 offset:32
	ds_read_u16 v5, v161 offset:40
	ds_read_u16 v6, v161 offset:48
	ds_read_u16 v7, v161 offset:56
	s_waitcnt lgkmcnt(7)
	s_add_i32 m0, s8, 0x0
	v_lshl_add_u32 v8, v0, 8, v10
	global_load_lds_dwordx4 v8, s[16:17]
	s_waitcnt lgkmcnt(6)
	s_add_i32 m0, s8, 0x400
	v_lshl_add_u32 v9, v1, 8, v11
	global_load_lds_dwordx4 v9, s[16:17]
	s_waitcnt lgkmcnt(5)
	s_add_i32 m0, s8, 0x800
	v_lshl_add_u32 v8, v2, 8, v12
	global_load_lds_dwordx4 v8, s[16:17]
	s_waitcnt lgkmcnt(4)
	s_add_i32 m0, s8, 0xc00
	v_lshl_add_u32 v9, v3, 8, v13
	global_load_lds_dwordx4 v9, s[16:17]
	s_waitcnt lgkmcnt(3)
	s_add_i32 m0, s8, 0x1000
	v_lshl_add_u32 v8, v4, 8, v10
	global_load_lds_dwordx4 v8, s[16:17]
	s_waitcnt lgkmcnt(2)
	s_add_i32 m0, s8, 0x1400
	v_lshl_add_u32 v9, v5, 8, v11
	global_load_lds_dwordx4 v9, s[16:17]
	s_waitcnt lgkmcnt(1)
	s_add_i32 m0, s8, 0x1800
	v_lshl_add_u32 v8, v6, 8, v12
	global_load_lds_dwordx4 v8, s[16:17]
	s_waitcnt lgkmcnt(0)
	s_add_i32 m0, s8, 0x1c00
	v_lshl_add_u32 v9, v7, 8, v13
	global_load_lds_dwordx4 v9, s[16:17]
	s_waitcnt vmcnt(8)
	ds_read_b128 v[104:107], v18 offset:8192
	ds_read_b128 v[108:111], v19 offset:8192
	ds_read_b128 v[112:115], v20 offset:8192
	ds_read_b128 v[116:119], v21 offset:8192
	ds_read_b128 v[120:123], v18 offset:12288
	ds_read_b128 v[124:127], v19 offset:12288
	ds_read_b128 v[128:131], v20 offset:12288
	ds_read_b128 v[132:135], v21 offset:12288
	s_waitcnt lgkmcnt(7)
	v_mfma_f32_16x16x32_bf16 v[136:139], v[104:107], v[88:91], 0
	s_waitcnt lgkmcnt(6)
	v_mfma_f32_16x16x32_bf16 v[136:139], v[108:111], v[92:95], v[136:139]
	s_waitcnt lgkmcnt(5)
	v_mfma_f32_16x16x32_bf16 v[136:139], v[112:115], v[96:99], v[136:139]
	s_waitcnt lgkmcnt(4)
	v_mfma_f32_16x16x32_bf16 v[136:139], v[116:119], v[100:103], v[136:139]
	s_waitcnt lgkmcnt(3)
	v_mfma_f32_16x16x32_bf16 v[140:143], v[120:123], v[88:91], 0
	s_waitcnt lgkmcnt(2)
	v_mfma_f32_16x16x32_bf16 v[140:143], v[124:127], v[92:95], v[140:143]
	s_waitcnt lgkmcnt(1)
	v_mfma_f32_16x16x32_bf16 v[140:143], v[128:131], v[96:99], v[140:143]
	s_waitcnt lgkmcnt(0)
	v_mfma_f32_16x16x32_bf16 v[140:143], v[132:135], v[100:103], v[140:143]
	v_mul_f32_e32 v48, 0x3db504f3, v136
	v_mul_f32_e32 v49, 0x3db504f3, v137
	v_mul_f32_e32 v50, 0x3db504f3, v138
	v_mul_f32_e32 v51, 0x3db504f3, v139
	s_nop 3
	v_mul_f32_e32 v52, 0x3db504f3, v140
	v_mul_f32_e32 v53, 0x3db504f3, v141
	v_mul_f32_e32 v54, 0x3db504f3, v142
	v_mul_f32_e32 v55, 0x3db504f3, v143
	s_add_i32 s18, s14, 320
	s_mov_b64 s[16:17], s[2:3]
	v_add_u32_e32 v161, s18, v156
	ds_read_u16 v0, v161 offset:0
	ds_read_u16 v1, v161 offset:8
	ds_read_u16 v2, v161 offset:16
	ds_read_u16 v3, v161 offset:24
	ds_read_u16 v4, v161 offset:32
	ds_read_u16 v5, v161 offset:40
	ds_read_u16 v6, v161 offset:48
	ds_read_u16 v7, v161 offset:56
	s_waitcnt lgkmcnt(7)
	s_add_i32 m0, s8, 0x2000
	v_lshl_add_u32 v8, v0, 8, v10
	global_load_lds_dwordx4 v8, s[16:17]
	s_waitcnt lgkmcnt(6)
	s_add_i32 m0, s8, 0x2400
	v_lshl_add_u32 v9, v1, 8, v11
	global_load_lds_dwordx4 v9, s[16:17]
	s_waitcnt lgkmcnt(5)
	s_add_i32 m0, s8, 0x2800
	v_lshl_add_u32 v8, v2, 8, v12
	global_load_lds_dwordx4 v8, s[16:17]
	s_waitcnt lgkmcnt(4)
	s_add_i32 m0, s8, 0x2c00
	v_lshl_add_u32 v9, v3, 8, v13
	global_load_lds_dwordx4 v9, s[16:17]
	s_waitcnt lgkmcnt(3)
	s_add_i32 m0, s8, 0x3000
	v_lshl_add_u32 v8, v4, 8, v10
	global_load_lds_dwordx4 v8, s[16:17]
	s_waitcnt lgkmcnt(2)
	s_add_i32 m0, s8, 0x3400
	v_lshl_add_u32 v9, v5, 8, v11
	global_load_lds_dwordx4 v9, s[16:17]
	s_waitcnt lgkmcnt(1)
	s_add_i32 m0, s8, 0x3800
	v_lshl_add_u32 v8, v6, 8, v12
	global_load_lds_dwordx4 v8, s[16:17]
	s_waitcnt lgkmcnt(0)
	s_add_i32 m0, s8, 0x3c00
	v_lshl_add_u32 v9, v7, 8, v13
	global_load_lds_dwordx4 v9, s[16:17]
	s_waitcnt vmcnt(8)
	ds_read_b128 v[104:107], v18 offset:0
	ds_read_b128 v[108:111], v19 offset:0
	ds_read_b128 v[112:115], v20 offset:0
	ds_read_b128 v[116:119], v21 offset:0
	ds_read_b128 v[120:123], v18 offset:4096
	ds_read_b128 v[124:127], v19 offset:4096
	ds_read_b128 v[128:131], v20 offset:4096
	ds_read_b128 v[132:135], v21 offset:4096
	s_waitcnt lgkmcnt(7)
	v_mfma_f32_16x16x32_bf16 v[136:139], v[104:107], v[88:91], 0
	s_waitcnt lgkmcnt(6)
	v_mfma_f32_16x16x32_bf16 v[136:139], v[108:111], v[92:95], v[136:139]
	s_waitcnt lgkmcnt(5)
	v_mfma_f32_16x16x32_bf16 v[136:139], v[112:115], v[96:99], v[136:139]
	s_waitcnt lgkmcnt(4)
	v_mfma_f32_16x16x32_bf16 v[136:139], v[116:119], v[100:103], v[136:139]
	s_waitcnt lgkmcnt(3)
	v_mfma_f32_16x16x32_bf16 v[140:143], v[120:123], v[88:91], 0
	s_waitcnt lgkmcnt(2)
	v_mfma_f32_16x16x32_bf16 v[140:143], v[124:127], v[92:95], v[140:143]
	s_waitcnt lgkmcnt(1)
	v_mfma_f32_16x16x32_bf16 v[140:143], v[128:131], v[96:99], v[140:143]
	s_waitcnt lgkmcnt(0)
	v_mfma_f32_16x16x32_bf16 v[140:143], v[132:135], v[100:103], v[140:143]
	v_mul_f32_e32 v56, 0x3db504f3, v136
	v_mul_f32_e32 v57, 0x3db504f3, v137
	v_mul_f32_e32 v58, 0x3db504f3, v138
	v_mul_f32_e32 v59, 0x3db504f3, v139
	s_nop 3
	v_mul_f32_e32 v60, 0x3db504f3, v140
	v_mul_f32_e32 v61, 0x3db504f3, v141
	v_mul_f32_e32 v62, 0x3db504f3, v142
	v_mul_f32_e32 v63, 0x3db504f3, v143
	s_mov_b32 s18, s14
	s_mov_b64 s[16:17], s[4:5]
	v_add_u32_e32 v161, s18, v156
	ds_read_u16 v0, v161 offset:0
	ds_read_u16 v1, v161 offset:8
	ds_read_u16 v2, v161 offset:16
	ds_read_u16 v3, v161 offset:24
	ds_read_u16 v4, v161 offset:32
	ds_read_u16 v5, v161 offset:40
	ds_read_u16 v6, v161 offset:48
	ds_read_u16 v7, v161 offset:56
	s_waitcnt lgkmcnt(7)
	s_add_i32 m0, s8, 0x0
	v_lshl_add_u32 v8, v0, 8, v10
	global_load_lds_dwordx4 v8, s[16:17]
	s_waitcnt lgkmcnt(6)
	s_add_i32 m0, s8, 0x400
	v_lshl_add_u32 v9, v1, 8, v11
	global_load_lds_dwordx4 v9, s[16:17]
	s_waitcnt lgkmcnt(5)
	s_add_i32 m0, s8, 0x800
	v_lshl_add_u32 v8, v2, 8, v12
	global_load_lds_dwordx4 v8, s[16:17]
	s_waitcnt lgkmcnt(4)
	s_add_i32 m0, s8, 0xc00
	v_lshl_add_u32 v9, v3, 8, v13
	global_load_lds_dwordx4 v9, s[16:17]
	s_waitcnt lgkmcnt(3)
	s_add_i32 m0, s8, 0x1000
	v_lshl_add_u32 v8, v4, 8, v10
	global_load_lds_dwordx4 v8, s[16:17]
	s_waitcnt lgkmcnt(2)
	s_add_i32 m0, s8, 0x1400
	v_lshl_add_u32 v9, v5, 8, v11
	global_load_lds_dwordx4 v9, s[16:17]
	s_waitcnt lgkmcnt(1)
	s_add_i32 m0, s8, 0x1800
	v_lshl_add_u32 v8, v6, 8, v12
	global_load_lds_dwordx4 v8, s[16:17]
	s_waitcnt lgkmcnt(0)
	s_add_i32 m0, s8, 0x1c00
	v_lshl_add_u32 v9, v7, 8, v13
	global_load_lds_dwordx4 v9, s[16:17]
	s_waitcnt vmcnt(8)
	ds_read_b128 v[104:107], v18 offset:8192
	ds_read_b128 v[108:111], v19 offset:8192
	ds_read_b128 v[112:115], v20 offset:8192
	ds_read_b128 v[116:119], v21 offset:8192
	ds_read_b128 v[120:123], v18 offset:12288
	ds_read_b128 v[124:127], v19 offset:12288
	ds_read_b128 v[128:131], v20 offset:12288
	ds_read_b128 v[132:135], v21 offset:12288
	s_waitcnt lgkmcnt(7)
	v_mfma_f32_16x16x32_bf16 v[136:139], v[104:107], v[88:91], 0
	s_waitcnt lgkmcnt(6)
	v_mfma_f32_16x16x32_bf16 v[136:139], v[108:111], v[92:95], v[136:139]
	s_waitcnt lgkmcnt(5)
	v_mfma_f32_16x16x32_bf16 v[136:139], v[112:115], v[96:99], v[136:139]
	s_waitcnt lgkmcnt(4)
	v_mfma_f32_16x16x32_bf16 v[136:139], v[116:119], v[100:103], v[136:139]
	s_waitcnt lgkmcnt(3)
	v_mfma_f32_16x16x32_bf16 v[140:143], v[120:123], v[88:91], 0
	s_waitcnt lgkmcnt(2)
	v_mfma_f32_16x16x32_bf16 v[140:143], v[124:127], v[92:95], v[140:143]
	s_waitcnt lgkmcnt(1)
	v_mfma_f32_16x16x32_bf16 v[140:143], v[128:131], v[96:99], v[140:143]
	s_waitcnt lgkmcnt(0)
	v_mfma_f32_16x16x32_bf16 v[140:143], v[132:135], v[100:103], v[140:143]
	v_mul_f32_e32 v64, 0x3db504f3, v136
	v_mul_f32_e32 v65, 0x3db504f3, v137
	v_mul_f32_e32 v66, 0x3db504f3, v138
	v_mul_f32_e32 v67, 0x3db504f3, v139
	s_nop 3
	v_mul_f32_e32 v68, 0x3db504f3, v140
	v_mul_f32_e32 v69, 0x3db504f3, v141
	v_mul_f32_e32 v70, 0x3db504f3, v142
	v_mul_f32_e32 v71, 0x3db504f3, v143
	v_max3_f32 v163, v24, v25, v26
	v_max3_f32 v163, v163, v27, v28
	v_max3_f32 v163, v163, v29, v30
	v_max3_f32 v163, v163, v31, v32
	v_max3_f32 v163, v163, v33, v34
	v_max3_f32 v163, v163, v35, v36
	v_max3_f32 v163, v163, v37, v38
	v_max3_f32 v163, v163, v39, v40
	v_max3_f32 v163, v163, v41, v42
	v_max3_f32 v163, v163, v43, v44
	v_max3_f32 v163, v163, v45, v46
	v_max3_f32 v163, v163, v47, v48
	v_max3_f32 v163, v163, v49, v50
	v_max3_f32 v163, v163, v51, v52
	v_max3_f32 v163, v163, v53, v54
	v_max3_f32 v163, v163, v55, v56
	v_max3_f32 v163, v163, v57, v58
	v_max3_f32 v163, v163, v59, v60
	v_max3_f32 v163, v163, v61, v62
	v_max3_f32 v163, v163, v63, v64
	v_max3_f32 v163, v163, v65, v66
	v_max3_f32 v163, v163, v67, v68
	v_max3_f32 v163, v163, v69, v70
	v_max_f32_e32 v163, v163, v71
	s_nop 0
	ds_bpermute_b32 v165, v147, v163
	s_waitcnt lgkmcnt(0)
	v_max_f32_e32 v163, v163, v165
	s_nop 0
	ds_bpermute_b32 v165, v146, v163
	s_waitcnt lgkmcnt(0)
	v_max_f32_e32 v163, v163, v165
	v_sub_f32_e32 v165, v24, v163
	v_mul_f32_e32 v165, 0x3fb8aa3b, v165
	v_exp_f32_e32 v24, v165
	v_sub_f32_e32 v166, v25, v163
	v_mul_f32_e32 v166, 0x3fb8aa3b, v166
	v_exp_f32_e32 v25, v166
	v_sub_f32_e32 v167, v26, v163
	v_mul_f32_e32 v167, 0x3fb8aa3b, v167
	v_exp_f32_e32 v26, v167
	v_add_f32_e32 v164, 0, v24
	v_sub_f32_e32 v168, v27, v163
	v_mul_f32_e32 v168, 0x3fb8aa3b, v168
	v_exp_f32_e32 v27, v168
	v_add_f32_e32 v164, v164, v25
	v_sub_f32_e32 v165, v28, v163
	v_mul_f32_e32 v165, 0x3fb8aa3b, v165
	v_exp_f32_e32 v28, v165
	v_add_f32_e32 v164, v164, v26
	v_sub_f32_e32 v166, v29, v163
	v_mul_f32_e32 v166, 0x3fb8aa3b, v166
	v_exp_f32_e32 v29, v166
	v_add_f32_e32 v164, v164, v27
	v_sub_f32_e32 v167, v30, v163
	v_mul_f32_e32 v167, 0x3fb8aa3b, v167
	v_exp_f32_e32 v30, v167
	v_add_f32_e32 v164, v164, v28
	v_sub_f32_e32 v168, v31, v163
	v_mul_f32_e32 v168, 0x3fb8aa3b, v168
	v_exp_f32_e32 v31, v168
	v_add_f32_e32 v164, v164, v29
	v_sub_f32_e32 v165, v32, v163
	v_mul_f32_e32 v165, 0x3fb8aa3b, v165
	v_exp_f32_e32 v32, v165
	v_add_f32_e32 v164, v164, v30
	v_sub_f32_e32 v166, v33, v163
	v_mul_f32_e32 v166, 0x3fb8aa3b, v166
	v_exp_f32_e32 v33, v166
	v_add_f32_e32 v164, v164, v31
	v_sub_f32_e32 v167, v34, v163
	v_mul_f32_e32 v167, 0x3fb8aa3b, v167
	v_exp_f32_e32 v34, v167
	v_add_f32_e32 v164, v164, v32
	v_sub_f32_e32 v168, v35, v163
	v_mul_f32_e32 v168, 0x3fb8aa3b, v168
	v_exp_f32_e32 v35, v168
	v_add_f32_e32 v164, v164, v33
	v_sub_f32_e32 v165, v36, v163
	v_mul_f32_e32 v165, 0x3fb8aa3b, v165
	v_exp_f32_e32 v36, v165
	v_add_f32_e32 v164, v164, v34
	v_sub_f32_e32 v166, v37, v163
	v_mul_f32_e32 v166, 0x3fb8aa3b, v166
	v_exp_f32_e32 v37, v166
	v_add_f32_e32 v164, v164, v35
	v_sub_f32_e32 v167, v38, v163
	v_mul_f32_e32 v167, 0x3fb8aa3b, v167
	v_exp_f32_e32 v38, v167
	v_add_f32_e32 v164, v164, v36
	v_sub_f32_e32 v168, v39, v163
	v_mul_f32_e32 v168, 0x3fb8aa3b, v168
	v_exp_f32_e32 v39, v168
	v_add_f32_e32 v164, v164, v37
	v_sub_f32_e32 v165, v40, v163
	v_mul_f32_e32 v165, 0x3fb8aa3b, v165
	v_exp_f32_e32 v40, v165
	v_add_f32_e32 v164, v164, v38
	v_sub_f32_e32 v166, v41, v163
	v_mul_f32_e32 v166, 0x3fb8aa3b, v166
	v_exp_f32_e32 v41, v166
	v_add_f32_e32 v164, v164, v39
	v_sub_f32_e32 v167, v42, v163
	v_mul_f32_e32 v167, 0x3fb8aa3b, v167
	v_exp_f32_e32 v42, v167
	v_add_f32_e32 v164, v164, v40
	v_sub_f32_e32 v168, v43, v163
	v_mul_f32_e32 v168, 0x3fb8aa3b, v168
	v_exp_f32_e32 v43, v168
	v_add_f32_e32 v164, v164, v41
	v_sub_f32_e32 v165, v44, v163
	v_mul_f32_e32 v165, 0x3fb8aa3b, v165
	v_exp_f32_e32 v44, v165
	v_add_f32_e32 v164, v164, v42
	v_sub_f32_e32 v166, v45, v163
	v_mul_f32_e32 v166, 0x3fb8aa3b, v166
	v_exp_f32_e32 v45, v166
	v_add_f32_e32 v164, v164, v43
	v_sub_f32_e32 v167, v46, v163
	v_mul_f32_e32 v167, 0x3fb8aa3b, v167
	v_exp_f32_e32 v46, v167
	v_add_f32_e32 v164, v164, v44
	v_sub_f32_e32 v168, v47, v163
	v_mul_f32_e32 v168, 0x3fb8aa3b, v168
	v_exp_f32_e32 v47, v168
	v_add_f32_e32 v164, v164, v45
	v_sub_f32_e32 v165, v48, v163
	v_mul_f32_e32 v165, 0x3fb8aa3b, v165
	v_exp_f32_e32 v48, v165
	v_add_f32_e32 v164, v164, v46
	v_sub_f32_e32 v166, v49, v163
	v_mul_f32_e32 v166, 0x3fb8aa3b, v166
	v_exp_f32_e32 v49, v166
	v_add_f32_e32 v164, v164, v47
	v_sub_f32_e32 v167, v50, v163
	v_mul_f32_e32 v167, 0x3fb8aa3b, v167
	v_exp_f32_e32 v50, v167
	v_add_f32_e32 v164, v164, v48
	v_sub_f32_e32 v168, v51, v163
	v_mul_f32_e32 v168, 0x3fb8aa3b, v168
	v_exp_f32_e32 v51, v168
	v_add_f32_e32 v164, v164, v49
	v_sub_f32_e32 v165, v52, v163
	v_mul_f32_e32 v165, 0x3fb8aa3b, v165
	v_exp_f32_e32 v52, v165
	v_add_f32_e32 v164, v164, v50
	v_sub_f32_e32 v166, v53, v163
	v_mul_f32_e32 v166, 0x3fb8aa3b, v166
	v_exp_f32_e32 v53, v166
	v_add_f32_e32 v164, v164, v51
	v_sub_f32_e32 v167, v54, v163
	v_mul_f32_e32 v167, 0x3fb8aa3b, v167
	v_exp_f32_e32 v54, v167
	v_add_f32_e32 v164, v164, v52
	v_sub_f32_e32 v168, v55, v163
	v_mul_f32_e32 v168, 0x3fb8aa3b, v168
	v_exp_f32_e32 v55, v168
	v_add_f32_e32 v164, v164, v53
	v_sub_f32_e32 v165, v56, v163
	v_mul_f32_e32 v165, 0x3fb8aa3b, v165
	v_exp_f32_e32 v56, v165
	v_add_f32_e32 v164, v164, v54
	v_sub_f32_e32 v166, v57, v163
	v_mul_f32_e32 v166, 0x3fb8aa3b, v166
	v_exp_f32_e32 v57, v166
	v_add_f32_e32 v164, v164, v55
	v_sub_f32_e32 v167, v58, v163
	v_mul_f32_e32 v167, 0x3fb8aa3b, v167
	v_exp_f32_e32 v58, v167
	v_add_f32_e32 v164, v164, v56
	v_sub_f32_e32 v168, v59, v163
	v_mul_f32_e32 v168, 0x3fb8aa3b, v168
	v_exp_f32_e32 v59, v168
	v_add_f32_e32 v164, v164, v57
	v_sub_f32_e32 v165, v60, v163
	v_mul_f32_e32 v165, 0x3fb8aa3b, v165
	v_exp_f32_e32 v60, v165
	v_add_f32_e32 v164, v164, v58
	v_sub_f32_e32 v166, v61, v163
	v_mul_f32_e32 v166, 0x3fb8aa3b, v166
	v_exp_f32_e32 v61, v166
	v_add_f32_e32 v164, v164, v59
	v_sub_f32_e32 v167, v62, v163
	v_mul_f32_e32 v167, 0x3fb8aa3b, v167
	v_exp_f32_e32 v62, v167
	v_add_f32_e32 v164, v164, v60
	v_sub_f32_e32 v168, v63, v163
	v_mul_f32_e32 v168, 0x3fb8aa3b, v168
	v_exp_f32_e32 v63, v168
	v_add_f32_e32 v164, v164, v61
	v_sub_f32_e32 v165, v64, v163
	v_mul_f32_e32 v165, 0x3fb8aa3b, v165
	v_exp_f32_e32 v64, v165
	v_add_f32_e32 v164, v164, v62
	v_sub_f32_e32 v166, v65, v163
	v_mul_f32_e32 v166, 0x3fb8aa3b, v166
	v_exp_f32_e32 v65, v166
	v_add_f32_e32 v164, v164, v63
	v_sub_f32_e32 v167, v66, v163
	v_mul_f32_e32 v167, 0x3fb8aa3b, v167
	v_exp_f32_e32 v66, v167
	v_add_f32_e32 v164, v164, v64
	v_sub_f32_e32 v168, v67, v163
	v_mul_f32_e32 v168, 0x3fb8aa3b, v168
	v_exp_f32_e32 v67, v168
	v_add_f32_e32 v164, v164, v65
	v_sub_f32_e32 v165, v68, v163
	v_mul_f32_e32 v165, 0x3fb8aa3b, v165
	v_exp_f32_e32 v68, v165
	v_add_f32_e32 v164, v164, v66
	v_sub_f32_e32 v166, v69, v163
	v_mul_f32_e32 v166, 0x3fb8aa3b, v166
	v_exp_f32_e32 v69, v166
	v_add_f32_e32 v164, v164, v67
	v_sub_f32_e32 v167, v70, v163
	v_mul_f32_e32 v167, 0x3fb8aa3b, v167
	v_exp_f32_e32 v70, v167
	v_add_f32_e32 v164, v164, v68
	v_sub_f32_e32 v168, v71, v163
	v_mul_f32_e32 v168, 0x3fb8aa3b, v168
	v_exp_f32_e32 v71, v168
	v_add_f32_e32 v164, v164, v69
	s_nop 0
	v_add_f32_e32 v164, v164, v70
	v_add_f32_e32 v164, v164, v71
	s_nop 0
	ds_bpermute_b32 v165, v147, v164
	s_waitcnt lgkmcnt(0)
	v_add_f32_e32 v164, v164, v165
	s_nop 0
	ds_bpermute_b32 v165, v146, v164
	s_waitcnt lgkmcnt(0)
	v_add_f32_e32 v164, v164, v165
	v_div_scale_f32 v170, s[74:75], v164, v164, 1.0
	v_rcp_f32_e32 v171, v170
	s_nop 0
	v_fma_f32 v172, -v170, v171, 1.0
	v_fmac_f32_e32 v171, v172, v171
	v_div_scale_f32 v172, vcc, 1.0, v164, 1.0
	v_mul_f32_e32 v173, v172, v171
	v_fma_f32 v169, -v170, v173, v172
	v_fmac_f32_e32 v173, v169, v171
	v_fma_f32 v170, -v170, v173, v172
	v_div_fmas_f32 v170, v170, v171, v173
	v_div_fixup_f32 v169, v170, v164, 1.0
	v_mul_f32_e32 v165, v24, v169
	v_mul_f32_e32 v166, v25, v169
	v_cvt_pk_bf16_f32 v24, v165, v166
	v_mul_f32_e32 v167, v26, v169
	v_mul_f32_e32 v168, v27, v169
	v_cvt_pk_bf16_f32 v25, v167, v168
	v_mul_f32_e32 v165, v28, v169
	v_mul_f32_e32 v166, v29, v169
	v_cvt_pk_bf16_f32 v26, v165, v166
	v_mul_f32_e32 v167, v30, v169
	v_mul_f32_e32 v168, v31, v169
	v_cvt_pk_bf16_f32 v27, v167, v168
	v_mul_f32_e32 v165, v32, v169
	v_mul_f32_e32 v166, v33, v169
	v_cvt_pk_bf16_f32 v32, v165, v166
	v_mul_f32_e32 v167, v34, v169
	v_mul_f32_e32 v168, v35, v169
	v_cvt_pk_bf16_f32 v33, v167, v168
	v_mul_f32_e32 v165, v36, v169
	v_mul_f32_e32 v166, v37, v169
	v_cvt_pk_bf16_f32 v34, v165, v166
	v_mul_f32_e32 v167, v38, v169
	v_mul_f32_e32 v168, v39, v169
	v_cvt_pk_bf16_f32 v35, v167, v168
	v_mul_f32_e32 v165, v40, v169
	v_mul_f32_e32 v166, v41, v169
	v_cvt_pk_bf16_f32 v40, v165, v166
	v_mul_f32_e32 v167, v42, v169
	v_mul_f32_e32 v168, v43, v169
	v_cvt_pk_bf16_f32 v41, v167, v168
	v_mul_f32_e32 v165, v44, v169
	v_mul_f32_e32 v166, v45, v169
	v_cvt_pk_bf16_f32 v42, v165, v166
	v_mul_f32_e32 v167, v46, v169
	v_mul_f32_e32 v168, v47, v169
	v_cvt_pk_bf16_f32 v43, v167, v168
	v_mul_f32_e32 v165, v48, v169
	v_mul_f32_e32 v166, v49, v169
	v_cvt_pk_bf16_f32 v48, v165, v166
	v_mul_f32_e32 v167, v50, v169
	v_mul_f32_e32 v168, v51, v169
	v_cvt_pk_bf16_f32 v49, v167, v168
	v_mul_f32_e32 v165, v52, v169
	v_mul_f32_e32 v166, v53, v169
	v_cvt_pk_bf16_f32 v50, v165, v166
	v_mul_f32_e32 v167, v54, v169
	v_mul_f32_e32 v168, v55, v169
	v_cvt_pk_bf16_f32 v51, v167, v168
	v_mul_f32_e32 v165, v56, v169
	v_mul_f32_e32 v166, v57, v169
	v_cvt_pk_bf16_f32 v56, v165, v166
	v_mul_f32_e32 v167, v58, v169
	v_mul_f32_e32 v168, v59, v169
	v_cvt_pk_bf16_f32 v57, v167, v168
	v_mul_f32_e32 v165, v60, v169
	v_mul_f32_e32 v166, v61, v169
	v_cvt_pk_bf16_f32 v58, v165, v166
	v_mul_f32_e32 v167, v62, v169
	v_mul_f32_e32 v168, v63, v169
	v_cvt_pk_bf16_f32 v59, v167, v168
	v_mul_f32_e32 v165, v64, v169
	v_mul_f32_e32 v166, v65, v169
	v_cvt_pk_bf16_f32 v64, v165, v166
	v_mul_f32_e32 v167, v66, v169
	v_mul_f32_e32 v168, v67, v169
	v_cvt_pk_bf16_f32 v65, v167, v168
	v_mul_f32_e32 v165, v68, v169
	v_mul_f32_e32 v166, v69, v169
	v_cvt_pk_bf16_f32 v66, v165, v166
	v_mul_f32_e32 v167, v70, v169
	v_mul_f32_e32 v168, v71, v169
	v_cvt_pk_bf16_f32 v67, v167, v168
	s_cmp_eq_u32 s11, 1
	s_cbranch_scc1 .Lattn_noq6
	s_add_i32 s15, s12, 1
	s_lshl_b32 s13, s15, 12
	v_add_u32_e32 v162, s13, v157
	global_load_dwordx4 v[88:91], v162, s[6:7] offset:0
	global_load_dwordx4 v[92:95], v162, s[6:7] offset:64
	global_load_dwordx4 v[96:99], v162, s[6:7] offset:128
	global_load_dwordx4 v[100:103], v162, s[6:7] offset:192
.Lattn_noq6:
	s_add_i32 s18, s14, 64
	s_mov_b64 s[16:17], s[4:5]
	v_add_u32_e32 v161, s18, v156
	ds_read_u16 v0, v161 offset:0
	ds_read_u16 v1, v161 offset:8
	ds_read_u16 v2, v161 offset:16
	ds_read_u16 v3, v161 offset:24
	ds_read_u16 v4, v161 offset:32
	ds_read_u16 v5, v161 offset:40
	ds_read_u16 v6, v161 offset:48
	ds_read_u16 v7, v161 offset:56
	s_waitcnt lgkmcnt(7)
	s_add_i32 m0, s8, 0x2000
	v_lshl_add_u32 v8, v0, 8, v10
	global_load_lds_dwordx4 v8, s[16:17]
	s_waitcnt lgkmcnt(6)
	s_add_i32 m0, s8, 0x2400
	v_lshl_add_u32 v9, v1, 8, v11
	global_load_lds_dwordx4 v9, s[16:17]
	s_waitcnt lgkmcnt(5)
	s_add_i32 m0, s8, 0x2800
	v_lshl_add_u32 v8, v2, 8, v12
	global_load_lds_dwordx4 v8, s[16:17]
	s_waitcnt lgkmcnt(4)
	s_add_i32 m0, s8, 0x2c00
	v_lshl_add_u32 v9, v3, 8, v13
	global_load_lds_dwordx4 v9, s[16:17]
	s_waitcnt lgkmcnt(3)
	s_add_i32 m0, s8, 0x3000
	v_lshl_add_u32 v8, v4, 8, v10
	global_load_lds_dwordx4 v8, s[16:17]
	s_waitcnt lgkmcnt(2)
	s_add_i32 m0, s8, 0x3400
	v_lshl_add_u32 v9, v5, 8, v11
	global_load_lds_dwordx4 v9, s[16:17]
	s_waitcnt lgkmcnt(1)
	s_add_i32 m0, s8, 0x3800
	v_lshl_add_u32 v8, v6, 8, v12
	global_load_lds_dwordx4 v8, s[16:17]
	s_waitcnt lgkmcnt(0)
	s_add_i32 m0, s8, 0x3c00
	v_lshl_add_u32 v9, v7, 8, v13
	global_load_lds_dwordx4 v9, s[16:17]
	s_waitcnt vmcnt(8)
	ds_read_b64_tr_b16 v[104:105], v148 offset:0
	ds_read_b64_tr_b16 v[106:107], v148 offset:4096
	ds_read_b64_tr_b16 v[108:109], v149 offset:0
	ds_read_b64_tr_b16 v[110:111], v149 offset:4096
	ds_read_b64_tr_b16 v[112:113], v150 offset:0
	ds_read_b64_tr_b16 v[114:115], v150 offset:4096
	ds_read_b64_tr_b16 v[116:117], v151 offset:0
	ds_read_b64_tr_b16 v[118:119], v151 offset:4096
	ds_read_b64_tr_b16 v[120:121], v152 offset:0
	ds_read_b64_tr_b16 v[122:123], v152 offset:4096
	ds_read_b64_tr_b16 v[124:125], v153 offset:0
	ds_read_b64_tr_b16 v[126:127], v153 offset:4096
	ds_read_b64_tr_b16 v[128:129], v154 offset:0
	ds_read_b64_tr_b16 v[130:131], v154 offset:4096
	s_waitcnt lgkmcnt(12)
	v_mfma_f32_16x16x32_bf16 v[176:179], v[24:27], v[104:107], 0
	ds_read_b64_tr_b16 v[132:133], v155 offset:0
	ds_read_b64_tr_b16 v[134:135], v155 offset:4096
	s_waitcnt lgkmcnt(12)
	v_mfma_f32_16x16x32_bf16 v[180:183], v[24:27], v[108:111], 0
	s_waitcnt lgkmcnt(10)
	v_mfma_f32_16x16x32_bf16 v[184:187], v[24:27], v[112:115], 0
	s_waitcnt lgkmcnt(8)
	v_mfma_f32_16x16x32_bf16 v[188:191], v[24:27], v[116:119], 0
	s_waitcnt lgkmcnt(6)
	v_mfma_f32_16x16x32_bf16 v[192:195], v[24:27], v[120:123], 0
	s_waitcnt lgkmcnt(4)
	v_mfma_f32_16x16x32_bf16 v[196:199], v[24:27], v[124:127], 0
	s_waitcnt lgkmcnt(2)
	v_mfma_f32_16x16x32_bf16 v[200:203], v[24:27], v[128:131], 0
	s_waitcnt lgkmcnt(0)
	v_mfma_f32_16x16x32_bf16 v[204:207], v[24:27], v[132:135], 0
	s_add_i32 s18, s14, 128
	s_mov_b64 s[16:17], s[4:5]
	v_add_u32_e32 v161, s18, v156
	ds_read_u16 v0, v161 offset:0
	ds_read_u16 v1, v161 offset:8
	ds_read_u16 v2, v161 offset:16
	ds_read_u16 v3, v161 offset:24
	ds_read_u16 v4, v161 offset:32
	ds_read_u16 v5, v161 offset:40
	ds_read_u16 v6, v161 offset:48
	ds_read_u16 v7, v161 offset:56
	s_waitcnt lgkmcnt(7)
	s_add_i32 m0, s8, 0x0
	v_lshl_add_u32 v8, v0, 8, v10
	global_load_lds_dwordx4 v8, s[16:17]
	s_waitcnt lgkmcnt(6)
	s_add_i32 m0, s8, 0x400
	v_lshl_add_u32 v9, v1, 8, v11
	global_load_lds_dwordx4 v9, s[16:17]
	s_waitcnt lgkmcnt(5)
	s_add_i32 m0, s8, 0x800
	v_lshl_add_u32 v8, v2, 8, v12
	global_load_lds_dwordx4 v8, s[16:17]
	s_waitcnt lgkmcnt(4)
	s_add_i32 m0, s8, 0xc00
	v_lshl_add_u32 v9, v3, 8, v13
	global_load_lds_dwordx4 v9, s[16:17]
	s_waitcnt lgkmcnt(3)
	s_add_i32 m0, s8, 0x1000
	v_lshl_add_u32 v8, v4, 8, v10
	global_load_lds_dwordx4 v8, s[16:17]
	s_waitcnt lgkmcnt(2)
	s_add_i32 m0, s8, 0x1400
	v_lshl_add_u32 v9, v5, 8, v11
	global_load_lds_dwordx4 v9, s[16:17]
	s_waitcnt lgkmcnt(1)
	s_add_i32 m0, s8, 0x1800
	v_lshl_add_u32 v8, v6, 8, v12
	global_load_lds_dwordx4 v8, s[16:17]
	s_waitcnt lgkmcnt(0)
	s_add_i32 m0, s8, 0x1c00
	v_lshl_add_u32 v9, v7, 8, v13
	global_load_lds_dwordx4 v9, s[16:17]
	s_waitcnt vmcnt(8)
	ds_read_b64_tr_b16 v[104:105], v148 offset:8192
	ds_read_b64_tr_b16 v[106:107], v148 offset:12288
	ds_read_b64_tr_b16 v[108:109], v149 offset:8192
	ds_read_b64_tr_b16 v[110:111], v149 offset:12288
	ds_read_b64_tr_b16 v[112:113], v150 offset:8192
	ds_read_b64_tr_b16 v[114:115], v150 offset:12288
	ds_read_b64_tr_b16 v[116:117], v151 offset:8192
	ds_read_b64_tr_b16 v[118:119], v151 offset:12288
	ds_read_b64_tr_b16 v[120:121], v152 offset:8192
	ds_read_b64_tr_b16 v[122:123], v152 offset:12288
	ds_read_b64_tr_b16 v[124:125], v153 offset:8192
	ds_read_b64_tr_b16 v[126:127], v153 offset:12288
	ds_read_b64_tr_b16 v[128:129], v154 offset:8192
	ds_read_b64_tr_b16 v[130:131], v154 offset:12288
	s_waitcnt lgkmcnt(12)
	v_mfma_f32_16x16x32_bf16 v[176:179], v[32:35], v[104:107], v[176:179]
	ds_read_b64_tr_b16 v[132:133], v155 offset:8192
	ds_read_b64_tr_b16 v[134:135], v155 offset:12288
	s_waitcnt lgkmcnt(12)
	v_mfma_f32_16x16x32_bf16 v[180:183], v[32:35], v[108:111], v[180:183]
	s_waitcnt lgkmcnt(10)
	v_mfma_f32_16x16x32_bf16 v[184:187], v[32:35], v[112:115], v[184:187]
	s_waitcnt lgkmcnt(8)
	v_mfma_f32_16x16x32_bf16 v[188:191], v[32:35], v[116:119], v[188:191]
	s_waitcnt lgkmcnt(6)
	v_mfma_f32_16x16x32_bf16 v[192:195], v[32:35], v[120:123], v[192:195]
	s_waitcnt lgkmcnt(4)
	v_mfma_f32_16x16x32_bf16 v[196:199], v[32:35], v[124:127], v[196:199]
	s_waitcnt lgkmcnt(2)
	v_mfma_f32_16x16x32_bf16 v[200:203], v[32:35], v[128:131], v[200:203]
	s_waitcnt lgkmcnt(0)
	v_mfma_f32_16x16x32_bf16 v[204:207], v[32:35], v[132:135], v[204:207]
	s_add_i32 s18, s14, 192
	s_mov_b64 s[16:17], s[4:5]
	v_add_u32_e32 v161, s18, v156
	ds_read_u16 v0, v161 offset:0
	ds_read_u16 v1, v161 offset:8
	ds_read_u16 v2, v161 offset:16
	ds_read_u16 v3, v161 offset:24
	ds_read_u16 v4, v161 offset:32
	ds_read_u16 v5, v161 offset:40
	ds_read_u16 v6, v161 offset:48
	ds_read_u16 v7, v161 offset:56
	s_waitcnt lgkmcnt(7)
	s_add_i32 m0, s8, 0x2000
	v_lshl_add_u32 v8, v0, 8, v10
	global_load_lds_dwordx4 v8, s[16:17]
	s_waitcnt lgkmcnt(6)
	s_add_i32 m0, s8, 0x2400
	v_lshl_add_u32 v9, v1, 8, v11
	global_load_lds_dwordx4 v9, s[16:17]
	s_waitcnt lgkmcnt(5)
	s_add_i32 m0, s8, 0x2800
	v_lshl_add_u32 v8, v2, 8, v12
	global_load_lds_dwordx4 v8, s[16:17]
	s_waitcnt lgkmcnt(4)
	s_add_i32 m0, s8, 0x2c00
	v_lshl_add_u32 v9, v3, 8, v13
	global_load_lds_dwordx4 v9, s[16:17]
	s_waitcnt lgkmcnt(3)
	s_add_i32 m0, s8, 0x3000
	v_lshl_add_u32 v8, v4, 8, v10
	global_load_lds_dwordx4 v8, s[16:17]
	s_waitcnt lgkmcnt(2)
	s_add_i32 m0, s8, 0x3400
	v_lshl_add_u32 v9, v5, 8, v11
	global_load_lds_dwordx4 v9, s[16:17]
	s_waitcnt lgkmcnt(1)
	s_add_i32 m0, s8, 0x3800
	v_lshl_add_u32 v8, v6, 8, v12
	global_load_lds_dwordx4 v8, s[16:17]
	s_waitcnt lgkmcnt(0)
	s_add_i32 m0, s8, 0x3c00
	v_lshl_add_u32 v9, v7, 8, v13
	global_load_lds_dwordx4 v9, s[16:17]
	s_waitcnt vmcnt(8)
	ds_read_b64_tr_b16 v[104:105], v148 offset:0
	ds_read_b64_tr_b16 v[106:107], v148 offset:4096
	ds_read_b64_tr_b16 v[108:109], v149 offset:0
	ds_read_b64_tr_b16 v[110:111], v149 offset:4096
	ds_read_b64_tr_b16 v[112:113], v150 offset:0
	ds_read_b64_tr_b16 v[114:115], v150 offset:4096
	ds_read_b64_tr_b16 v[116:117], v151 offset:0
	ds_read_b64_tr_b16 v[118:119], v151 offset:4096
	ds_read_b64_tr_b16 v[120:121], v152 offset:0
	ds_read_b64_tr_b16 v[122:123], v152 offset:4096
	ds_read_b64_tr_b16 v[124:125], v153 offset:0
	ds_read_b64_tr_b16 v[126:127], v153 offset:4096
	ds_read_b64_tr_b16 v[128:129], v154 offset:0
	ds_read_b64_tr_b16 v[130:131], v154 offset:4096
	s_waitcnt lgkmcnt(12)
	v_mfma_f32_16x16x32_bf16 v[176:179], v[40:43], v[104:107], v[176:179]
	ds_read_b64_tr_b16 v[132:133], v155 offset:0
	ds_read_b64_tr_b16 v[134:135], v155 offset:4096
	s_waitcnt lgkmcnt(12)
	v_mfma_f32_16x16x32_bf16 v[180:183], v[40:43], v[108:111], v[180:183]
	s_waitcnt lgkmcnt(10)
	v_mfma_f32_16x16x32_bf16 v[184:187], v[40:43], v[112:115], v[184:187]
	s_waitcnt lgkmcnt(8)
	v_mfma_f32_16x16x32_bf16 v[188:191], v[40:43], v[116:119], v[188:191]
	s_waitcnt lgkmcnt(6)
	v_mfma_f32_16x16x32_bf16 v[192:195], v[40:43], v[120:123], v[192:195]
	s_waitcnt lgkmcnt(4)
	v_mfma_f32_16x16x32_bf16 v[196:199], v[40:43], v[124:127], v[196:199]
	s_waitcnt lgkmcnt(2)
	v_mfma_f32_16x16x32_bf16 v[200:203], v[40:43], v[128:131], v[200:203]
	s_waitcnt lgkmcnt(0)
	v_mfma_f32_16x16x32_bf16 v[204:207], v[40:43], v[132:135], v[204:207]
	s_add_i32 s18, s14, 256
	s_mov_b64 s[16:17], s[4:5]
	v_add_u32_e32 v161, s18, v156
	ds_read_u16 v0, v161 offset:0
	ds_read_u16 v1, v161 offset:8
	ds_read_u16 v2, v161 offset:16
	ds_read_u16 v3, v161 offset:24
	ds_read_u16 v4, v161 offset:32
	ds_read_u16 v5, v161 offset:40
	ds_read_u16 v6, v161 offset:48
	ds_read_u16 v7, v161 offset:56
	s_waitcnt lgkmcnt(7)
	s_add_i32 m0, s8, 0x0
	v_lshl_add_u32 v8, v0, 8, v10
	global_load_lds_dwordx4 v8, s[16:17]
	s_waitcnt lgkmcnt(6)
	s_add_i32 m0, s8, 0x400
	v_lshl_add_u32 v9, v1, 8, v11
	global_load_lds_dwordx4 v9, s[16:17]
	s_waitcnt lgkmcnt(5)
	s_add_i32 m0, s8, 0x800
	v_lshl_add_u32 v8, v2, 8, v12
	global_load_lds_dwordx4 v8, s[16:17]
	s_waitcnt lgkmcnt(4)
	s_add_i32 m0, s8, 0xc00
	v_lshl_add_u32 v9, v3, 8, v13
	global_load_lds_dwordx4 v9, s[16:17]
	s_waitcnt lgkmcnt(3)
	s_add_i32 m0, s8, 0x1000
	v_lshl_add_u32 v8, v4, 8, v10
	global_load_lds_dwordx4 v8, s[16:17]
	s_waitcnt lgkmcnt(2)
	s_add_i32 m0, s8, 0x1400
	v_lshl_add_u32 v9, v5, 8, v11
	global_load_lds_dwordx4 v9, s[16:17]
	s_waitcnt lgkmcnt(1)
	s_add_i32 m0, s8, 0x1800
	v_lshl_add_u32 v8, v6, 8, v12
	global_load_lds_dwordx4 v8, s[16:17]
	s_waitcnt lgkmcnt(0)
	s_add_i32 m0, s8, 0x1c00
	v_lshl_add_u32 v9, v7, 8, v13
	global_load_lds_dwordx4 v9, s[16:17]
	s_waitcnt vmcnt(8)
	ds_read_b64_tr_b16 v[104:105], v148 offset:8192
	ds_read_b64_tr_b16 v[106:107], v148 offset:12288
	ds_read_b64_tr_b16 v[108:109], v149 offset:8192
	ds_read_b64_tr_b16 v[110:111], v149 offset:12288
	ds_read_b64_tr_b16 v[112:113], v150 offset:8192
	ds_read_b64_tr_b16 v[114:115], v150 offset:12288
	ds_read_b64_tr_b16 v[116:117], v151 offset:8192
	ds_read_b64_tr_b16 v[118:119], v151 offset:12288
	ds_read_b64_tr_b16 v[120:121], v152 offset:8192
	ds_read_b64_tr_b16 v[122:123], v152 offset:12288
	ds_read_b64_tr_b16 v[124:125], v153 offset:8192
	ds_read_b64_tr_b16 v[126:127], v153 offset:12288
	ds_read_b64_tr_b16 v[128:129], v154 offset:8192
	ds_read_b64_tr_b16 v[130:131], v154 offset:12288
	s_waitcnt lgkmcnt(12)
	v_mfma_f32_16x16x32_bf16 v[176:179], v[48:51], v[104:107], v[176:179]
	ds_read_b64_tr_b16 v[132:133], v155 offset:8192
	ds_read_b64_tr_b16 v[134:135], v155 offset:12288
	s_waitcnt lgkmcnt(12)
	v_mfma_f32_16x16x32_bf16 v[180:183], v[48:51], v[108:111], v[180:183]
	s_waitcnt lgkmcnt(10)
	v_mfma_f32_16x16x32_bf16 v[184:187], v[48:51], v[112:115], v[184:187]
	s_waitcnt lgkmcnt(8)
	v_mfma_f32_16x16x32_bf16 v[188:191], v[48:51], v[116:119], v[188:191]
	s_waitcnt lgkmcnt(6)
	v_mfma_f32_16x16x32_bf16 v[192:195], v[48:51], v[120:123], v[192:195]
	s_waitcnt lgkmcnt(4)
	v_mfma_f32_16x16x32_bf16 v[196:199], v[48:51], v[124:127], v[196:199]
	s_waitcnt lgkmcnt(2)
	v_mfma_f32_16x16x32_bf16 v[200:203], v[48:51], v[128:131], v[200:203]
	s_waitcnt lgkmcnt(0)
	v_mfma_f32_16x16x32_bf16 v[204:207], v[48:51], v[132:135], v[204:207]
	s_add_i32 s18, s14, 320
	s_mov_b64 s[16:17], s[4:5]
	v_add_u32_e32 v161, s18, v156
	ds_read_u16 v0, v161 offset:0
	ds_read_u16 v1, v161 offset:8
	ds_read_u16 v2, v161 offset:16
	ds_read_u16 v3, v161 offset:24
	ds_read_u16 v4, v161 offset:32
	ds_read_u16 v5, v161 offset:40
	ds_read_u16 v6, v161 offset:48
	ds_read_u16 v7, v161 offset:56
	s_waitcnt lgkmcnt(7)
	s_add_i32 m0, s8, 0x2000
	v_lshl_add_u32 v8, v0, 8, v10
	global_load_lds_dwordx4 v8, s[16:17]
	s_waitcnt lgkmcnt(6)
	s_add_i32 m0, s8, 0x2400
	v_lshl_add_u32 v9, v1, 8, v11
	global_load_lds_dwordx4 v9, s[16:17]
	s_waitcnt lgkmcnt(5)
	s_add_i32 m0, s8, 0x2800
	v_lshl_add_u32 v8, v2, 8, v12
	global_load_lds_dwordx4 v8, s[16:17]
	s_waitcnt lgkmcnt(4)
	s_add_i32 m0, s8, 0x2c00
	v_lshl_add_u32 v9, v3, 8, v13
	global_load_lds_dwordx4 v9, s[16:17]
	s_waitcnt lgkmcnt(3)
	s_add_i32 m0, s8, 0x3000
	v_lshl_add_u32 v8, v4, 8, v10
	global_load_lds_dwordx4 v8, s[16:17]
	s_waitcnt lgkmcnt(2)
	s_add_i32 m0, s8, 0x3400
	v_lshl_add_u32 v9, v5, 8, v11
	global_load_lds_dwordx4 v9, s[16:17]
	s_waitcnt lgkmcnt(1)
	s_add_i32 m0, s8, 0x3800
	v_lshl_add_u32 v8, v6, 8, v12
	global_load_lds_dwordx4 v8, s[16:17]
	s_waitcnt lgkmcnt(0)
	s_add_i32 m0, s8, 0x3c00
	v_lshl_add_u32 v9, v7, 8, v13
	global_load_lds_dwordx4 v9, s[16:17]
	s_waitcnt vmcnt(8)
	ds_read_b64_tr_b16 v[104:105], v148 offset:0
	ds_read_b64_tr_b16 v[106:107], v148 offset:4096
	ds_read_b64_tr_b16 v[108:109], v149 offset:0
	ds_read_b64_tr_b16 v[110:111], v149 offset:4096
	ds_read_b64_tr_b16 v[112:113], v150 offset:0
	ds_read_b64_tr_b16 v[114:115], v150 offset:4096
	ds_read_b64_tr_b16 v[116:117], v151 offset:0
	ds_read_b64_tr_b16 v[118:119], v151 offset:4096
	ds_read_b64_tr_b16 v[120:121], v152 offset:0
	ds_read_b64_tr_b16 v[122:123], v152 offset:4096
	ds_read_b64_tr_b16 v[124:125], v153 offset:0
	ds_read_b64_tr_b16 v[126:127], v153 offset:4096
	ds_read_b64_tr_b16 v[128:129], v154 offset:0
	ds_read_b64_tr_b16 v[130:131], v154 offset:4096
	s_waitcnt lgkmcnt(12)
	v_mfma_f32_16x16x32_bf16 v[176:179], v[56:59], v[104:107], v[176:179]
	ds_read_b64_tr_b16 v[132:133], v155 offset:0
	ds_read_b64_tr_b16 v[134:135], v155 offset:4096
	s_waitcnt lgkmcnt(12)
	v_mfma_f32_16x16x32_bf16 v[180:183], v[56:59], v[108:111], v[180:183]
	s_waitcnt lgkmcnt(10)
	v_mfma_f32_16x16x32_bf16 v[184:187], v[56:59], v[112:115], v[184:187]
	s_waitcnt lgkmcnt(8)
	v_mfma_f32_16x16x32_bf16 v[188:191], v[56:59], v[116:119], v[188:191]
	s_waitcnt lgkmcnt(6)
	v_mfma_f32_16x16x32_bf16 v[192:195], v[56:59], v[120:123], v[192:195]
	s_waitcnt lgkmcnt(4)
	v_mfma_f32_16x16x32_bf16 v[196:199], v[56:59], v[124:127], v[196:199]
	s_waitcnt lgkmcnt(2)
	v_mfma_f32_16x16x32_bf16 v[200:203], v[56:59], v[128:131], v[200:203]
	s_waitcnt lgkmcnt(0)
	v_mfma_f32_16x16x32_bf16 v[204:207], v[56:59], v[132:135], v[204:207]
	s_cmp_eq_u32 s11, 1
	s_cbranch_scc1 .Lattn_lastv6
	s_add_i32 s18, s14, 512
	s_mov_b64 s[16:17], s[2:3]
	v_add_u32_e32 v161, s18, v156
	ds_read_u16 v0, v161 offset:0
	ds_read_u16 v1, v161 offset:8
	ds_read_u16 v2, v161 offset:16
	ds_read_u16 v3, v161 offset:24
	ds_read_u16 v4, v161 offset:32
	ds_read_u16 v5, v161 offset:40
	ds_read_u16 v6, v161 offset:48
	ds_read_u16 v7, v161 offset:56
	s_waitcnt lgkmcnt(7)
	s_add_i32 m0, s8, 0x0
	v_lshl_add_u32 v8, v0, 8, v10
	global_load_lds_dwordx4 v8, s[16:17]
	s_waitcnt lgkmcnt(6)
	s_add_i32 m0, s8, 0x400
	v_lshl_add_u32 v9, v1, 8, v11
	global_load_lds_dwordx4 v9, s[16:17]
	s_waitcnt lgkmcnt(5)
	s_add_i32 m0, s8, 0x800
	v_lshl_add_u32 v8, v2, 8, v12
	global_load_lds_dwordx4 v8, s[16:17]
	s_waitcnt lgkmcnt(4)
	s_add_i32 m0, s8, 0xc00
	v_lshl_add_u32 v9, v3, 8, v13
	global_load_lds_dwordx4 v9, s[16:17]
	s_waitcnt lgkmcnt(3)
	s_add_i32 m0, s8, 0x1000
	v_lshl_add_u32 v8, v4, 8, v10
	global_load_lds_dwordx4 v8, s[16:17]
	s_waitcnt lgkmcnt(2)
	s_add_i32 m0, s8, 0x1400
	v_lshl_add_u32 v9, v5, 8, v11
	global_load_lds_dwordx4 v9, s[16:17]
	s_waitcnt lgkmcnt(1)
	s_add_i32 m0, s8, 0x1800
	v_lshl_add_u32 v8, v6, 8, v12
	global_load_lds_dwordx4 v8, s[16:17]
	s_waitcnt lgkmcnt(0)
	s_add_i32 m0, s8, 0x1c00
	v_lshl_add_u32 v9, v7, 8, v13
	global_load_lds_dwordx4 v9, s[16:17]
	s_waitcnt vmcnt(8)
	s_branch .Lattn_lastj6

.Lattn_lastj6:
	ds_read_b64_tr_b16 v[104:105], v148 offset:8192
	ds_read_b64_tr_b16 v[106:107], v148 offset:12288
	ds_read_b64_tr_b16 v[108:109], v149 offset:8192
	ds_read_b64_tr_b16 v[110:111], v149 offset:12288
	ds_read_b64_tr_b16 v[112:113], v150 offset:8192
	ds_read_b64_tr_b16 v[114:115], v150 offset:12288
	ds_read_b64_tr_b16 v[116:117], v151 offset:8192
	ds_read_b64_tr_b16 v[118:119], v151 offset:12288
	ds_read_b64_tr_b16 v[120:121], v152 offset:8192
	ds_read_b64_tr_b16 v[122:123], v152 offset:12288
	ds_read_b64_tr_b16 v[124:125], v153 offset:8192
	ds_read_b64_tr_b16 v[126:127], v153 offset:12288
	ds_read_b64_tr_b16 v[128:129], v154 offset:8192
	ds_read_b64_tr_b16 v[130:131], v154 offset:12288
	s_waitcnt lgkmcnt(12)
	v_mfma_f32_16x16x32_bf16 v[176:179], v[64:67], v[104:107], v[176:179]
	ds_read_b64_tr_b16 v[132:133], v155 offset:8192
	ds_read_b64_tr_b16 v[134:135], v155 offset:12288
	s_waitcnt lgkmcnt(12)
	v_mfma_f32_16x16x32_bf16 v[180:183], v[64:67], v[108:111], v[180:183]
	s_waitcnt lgkmcnt(10)
	v_mfma_f32_16x16x32_bf16 v[184:187], v[64:67], v[112:115], v[184:187]
	s_waitcnt lgkmcnt(8)
	v_mfma_f32_16x16x32_bf16 v[188:191], v[64:67], v[116:119], v[188:191]
	s_waitcnt lgkmcnt(6)
	v_mfma_f32_16x16x32_bf16 v[192:195], v[64:67], v[120:123], v[192:195]
	s_waitcnt lgkmcnt(4)
	v_mfma_f32_16x16x32_bf16 v[196:199], v[64:67], v[124:127], v[196:199]
	s_waitcnt lgkmcnt(2)
	v_mfma_f32_16x16x32_bf16 v[200:203], v[64:67], v[128:131], v[200:203]
	s_waitcnt lgkmcnt(0)
	v_mfma_f32_16x16x32_bf16 v[204:207], v[64:67], v[132:135], v[204:207]
	s_nop 7
	s_mov_b32 exec_lo, -1
	s_mov_b32 exec_hi, 0
	v_cvt_pk_bf16_f32 v165, v176, 0
	ds_write_b16 v158, v165 offset:0
	v_cvt_pk_bf16_f32 v166, v177, 0
	ds_write_b16 v158, v166 offset:256
	v_cvt_pk_bf16_f32 v167, v178, 0
	ds_write_b16 v158, v167 offset:512
	v_cvt_pk_bf16_f32 v168, v179, 0
	ds_write_b16 v158, v168 offset:768
	v_cvt_pk_bf16_f32 v165, v180, 0
	ds_write_b16 v158, v165 offset:32
	v_cvt_pk_bf16_f32 v166, v181, 0
	ds_write_b16 v158, v166 offset:288
	v_cvt_pk_bf16_f32 v167, v182, 0
	ds_write_b16 v158, v167 offset:544
	v_cvt_pk_bf16_f32 v168, v183, 0
	ds_write_b16 v158, v168 offset:800
	v_cvt_pk_bf16_f32 v165, v184, 0
	ds_write_b16 v158, v165 offset:64
	v_cvt_pk_bf16_f32 v166, v185, 0
	ds_write_b16 v158, v166 offset:320
	v_cvt_pk_bf16_f32 v167, v186, 0
	ds_write_b16 v158, v167 offset:576
	v_cvt_pk_bf16_f32 v168, v187, 0
	ds_write_b16 v158, v168 offset:832
	v_cvt_pk_bf16_f32 v165, v188, 0
	ds_write_b16 v158, v165 offset:96
	v_cvt_pk_bf16_f32 v166, v189, 0
	ds_write_b16 v158, v166 offset:352
	v_cvt_pk_bf16_f32 v167, v190, 0
	ds_write_b16 v158, v167 offset:608
	v_cvt_pk_bf16_f32 v168, v191, 0
	ds_write_b16 v158, v168 offset:864
	v_cvt_pk_bf16_f32 v165, v192, 0
	ds_write_b16 v158, v165 offset:128
	v_cvt_pk_bf16_f32 v166, v193, 0
	ds_write_b16 v158, v166 offset:384
	v_cvt_pk_bf16_f32 v167, v194, 0
	ds_write_b16 v158, v167 offset:640
	v_cvt_pk_bf16_f32 v168, v195, 0
	ds_write_b16 v158, v168 offset:896
	v_cvt_pk_bf16_f32 v165, v196, 0
	ds_write_b16 v158, v165 offset:160
	v_cvt_pk_bf16_f32 v166, v197, 0
	ds_write_b16 v158, v166 offset:416
	v_cvt_pk_bf16_f32 v167, v198, 0
	ds_write_b16 v158, v167 offset:672
	v_cvt_pk_bf16_f32 v168, v199, 0
	ds_write_b16 v158, v168 offset:928
	v_cvt_pk_bf16_f32 v165, v200, 0
	ds_write_b16 v158, v165 offset:192
	v_cvt_pk_bf16_f32 v166, v201, 0
	ds_write_b16 v158, v166 offset:448
	v_cvt_pk_bf16_f32 v167, v202, 0
	ds_write_b16 v158, v167 offset:704
	v_cvt_pk_bf16_f32 v168, v203, 0
	ds_write_b16 v158, v168 offset:960
	v_cvt_pk_bf16_f32 v165, v204, 0
	ds_write_b16 v158, v165 offset:224
	v_cvt_pk_bf16_f32 v166, v205, 0
	ds_write_b16 v158, v166 offset:480
	v_cvt_pk_bf16_f32 v167, v206, 0
	ds_write_b16 v158, v167 offset:736
	v_cvt_pk_bf16_f32 v168, v207, 0
	ds_write_b16 v158, v168 offset:992
	s_mov_b64 exec, -1
	s_waitcnt lgkmcnt(0)
	ds_read_b128 v[104:107], v159
	ds_read_b128 v[108:111], v159 offset:1024
	s_lshl_b32 s13, s12, 12
	v_add_u32_e32 v162, s13, v160
	s_waitcnt lgkmcnt(1)
	global_store_dwordx4 v162, v[104:107], s[6:7]
	s_waitcnt lgkmcnt(0)
	global_store_dwordx4 v162, v[108:111], s[6:7] offset:1024
	s_add_i32 s11, s11, 1
	s_add_i32 s12, s12, 1
	s_addk_i32 s14, 0x200
	s_cmp_lt_u32 s11, 2
	s_cbranch_scc1 .Lattn_q6
	s_branch .Lattn_done
.Lattn_q4:
	s_add_i32 s18, s14, 64
	s_mov_b64 s[16:17], s[2:3]
	v_add_u32_e32 v161, s18, v156
	ds_read_u16 v0, v161 offset:0
	ds_read_u16 v1, v161 offset:8
	ds_read_u16 v2, v161 offset:16
	ds_read_u16 v3, v161 offset:24
	ds_read_u16 v4, v161 offset:32
	ds_read_u16 v5, v161 offset:40
	ds_read_u16 v6, v161 offset:48
	ds_read_u16 v7, v161 offset:56
	s_waitcnt lgkmcnt(7)
	s_add_i32 m0, s8, 0x2000
	v_lshl_add_u32 v8, v0, 8, v10
	global_load_lds_dwordx4 v8, s[16:17]
	s_waitcnt lgkmcnt(6)
	s_add_i32 m0, s8, 0x2400
	v_lshl_add_u32 v9, v1, 8, v11
	global_load_lds_dwordx4 v9, s[16:17]
	s_waitcnt lgkmcnt(5)
	s_add_i32 m0, s8, 0x2800
	v_lshl_add_u32 v8, v2, 8, v12
	global_load_lds_dwordx4 v8, s[16:17]
	s_waitcnt lgkmcnt(4)
	s_add_i32 m0, s8, 0x2c00
	v_lshl_add_u32 v9, v3, 8, v13
	global_load_lds_dwordx4 v9, s[16:17]
	s_waitcnt lgkmcnt(3)
	s_add_i32 m0, s8, 0x3000
	v_lshl_add_u32 v8, v4, 8, v10
	global_load_lds_dwordx4 v8, s[16:17]
	s_waitcnt lgkmcnt(2)
	s_add_i32 m0, s8, 0x3400
	v_lshl_add_u32 v9, v5, 8, v11
	global_load_lds_dwordx4 v9, s[16:17]
	s_waitcnt lgkmcnt(1)
	s_add_i32 m0, s8, 0x3800
	v_lshl_add_u32 v8, v6, 8, v12
	global_load_lds_dwordx4 v8, s[16:17]
	s_waitcnt lgkmcnt(0)
	s_add_i32 m0, s8, 0x3c00
	v_lshl_add_u32 v9, v7, 8, v13
	global_load_lds_dwordx4 v9, s[16:17]
	s_waitcnt vmcnt(8)
	ds_read_b128 v[104:107], v18 offset:0
	ds_read_b128 v[108:111], v19 offset:0
	ds_read_b128 v[112:115], v20 offset:0
	ds_read_b128 v[116:119], v21 offset:0
	ds_read_b128 v[120:123], v18 offset:4096
	ds_read_b128 v[124:127], v19 offset:4096
	ds_read_b128 v[128:131], v20 offset:4096
	ds_read_b128 v[132:135], v21 offset:4096
	s_waitcnt lgkmcnt(7)
	v_mfma_f32_16x16x32_bf16 v[136:139], v[104:107], v[88:91], 0
	s_waitcnt lgkmcnt(6)
	v_mfma_f32_16x16x32_bf16 v[136:139], v[108:111], v[92:95], v[136:139]
	s_waitcnt lgkmcnt(5)
	v_mfma_f32_16x16x32_bf16 v[136:139], v[112:115], v[96:99], v[136:139]
	s_waitcnt lgkmcnt(4)
	v_mfma_f32_16x16x32_bf16 v[136:139], v[116:119], v[100:103], v[136:139]
	s_waitcnt lgkmcnt(3)
	v_mfma_f32_16x16x32_bf16 v[140:143], v[120:123], v[88:91], 0
	s_waitcnt lgkmcnt(2)
	v_mfma_f32_16x16x32_bf16 v[140:143], v[124:127], v[92:95], v[140:143]
	s_waitcnt lgkmcnt(1)
	v_mfma_f32_16x16x32_bf16 v[140:143], v[128:131], v[96:99], v[140:143]
	s_waitcnt lgkmcnt(0)
	v_mfma_f32_16x16x32_bf16 v[140:143], v[132:135], v[100:103], v[140:143]
	v_mul_f32_e32 v24, 0x3db504f3, v136
	v_mul_f32_e32 v25, 0x3db504f3, v137
	v_mul_f32_e32 v26, 0x3db504f3, v138
	v_mul_f32_e32 v27, 0x3db504f3, v139
	s_nop 3
	v_mul_f32_e32 v28, 0x3db504f3, v140
	v_mul_f32_e32 v29, 0x3db504f3, v141
	v_mul_f32_e32 v30, 0x3db504f3, v142
	v_mul_f32_e32 v31, 0x3db504f3, v143
	s_add_i32 s18, s14, 128
	s_mov_b64 s[16:17], s[2:3]
	v_add_u32_e32 v161, s18, v156
	ds_read_u16 v0, v161 offset:0
	ds_read_u16 v1, v161 offset:8
	ds_read_u16 v2, v161 offset:16
	ds_read_u16 v3, v161 offset:24
	ds_read_u16 v4, v161 offset:32
	ds_read_u16 v5, v161 offset:40
	ds_read_u16 v6, v161 offset:48
	ds_read_u16 v7, v161 offset:56
	s_waitcnt lgkmcnt(7)
	s_add_i32 m0, s8, 0x0
	v_lshl_add_u32 v8, v0, 8, v10
	global_load_lds_dwordx4 v8, s[16:17]
	s_waitcnt lgkmcnt(6)
	s_add_i32 m0, s8, 0x400
	v_lshl_add_u32 v9, v1, 8, v11
	global_load_lds_dwordx4 v9, s[16:17]
	s_waitcnt lgkmcnt(5)
	s_add_i32 m0, s8, 0x800
	v_lshl_add_u32 v8, v2, 8, v12
	global_load_lds_dwordx4 v8, s[16:17]
	s_waitcnt lgkmcnt(4)
	s_add_i32 m0, s8, 0xc00
	v_lshl_add_u32 v9, v3, 8, v13
	global_load_lds_dwordx4 v9, s[16:17]
	s_waitcnt lgkmcnt(3)
	s_add_i32 m0, s8, 0x1000
	v_lshl_add_u32 v8, v4, 8, v10
	global_load_lds_dwordx4 v8, s[16:17]
	s_waitcnt lgkmcnt(2)
	s_add_i32 m0, s8, 0x1400
	v_lshl_add_u32 v9, v5, 8, v11
	global_load_lds_dwordx4 v9, s[16:17]
	s_waitcnt lgkmcnt(1)
	s_add_i32 m0, s8, 0x1800
	v_lshl_add_u32 v8, v6, 8, v12
	global_load_lds_dwordx4 v8, s[16:17]
	s_waitcnt lgkmcnt(0)
	s_add_i32 m0, s8, 0x1c00
	v_lshl_add_u32 v9, v7, 8, v13
	global_load_lds_dwordx4 v9, s[16:17]
	s_waitcnt vmcnt(8)
	ds_read_b128 v[104:107], v18 offset:8192
	ds_read_b128 v[108:111], v19 offset:8192
	ds_read_b128 v[112:115], v20 offset:8192
	ds_read_b128 v[116:119], v21 offset:8192
	ds_read_b128 v[120:123], v18 offset:12288
	ds_read_b128 v[124:127], v19 offset:12288
	ds_read_b128 v[128:131], v20 offset:12288
	ds_read_b128 v[132:135], v21 offset:12288
	s_waitcnt lgkmcnt(7)
	v_mfma_f32_16x16x32_bf16 v[136:139], v[104:107], v[88:91], 0
	s_waitcnt lgkmcnt(6)
	v_mfma_f32_16x16x32_bf16 v[136:139], v[108:111], v[92:95], v[136:139]
	s_waitcnt lgkmcnt(5)
	v_mfma_f32_16x16x32_bf16 v[136:139], v[112:115], v[96:99], v[136:139]
	s_waitcnt lgkmcnt(4)
	v_mfma_f32_16x16x32_bf16 v[136:139], v[116:119], v[100:103], v[136:139]
	s_waitcnt lgkmcnt(3)
	v_mfma_f32_16x16x32_bf16 v[140:143], v[120:123], v[88:91], 0
	s_waitcnt lgkmcnt(2)
	v_mfma_f32_16x16x32_bf16 v[140:143], v[124:127], v[92:95], v[140:143]
	s_waitcnt lgkmcnt(1)
	v_mfma_f32_16x16x32_bf16 v[140:143], v[128:131], v[96:99], v[140:143]
	s_waitcnt lgkmcnt(0)
	v_mfma_f32_16x16x32_bf16 v[140:143], v[132:135], v[100:103], v[140:143]
	v_mul_f32_e32 v32, 0x3db504f3, v136
	v_mul_f32_e32 v33, 0x3db504f3, v137
	v_mul_f32_e32 v34, 0x3db504f3, v138
	v_mul_f32_e32 v35, 0x3db504f3, v139
	s_nop 3
	v_mul_f32_e32 v36, 0x3db504f3, v140
	v_mul_f32_e32 v37, 0x3db504f3, v141
	v_mul_f32_e32 v38, 0x3db504f3, v142
	v_mul_f32_e32 v39, 0x3db504f3, v143
	s_add_i32 s18, s14, 192
	s_mov_b64 s[16:17], s[2:3]
	v_add_u32_e32 v161, s18, v156
	ds_read_u16 v0, v161 offset:0
	ds_read_u16 v1, v161 offset:8
	ds_read_u16 v2, v161 offset:16
	ds_read_u16 v3, v161 offset:24
	ds_read_u16 v4, v161 offset:32
	ds_read_u16 v5, v161 offset:40
	ds_read_u16 v6, v161 offset:48
	ds_read_u16 v7, v161 offset:56
	s_waitcnt lgkmcnt(7)
	s_add_i32 m0, s8, 0x2000
	v_lshl_add_u32 v8, v0, 8, v10
	global_load_lds_dwordx4 v8, s[16:17]
	s_waitcnt lgkmcnt(6)
	s_add_i32 m0, s8, 0x2400
	v_lshl_add_u32 v9, v1, 8, v11
	global_load_lds_dwordx4 v9, s[16:17]
	s_waitcnt lgkmcnt(5)
	s_add_i32 m0, s8, 0x2800
	v_lshl_add_u32 v8, v2, 8, v12
	global_load_lds_dwordx4 v8, s[16:17]
	s_waitcnt lgkmcnt(4)
	s_add_i32 m0, s8, 0x2c00
	v_lshl_add_u32 v9, v3, 8, v13
	global_load_lds_dwordx4 v9, s[16:17]
	s_waitcnt lgkmcnt(3)
	s_add_i32 m0, s8, 0x3000
	v_lshl_add_u32 v8, v4, 8, v10
	global_load_lds_dwordx4 v8, s[16:17]
	s_waitcnt lgkmcnt(2)
	s_add_i32 m0, s8, 0x3400
	v_lshl_add_u32 v9, v5, 8, v11
	global_load_lds_dwordx4 v9, s[16:17]
	s_waitcnt lgkmcnt(1)
	s_add_i32 m0, s8, 0x3800
	v_lshl_add_u32 v8, v6, 8, v12
	global_load_lds_dwordx4 v8, s[16:17]
	s_waitcnt lgkmcnt(0)
	s_add_i32 m0, s8, 0x3c00
	v_lshl_add_u32 v9, v7, 8, v13
	global_load_lds_dwordx4 v9, s[16:17]
	s_waitcnt vmcnt(8)
	ds_read_b128 v[104:107], v18 offset:0
	ds_read_b128 v[108:111], v19 offset:0
	ds_read_b128 v[112:115], v20 offset:0
	ds_read_b128 v[116:119], v21 offset:0
	ds_read_b128 v[120:123], v18 offset:4096
	ds_read_b128 v[124:127], v19 offset:4096
	ds_read_b128 v[128:131], v20 offset:4096
	ds_read_b128 v[132:135], v21 offset:4096
	s_waitcnt lgkmcnt(7)
	v_mfma_f32_16x16x32_bf16 v[136:139], v[104:107], v[88:91], 0
	s_waitcnt lgkmcnt(6)
	v_mfma_f32_16x16x32_bf16 v[136:139], v[108:111], v[92:95], v[136:139]
	s_waitcnt lgkmcnt(5)
	v_mfma_f32_16x16x32_bf16 v[136:139], v[112:115], v[96:99], v[136:139]
	s_waitcnt lgkmcnt(4)
	v_mfma_f32_16x16x32_bf16 v[136:139], v[116:119], v[100:103], v[136:139]
	s_waitcnt lgkmcnt(3)
	v_mfma_f32_16x16x32_bf16 v[140:143], v[120:123], v[88:91], 0
	s_waitcnt lgkmcnt(2)
	v_mfma_f32_16x16x32_bf16 v[140:143], v[124:127], v[92:95], v[140:143]
	s_waitcnt lgkmcnt(1)
	v_mfma_f32_16x16x32_bf16 v[140:143], v[128:131], v[96:99], v[140:143]
	s_waitcnt lgkmcnt(0)
	v_mfma_f32_16x16x32_bf16 v[140:143], v[132:135], v[100:103], v[140:143]
	v_mul_f32_e32 v40, 0x3db504f3, v136
	v_mul_f32_e32 v41, 0x3db504f3, v137
	v_mul_f32_e32 v42, 0x3db504f3, v138
	v_mul_f32_e32 v43, 0x3db504f3, v139
	s_nop 3
	v_mul_f32_e32 v44, 0x3db504f3, v140
	v_mul_f32_e32 v45, 0x3db504f3, v141
	v_mul_f32_e32 v46, 0x3db504f3, v142
	v_mul_f32_e32 v47, 0x3db504f3, v143
	s_mov_b32 s18, s14
	s_mov_b64 s[16:17], s[4:5]
	v_add_u32_e32 v161, s18, v156
	ds_read_u16 v0, v161 offset:0
	ds_read_u16 v1, v161 offset:8
	ds_read_u16 v2, v161 offset:16
	ds_read_u16 v3, v161 offset:24
	ds_read_u16 v4, v161 offset:32
	ds_read_u16 v5, v161 offset:40
	ds_read_u16 v6, v161 offset:48
	ds_read_u16 v7, v161 offset:56
	s_waitcnt lgkmcnt(7)
	s_add_i32 m0, s8, 0x0
	v_lshl_add_u32 v8, v0, 8, v10
	global_load_lds_dwordx4 v8, s[16:17]
	s_waitcnt lgkmcnt(6)
	s_add_i32 m0, s8, 0x400
	v_lshl_add_u32 v9, v1, 8, v11
	global_load_lds_dwordx4 v9, s[16:17]
	s_waitcnt lgkmcnt(5)
	s_add_i32 m0, s8, 0x800
	v_lshl_add_u32 v8, v2, 8, v12
	global_load_lds_dwordx4 v8, s[16:17]
	s_waitcnt lgkmcnt(4)
	s_add_i32 m0, s8, 0xc00
	v_lshl_add_u32 v9, v3, 8, v13
	global_load_lds_dwordx4 v9, s[16:17]
	s_waitcnt lgkmcnt(3)
	s_add_i32 m0, s8, 0x1000
	v_lshl_add_u32 v8, v4, 8, v10
	global_load_lds_dwordx4 v8, s[16:17]
	s_waitcnt lgkmcnt(2)
	s_add_i32 m0, s8, 0x1400
	v_lshl_add_u32 v9, v5, 8, v11
	global_load_lds_dwordx4 v9, s[16:17]
	s_waitcnt lgkmcnt(1)
	s_add_i32 m0, s8, 0x1800
	v_lshl_add_u32 v8, v6, 8, v12
	global_load_lds_dwordx4 v8, s[16:17]
	s_waitcnt lgkmcnt(0)
	s_add_i32 m0, s8, 0x1c00
	v_lshl_add_u32 v9, v7, 8, v13
	global_load_lds_dwordx4 v9, s[16:17]
	s_waitcnt vmcnt(8)
	ds_read_b128 v[104:107], v18 offset:8192
	ds_read_b128 v[108:111], v19 offset:8192
	ds_read_b128 v[112:115], v20 offset:8192
	ds_read_b128 v[116:119], v21 offset:8192
	ds_read_b128 v[120:123], v18 offset:12288
	ds_read_b128 v[124:127], v19 offset:12288
	ds_read_b128 v[128:131], v20 offset:12288
	ds_read_b128 v[132:135], v21 offset:12288
	s_waitcnt lgkmcnt(7)
	v_mfma_f32_16x16x32_bf16 v[136:139], v[104:107], v[88:91], 0
	s_waitcnt lgkmcnt(6)
	v_mfma_f32_16x16x32_bf16 v[136:139], v[108:111], v[92:95], v[136:139]
	s_waitcnt lgkmcnt(5)
	v_mfma_f32_16x16x32_bf16 v[136:139], v[112:115], v[96:99], v[136:139]
	s_waitcnt lgkmcnt(4)
	v_mfma_f32_16x16x32_bf16 v[136:139], v[116:119], v[100:103], v[136:139]
	s_waitcnt lgkmcnt(3)
	v_mfma_f32_16x16x32_bf16 v[140:143], v[120:123], v[88:91], 0
	s_waitcnt lgkmcnt(2)
	v_mfma_f32_16x16x32_bf16 v[140:143], v[124:127], v[92:95], v[140:143]
	s_waitcnt lgkmcnt(1)
	v_mfma_f32_16x16x32_bf16 v[140:143], v[128:131], v[96:99], v[140:143]
	s_waitcnt lgkmcnt(0)
	v_mfma_f32_16x16x32_bf16 v[140:143], v[132:135], v[100:103], v[140:143]
	v_mul_f32_e32 v48, 0x3db504f3, v136
	v_mul_f32_e32 v49, 0x3db504f3, v137
	v_mul_f32_e32 v50, 0x3db504f3, v138
	v_mul_f32_e32 v51, 0x3db504f3, v139
	s_nop 3
	v_mul_f32_e32 v52, 0x3db504f3, v140
	v_mul_f32_e32 v53, 0x3db504f3, v141
	v_mul_f32_e32 v54, 0x3db504f3, v142
	v_mul_f32_e32 v55, 0x3db504f3, v143
	v_max3_f32 v163, v24, v25, v26
	v_max3_f32 v163, v163, v27, v28
	v_max3_f32 v163, v163, v29, v30
	v_max3_f32 v163, v163, v31, v32
	v_max3_f32 v163, v163, v33, v34
	v_max3_f32 v163, v163, v35, v36
	v_max3_f32 v163, v163, v37, v38
	v_max3_f32 v163, v163, v39, v40
	v_max3_f32 v163, v163, v41, v42
	v_max3_f32 v163, v163, v43, v44
	v_max3_f32 v163, v163, v45, v46
	v_max3_f32 v163, v163, v47, v48
	v_max3_f32 v163, v163, v49, v50
	v_max3_f32 v163, v163, v51, v52
	v_max3_f32 v163, v163, v53, v54
	v_max_f32_e32 v163, v163, v55
	s_nop 0
	ds_bpermute_b32 v165, v147, v163
	s_waitcnt lgkmcnt(0)
	v_max_f32_e32 v163, v163, v165
	s_nop 0
	ds_bpermute_b32 v165, v146, v163
	s_waitcnt lgkmcnt(0)
	v_max_f32_e32 v163, v163, v165
	v_sub_f32_e32 v165, v24, v163
	v_mul_f32_e32 v165, 0x3fb8aa3b, v165
	v_exp_f32_e32 v24, v165
	v_sub_f32_e32 v166, v25, v163
	v_mul_f32_e32 v166, 0x3fb8aa3b, v166
	v_exp_f32_e32 v25, v166
	v_sub_f32_e32 v167, v26, v163
	v_mul_f32_e32 v167, 0x3fb8aa3b, v167
	v_exp_f32_e32 v26, v167
	v_add_f32_e32 v164, 0, v24
	v_sub_f32_e32 v168, v27, v163
	v_mul_f32_e32 v168, 0x3fb8aa3b, v168
	v_exp_f32_e32 v27, v168
	v_add_f32_e32 v164, v164, v25
	v_sub_f32_e32 v165, v28, v163
	v_mul_f32_e32 v165, 0x3fb8aa3b, v165
	v_exp_f32_e32 v28, v165
	v_add_f32_e32 v164, v164, v26
	v_sub_f32_e32 v166, v29, v163
	v_mul_f32_e32 v166, 0x3fb8aa3b, v166
	v_exp_f32_e32 v29, v166
	v_add_f32_e32 v164, v164, v27
	v_sub_f32_e32 v167, v30, v163
	v_mul_f32_e32 v167, 0x3fb8aa3b, v167
	v_exp_f32_e32 v30, v167
	v_add_f32_e32 v164, v164, v28
	v_sub_f32_e32 v168, v31, v163
	v_mul_f32_e32 v168, 0x3fb8aa3b, v168
	v_exp_f32_e32 v31, v168
	v_add_f32_e32 v164, v164, v29
	v_sub_f32_e32 v165, v32, v163
	v_mul_f32_e32 v165, 0x3fb8aa3b, v165
	v_exp_f32_e32 v32, v165
	v_add_f32_e32 v164, v164, v30
	v_sub_f32_e32 v166, v33, v163
	v_mul_f32_e32 v166, 0x3fb8aa3b, v166
	v_exp_f32_e32 v33, v166
	v_add_f32_e32 v164, v164, v31
	v_sub_f32_e32 v167, v34, v163
	v_mul_f32_e32 v167, 0x3fb8aa3b, v167
	v_exp_f32_e32 v34, v167
	v_add_f32_e32 v164, v164, v32
	v_sub_f32_e32 v168, v35, v163
	v_mul_f32_e32 v168, 0x3fb8aa3b, v168
	v_exp_f32_e32 v35, v168
	v_add_f32_e32 v164, v164, v33
	v_sub_f32_e32 v165, v36, v163
	v_mul_f32_e32 v165, 0x3fb8aa3b, v165
	v_exp_f32_e32 v36, v165
	v_add_f32_e32 v164, v164, v34
	v_sub_f32_e32 v166, v37, v163
	v_mul_f32_e32 v166, 0x3fb8aa3b, v166
	v_exp_f32_e32 v37, v166
	v_add_f32_e32 v164, v164, v35
	v_sub_f32_e32 v167, v38, v163
	v_mul_f32_e32 v167, 0x3fb8aa3b, v167
	v_exp_f32_e32 v38, v167
	v_add_f32_e32 v164, v164, v36
	v_sub_f32_e32 v168, v39, v163
	v_mul_f32_e32 v168, 0x3fb8aa3b, v168
	v_exp_f32_e32 v39, v168
	v_add_f32_e32 v164, v164, v37
	v_sub_f32_e32 v165, v40, v163
	v_mul_f32_e32 v165, 0x3fb8aa3b, v165
	v_exp_f32_e32 v40, v165
	v_add_f32_e32 v164, v164, v38
	v_sub_f32_e32 v166, v41, v163
	v_mul_f32_e32 v166, 0x3fb8aa3b, v166
	v_exp_f32_e32 v41, v166
	v_add_f32_e32 v164, v164, v39
	v_sub_f32_e32 v167, v42, v163
	v_mul_f32_e32 v167, 0x3fb8aa3b, v167
	v_exp_f32_e32 v42, v167
	v_add_f32_e32 v164, v164, v40
	v_sub_f32_e32 v168, v43, v163
	v_mul_f32_e32 v168, 0x3fb8aa3b, v168
	v_exp_f32_e32 v43, v168
	v_add_f32_e32 v164, v164, v41
	v_sub_f32_e32 v165, v44, v163
	v_mul_f32_e32 v165, 0x3fb8aa3b, v165
	v_exp_f32_e32 v44, v165
	v_add_f32_e32 v164, v164, v42
	v_sub_f32_e32 v166, v45, v163
	v_mul_f32_e32 v166, 0x3fb8aa3b, v166
	v_exp_f32_e32 v45, v166
	v_add_f32_e32 v164, v164, v43
	v_sub_f32_e32 v167, v46, v163
	v_mul_f32_e32 v167, 0x3fb8aa3b, v167
	v_exp_f32_e32 v46, v167
	v_add_f32_e32 v164, v164, v44
	v_sub_f32_e32 v168, v47, v163
	v_mul_f32_e32 v168, 0x3fb8aa3b, v168
	v_exp_f32_e32 v47, v168
	v_add_f32_e32 v164, v164, v45
	v_sub_f32_e32 v165, v48, v163
	v_mul_f32_e32 v165, 0x3fb8aa3b, v165
	v_exp_f32_e32 v48, v165
	v_add_f32_e32 v164, v164, v46
	v_sub_f32_e32 v166, v49, v163
	v_mul_f32_e32 v166, 0x3fb8aa3b, v166
	v_exp_f32_e32 v49, v166
	v_add_f32_e32 v164, v164, v47
	v_sub_f32_e32 v167, v50, v163
	v_mul_f32_e32 v167, 0x3fb8aa3b, v167
	v_exp_f32_e32 v50, v167
	v_add_f32_e32 v164, v164, v48
	v_sub_f32_e32 v168, v51, v163
	v_mul_f32_e32 v168, 0x3fb8aa3b, v168
	v_exp_f32_e32 v51, v168
	v_add_f32_e32 v164, v164, v49
	v_sub_f32_e32 v165, v52, v163
	v_mul_f32_e32 v165, 0x3fb8aa3b, v165
	v_exp_f32_e32 v52, v165
	v_add_f32_e32 v164, v164, v50
	v_sub_f32_e32 v166, v53, v163
	v_mul_f32_e32 v166, 0x3fb8aa3b, v166
	v_exp_f32_e32 v53, v166
	v_add_f32_e32 v164, v164, v51
	v_sub_f32_e32 v167, v54, v163
	v_mul_f32_e32 v167, 0x3fb8aa3b, v167
	v_exp_f32_e32 v54, v167
	v_add_f32_e32 v164, v164, v52
	v_sub_f32_e32 v168, v55, v163
	v_mul_f32_e32 v168, 0x3fb8aa3b, v168
	v_exp_f32_e32 v55, v168
	v_add_f32_e32 v164, v164, v53
	s_nop 0
	v_add_f32_e32 v164, v164, v54
	v_add_f32_e32 v164, v164, v55
	s_nop 0
	ds_bpermute_b32 v165, v147, v164
	s_waitcnt lgkmcnt(0)
	v_add_f32_e32 v164, v164, v165
	s_nop 0
	ds_bpermute_b32 v165, v146, v164
	s_waitcnt lgkmcnt(0)
	v_add_f32_e32 v164, v164, v165
	v_div_scale_f32 v170, s[74:75], v164, v164, 1.0
	v_rcp_f32_e32 v171, v170
	s_nop 0
	v_fma_f32 v172, -v170, v171, 1.0
	v_fmac_f32_e32 v171, v172, v171
	v_div_scale_f32 v172, vcc, 1.0, v164, 1.0
	v_mul_f32_e32 v173, v172, v171
	v_fma_f32 v169, -v170, v173, v172
	v_fmac_f32_e32 v173, v169, v171
	v_fma_f32 v170, -v170, v173, v172
	v_div_fmas_f32 v170, v170, v171, v173
	v_div_fixup_f32 v169, v170, v164, 1.0
	v_mul_f32_e32 v165, v24, v169
	v_mul_f32_e32 v166, v25, v169
	v_cvt_pk_bf16_f32 v24, v165, v166
	v_mul_f32_e32 v167, v26, v169
	v_mul_f32_e32 v168, v27, v169
	v_cvt_pk_bf16_f32 v25, v167, v168
	v_mul_f32_e32 v165, v28, v169
	v_mul_f32_e32 v166, v29, v169
	v_cvt_pk_bf16_f32 v26, v165, v166
	v_mul_f32_e32 v167, v30, v169
	v_mul_f32_e32 v168, v31, v169
	v_cvt_pk_bf16_f32 v27, v167, v168
	v_mul_f32_e32 v165, v32, v169
	v_mul_f32_e32 v166, v33, v169
	v_cvt_pk_bf16_f32 v32, v165, v166
	v_mul_f32_e32 v167, v34, v169
	v_mul_f32_e32 v168, v35, v169
	v_cvt_pk_bf16_f32 v33, v167, v168
	v_mul_f32_e32 v165, v36, v169
	v_mul_f32_e32 v166, v37, v169
	v_cvt_pk_bf16_f32 v34, v165, v166
	v_mul_f32_e32 v167, v38, v169
	v_mul_f32_e32 v168, v39, v169
	v_cvt_pk_bf16_f32 v35, v167, v168
	v_mul_f32_e32 v165, v40, v169
	v_mul_f32_e32 v166, v41, v169
	v_cvt_pk_bf16_f32 v40, v165, v166
	v_mul_f32_e32 v167, v42, v169
	v_mul_f32_e32 v168, v43, v169
	v_cvt_pk_bf16_f32 v41, v167, v168
	v_mul_f32_e32 v165, v44, v169
	v_mul_f32_e32 v166, v45, v169
	v_cvt_pk_bf16_f32 v42, v165, v166
	v_mul_f32_e32 v167, v46, v169
	v_mul_f32_e32 v168, v47, v169
	v_cvt_pk_bf16_f32 v43, v167, v168
	v_mul_f32_e32 v165, v48, v169
	v_mul_f32_e32 v166, v49, v169
	v_cvt_pk_bf16_f32 v48, v165, v166
	v_mul_f32_e32 v167, v50, v169
	v_mul_f32_e32 v168, v51, v169
	v_cvt_pk_bf16_f32 v49, v167, v168
	v_mul_f32_e32 v165, v52, v169
	v_mul_f32_e32 v166, v53, v169
	v_cvt_pk_bf16_f32 v50, v165, v166
	v_mul_f32_e32 v167, v54, v169
	v_mul_f32_e32 v168, v55, v169
	v_cvt_pk_bf16_f32 v51, v167, v168
	s_cmp_eq_u32 s11, 1
	s_cbranch_scc1 .Lattn_noq4
	s_add_i32 s15, s12, 1
	s_lshl_b32 s13, s15, 12
	v_add_u32_e32 v162, s13, v157
	global_load_dwordx4 v[88:91], v162, s[6:7] offset:0
	global_load_dwordx4 v[92:95], v162, s[6:7] offset:64
	global_load_dwordx4 v[96:99], v162, s[6:7] offset:128
	global_load_dwordx4 v[100:103], v162, s[6:7] offset:192
.Lattn_noq4:
	s_add_i32 s18, s14, 64
	s_mov_b64 s[16:17], s[4:5]
	v_add_u32_e32 v161, s18, v156
	ds_read_u16 v0, v161 offset:0
	ds_read_u16 v1, v161 offset:8
	ds_read_u16 v2, v161 offset:16
	ds_read_u16 v3, v161 offset:24
	ds_read_u16 v4, v161 offset:32
	ds_read_u16 v5, v161 offset:40
	ds_read_u16 v6, v161 offset:48
	ds_read_u16 v7, v161 offset:56
	s_waitcnt lgkmcnt(7)
	s_add_i32 m0, s8, 0x2000
	v_lshl_add_u32 v8, v0, 8, v10
	global_load_lds_dwordx4 v8, s[16:17]
	s_waitcnt lgkmcnt(6)
	s_add_i32 m0, s8, 0x2400
	v_lshl_add_u32 v9, v1, 8, v11
	global_load_lds_dwordx4 v9, s[16:17]
	s_waitcnt lgkmcnt(5)
	s_add_i32 m0, s8, 0x2800
	v_lshl_add_u32 v8, v2, 8, v12
	global_load_lds_dwordx4 v8, s[16:17]
	s_waitcnt lgkmcnt(4)
	s_add_i32 m0, s8, 0x2c00
	v_lshl_add_u32 v9, v3, 8, v13
	global_load_lds_dwordx4 v9, s[16:17]
	s_waitcnt lgkmcnt(3)
	s_add_i32 m0, s8, 0x3000
	v_lshl_add_u32 v8, v4, 8, v10
	global_load_lds_dwordx4 v8, s[16:17]
	s_waitcnt lgkmcnt(2)
	s_add_i32 m0, s8, 0x3400
	v_lshl_add_u32 v9, v5, 8, v11
	global_load_lds_dwordx4 v9, s[16:17]
	s_waitcnt lgkmcnt(1)
	s_add_i32 m0, s8, 0x3800
	v_lshl_add_u32 v8, v6, 8, v12
	global_load_lds_dwordx4 v8, s[16:17]
	s_waitcnt lgkmcnt(0)
	s_add_i32 m0, s8, 0x3c00
	v_lshl_add_u32 v9, v7, 8, v13
	global_load_lds_dwordx4 v9, s[16:17]
	s_waitcnt vmcnt(8)
	ds_read_b64_tr_b16 v[104:105], v148 offset:0
	ds_read_b64_tr_b16 v[106:107], v148 offset:4096
	ds_read_b64_tr_b16 v[108:109], v149 offset:0
	ds_read_b64_tr_b16 v[110:111], v149 offset:4096
	ds_read_b64_tr_b16 v[112:113], v150 offset:0
	ds_read_b64_tr_b16 v[114:115], v150 offset:4096
	ds_read_b64_tr_b16 v[116:117], v151 offset:0
	ds_read_b64_tr_b16 v[118:119], v151 offset:4096
	ds_read_b64_tr_b16 v[120:121], v152 offset:0
	ds_read_b64_tr_b16 v[122:123], v152 offset:4096
	ds_read_b64_tr_b16 v[124:125], v153 offset:0
	ds_read_b64_tr_b16 v[126:127], v153 offset:4096
	ds_read_b64_tr_b16 v[128:129], v154 offset:0
	ds_read_b64_tr_b16 v[130:131], v154 offset:4096
	s_waitcnt lgkmcnt(12)
	v_mfma_f32_16x16x32_bf16 v[176:179], v[24:27], v[104:107], 0
	ds_read_b64_tr_b16 v[132:133], v155 offset:0
	ds_read_b64_tr_b16 v[134:135], v155 offset:4096
	s_waitcnt lgkmcnt(12)
	v_mfma_f32_16x16x32_bf16 v[180:183], v[24:27], v[108:111], 0
	s_waitcnt lgkmcnt(10)
	v_mfma_f32_16x16x32_bf16 v[184:187], v[24:27], v[112:115], 0
	s_waitcnt lgkmcnt(8)
	v_mfma_f32_16x16x32_bf16 v[188:191], v[24:27], v[116:119], 0
	s_waitcnt lgkmcnt(6)
	v_mfma_f32_16x16x32_bf16 v[192:195], v[24:27], v[120:123], 0
	s_waitcnt lgkmcnt(4)
	v_mfma_f32_16x16x32_bf16 v[196:199], v[24:27], v[124:127], 0
	s_waitcnt lgkmcnt(2)
	v_mfma_f32_16x16x32_bf16 v[200:203], v[24:27], v[128:131], 0
	s_waitcnt lgkmcnt(0)
	v_mfma_f32_16x16x32_bf16 v[204:207], v[24:27], v[132:135], 0
	s_add_i32 s18, s14, 128
	s_mov_b64 s[16:17], s[4:5]
	v_add_u32_e32 v161, s18, v156
	ds_read_u16 v0, v161 offset:0
	ds_read_u16 v1, v161 offset:8
	ds_read_u16 v2, v161 offset:16
	ds_read_u16 v3, v161 offset:24
	ds_read_u16 v4, v161 offset:32
	ds_read_u16 v5, v161 offset:40
	ds_read_u16 v6, v161 offset:48
	ds_read_u16 v7, v161 offset:56
	s_waitcnt lgkmcnt(7)
	s_add_i32 m0, s8, 0x0
	v_lshl_add_u32 v8, v0, 8, v10
	global_load_lds_dwordx4 v8, s[16:17]
	s_waitcnt lgkmcnt(6)
	s_add_i32 m0, s8, 0x400
	v_lshl_add_u32 v9, v1, 8, v11
	global_load_lds_dwordx4 v9, s[16:17]
	s_waitcnt lgkmcnt(5)
	s_add_i32 m0, s8, 0x800
	v_lshl_add_u32 v8, v2, 8, v12
	global_load_lds_dwordx4 v8, s[16:17]
	s_waitcnt lgkmcnt(4)
	s_add_i32 m0, s8, 0xc00
	v_lshl_add_u32 v9, v3, 8, v13
	global_load_lds_dwordx4 v9, s[16:17]
	s_waitcnt lgkmcnt(3)
	s_add_i32 m0, s8, 0x1000
	v_lshl_add_u32 v8, v4, 8, v10
	global_load_lds_dwordx4 v8, s[16:17]
	s_waitcnt lgkmcnt(2)
	s_add_i32 m0, s8, 0x1400
	v_lshl_add_u32 v9, v5, 8, v11
	global_load_lds_dwordx4 v9, s[16:17]
	s_waitcnt lgkmcnt(1)
	s_add_i32 m0, s8, 0x1800
	v_lshl_add_u32 v8, v6, 8, v12
	global_load_lds_dwordx4 v8, s[16:17]
	s_waitcnt lgkmcnt(0)
	s_add_i32 m0, s8, 0x1c00
	v_lshl_add_u32 v9, v7, 8, v13
	global_load_lds_dwordx4 v9, s[16:17]
	s_waitcnt vmcnt(8)
	ds_read_b64_tr_b16 v[104:105], v148 offset:8192
	ds_read_b64_tr_b16 v[106:107], v148 offset:12288
	ds_read_b64_tr_b16 v[108:109], v149 offset:8192
	ds_read_b64_tr_b16 v[110:111], v149 offset:12288
	ds_read_b64_tr_b16 v[112:113], v150 offset:8192
	ds_read_b64_tr_b16 v[114:115], v150 offset:12288
	ds_read_b64_tr_b16 v[116:117], v151 offset:8192
	ds_read_b64_tr_b16 v[118:119], v151 offset:12288
	ds_read_b64_tr_b16 v[120:121], v152 offset:8192
	ds_read_b64_tr_b16 v[122:123], v152 offset:12288
	ds_read_b64_tr_b16 v[124:125], v153 offset:8192
	ds_read_b64_tr_b16 v[126:127], v153 offset:12288
	ds_read_b64_tr_b16 v[128:129], v154 offset:8192
	ds_read_b64_tr_b16 v[130:131], v154 offset:12288
	s_waitcnt lgkmcnt(12)
	v_mfma_f32_16x16x32_bf16 v[176:179], v[32:35], v[104:107], v[176:179]
	ds_read_b64_tr_b16 v[132:133], v155 offset:8192
	ds_read_b64_tr_b16 v[134:135], v155 offset:12288
	s_waitcnt lgkmcnt(12)
	v_mfma_f32_16x16x32_bf16 v[180:183], v[32:35], v[108:111], v[180:183]
	s_waitcnt lgkmcnt(10)
	v_mfma_f32_16x16x32_bf16 v[184:187], v[32:35], v[112:115], v[184:187]
	s_waitcnt lgkmcnt(8)
	v_mfma_f32_16x16x32_bf16 v[188:191], v[32:35], v[116:119], v[188:191]
	s_waitcnt lgkmcnt(6)
	v_mfma_f32_16x16x32_bf16 v[192:195], v[32:35], v[120:123], v[192:195]
	s_waitcnt lgkmcnt(4)
	v_mfma_f32_16x16x32_bf16 v[196:199], v[32:35], v[124:127], v[196:199]
	s_waitcnt lgkmcnt(2)
	v_mfma_f32_16x16x32_bf16 v[200:203], v[32:35], v[128:131], v[200:203]
	s_waitcnt lgkmcnt(0)
	v_mfma_f32_16x16x32_bf16 v[204:207], v[32:35], v[132:135], v[204:207]
	s_add_i32 s18, s14, 192
	s_mov_b64 s[16:17], s[4:5]
	v_add_u32_e32 v161, s18, v156
	ds_read_u16 v0, v161 offset:0
	ds_read_u16 v1, v161 offset:8
	ds_read_u16 v2, v161 offset:16
	ds_read_u16 v3, v161 offset:24
	ds_read_u16 v4, v161 offset:32
	ds_read_u16 v5, v161 offset:40
	ds_read_u16 v6, v161 offset:48
	ds_read_u16 v7, v161 offset:56
	s_waitcnt lgkmcnt(7)
	s_add_i32 m0, s8, 0x2000
	v_lshl_add_u32 v8, v0, 8, v10
	global_load_lds_dwordx4 v8, s[16:17]
	s_waitcnt lgkmcnt(6)
	s_add_i32 m0, s8, 0x2400
	v_lshl_add_u32 v9, v1, 8, v11
	global_load_lds_dwordx4 v9, s[16:17]
	s_waitcnt lgkmcnt(5)
	s_add_i32 m0, s8, 0x2800
	v_lshl_add_u32 v8, v2, 8, v12
	global_load_lds_dwordx4 v8, s[16:17]
	s_waitcnt lgkmcnt(4)
	s_add_i32 m0, s8, 0x2c00
	v_lshl_add_u32 v9, v3, 8, v13
	global_load_lds_dwordx4 v9, s[16:17]
	s_waitcnt lgkmcnt(3)
	s_add_i32 m0, s8, 0x3000
	v_lshl_add_u32 v8, v4, 8, v10
	global_load_lds_dwordx4 v8, s[16:17]
	s_waitcnt lgkmcnt(2)
	s_add_i32 m0, s8, 0x3400
	v_lshl_add_u32 v9, v5, 8, v11
	global_load_lds_dwordx4 v9, s[16:17]
	s_waitcnt lgkmcnt(1)
	s_add_i32 m0, s8, 0x3800
	v_lshl_add_u32 v8, v6, 8, v12
	global_load_lds_dwordx4 v8, s[16:17]
	s_waitcnt lgkmcnt(0)
	s_add_i32 m0, s8, 0x3c00
	v_lshl_add_u32 v9, v7, 8, v13
	global_load_lds_dwordx4 v9, s[16:17]
	s_waitcnt vmcnt(8)
	ds_read_b64_tr_b16 v[104:105], v148 offset:0
	ds_read_b64_tr_b16 v[106:107], v148 offset:4096
	ds_read_b64_tr_b16 v[108:109], v149 offset:0
	ds_read_b64_tr_b16 v[110:111], v149 offset:4096
	ds_read_b64_tr_b16 v[112:113], v150 offset:0
	ds_read_b64_tr_b16 v[114:115], v150 offset:4096
	ds_read_b64_tr_b16 v[116:117], v151 offset:0
	ds_read_b64_tr_b16 v[118:119], v151 offset:4096
	ds_read_b64_tr_b16 v[120:121], v152 offset:0
	ds_read_b64_tr_b16 v[122:123], v152 offset:4096
	ds_read_b64_tr_b16 v[124:125], v153 offset:0
	ds_read_b64_tr_b16 v[126:127], v153 offset:4096
	ds_read_b64_tr_b16 v[128:129], v154 offset:0
	ds_read_b64_tr_b16 v[130:131], v154 offset:4096
	s_waitcnt lgkmcnt(12)
	v_mfma_f32_16x16x32_bf16 v[176:179], v[40:43], v[104:107], v[176:179]
	ds_read_b64_tr_b16 v[132:133], v155 offset:0
	ds_read_b64_tr_b16 v[134:135], v155 offset:4096
	s_waitcnt lgkmcnt(12)
	v_mfma_f32_16x16x32_bf16 v[180:183], v[40:43], v[108:111], v[180:183]
	s_waitcnt lgkmcnt(10)
	v_mfma_f32_16x16x32_bf16 v[184:187], v[40:43], v[112:115], v[184:187]
	s_waitcnt lgkmcnt(8)
	v_mfma_f32_16x16x32_bf16 v[188:191], v[40:43], v[116:119], v[188:191]
	s_waitcnt lgkmcnt(6)
	v_mfma_f32_16x16x32_bf16 v[192:195], v[40:43], v[120:123], v[192:195]
	s_waitcnt lgkmcnt(4)
	v_mfma_f32_16x16x32_bf16 v[196:199], v[40:43], v[124:127], v[196:199]
	s_waitcnt lgkmcnt(2)
	v_mfma_f32_16x16x32_bf16 v[200:203], v[40:43], v[128:131], v[200:203]
	s_waitcnt lgkmcnt(0)
	v_mfma_f32_16x16x32_bf16 v[204:207], v[40:43], v[132:135], v[204:207]
	s_cmp_eq_u32 s11, 1
	s_cbranch_scc1 .Lattn_lastv4
	s_add_i32 s18, s14, 512
	s_mov_b64 s[16:17], s[2:3]
	v_add_u32_e32 v161, s18, v156
	ds_read_u16 v0, v161 offset:0
	ds_read_u16 v1, v161 offset:8
	ds_read_u16 v2, v161 offset:16
	ds_read_u16 v3, v161 offset:24
	ds_read_u16 v4, v161 offset:32
	ds_read_u16 v5, v161 offset:40
	ds_read_u16 v6, v161 offset:48
	ds_read_u16 v7, v161 offset:56
	s_waitcnt lgkmcnt(7)
	s_add_i32 m0, s8, 0x0
	v_lshl_add_u32 v8, v0, 8, v10
	global_load_lds_dwordx4 v8, s[16:17]
	s_waitcnt lgkmcnt(6)
	s_add_i32 m0, s8, 0x400
	v_lshl_add_u32 v9, v1, 8, v11
	global_load_lds_dwordx4 v9, s[16:17]
	s_waitcnt lgkmcnt(5)
	s_add_i32 m0, s8, 0x800
	v_lshl_add_u32 v8, v2, 8, v12
	global_load_lds_dwordx4 v8, s[16:17]
	s_waitcnt lgkmcnt(4)
	s_add_i32 m0, s8, 0xc00
	v_lshl_add_u32 v9, v3, 8, v13
	global_load_lds_dwordx4 v9, s[16:17]
	s_waitcnt lgkmcnt(3)
	s_add_i32 m0, s8, 0x1000
	v_lshl_add_u32 v8, v4, 8, v10
	global_load_lds_dwordx4 v8, s[16:17]
	s_waitcnt lgkmcnt(2)
	s_add_i32 m0, s8, 0x1400
	v_lshl_add_u32 v9, v5, 8, v11
	global_load_lds_dwordx4 v9, s[16:17]
	s_waitcnt lgkmcnt(1)
	s_add_i32 m0, s8, 0x1800
	v_lshl_add_u32 v8, v6, 8, v12
	global_load_lds_dwordx4 v8, s[16:17]
	s_waitcnt lgkmcnt(0)
	s_add_i32 m0, s8, 0x1c00
	v_lshl_add_u32 v9, v7, 8, v13
	global_load_lds_dwordx4 v9, s[16:17]
	s_waitcnt vmcnt(8)
	s_branch .Lattn_lastj4

.Lattn_lastj4:
	ds_read_b64_tr_b16 v[104:105], v148 offset:8192
	ds_read_b64_tr_b16 v[106:107], v148 offset:12288
	ds_read_b64_tr_b16 v[108:109], v149 offset:8192
	ds_read_b64_tr_b16 v[110:111], v149 offset:12288
	ds_read_b64_tr_b16 v[112:113], v150 offset:8192
	ds_read_b64_tr_b16 v[114:115], v150 offset:12288
	ds_read_b64_tr_b16 v[116:117], v151 offset:8192
	ds_read_b64_tr_b16 v[118:119], v151 offset:12288
	ds_read_b64_tr_b16 v[120:121], v152 offset:8192
	ds_read_b64_tr_b16 v[122:123], v152 offset:12288
	ds_read_b64_tr_b16 v[124:125], v153 offset:8192
	ds_read_b64_tr_b16 v[126:127], v153 offset:12288
	ds_read_b64_tr_b16 v[128:129], v154 offset:8192
	ds_read_b64_tr_b16 v[130:131], v154 offset:12288
	s_waitcnt lgkmcnt(12)
	v_mfma_f32_16x16x32_bf16 v[176:179], v[48:51], v[104:107], v[176:179]
	ds_read_b64_tr_b16 v[132:133], v155 offset:8192
	ds_read_b64_tr_b16 v[134:135], v155 offset:12288
	s_waitcnt lgkmcnt(12)
	v_mfma_f32_16x16x32_bf16 v[180:183], v[48:51], v[108:111], v[180:183]
	s_waitcnt lgkmcnt(10)
	v_mfma_f32_16x16x32_bf16 v[184:187], v[48:51], v[112:115], v[184:187]
	s_waitcnt lgkmcnt(8)
	v_mfma_f32_16x16x32_bf16 v[188:191], v[48:51], v[116:119], v[188:191]
	s_waitcnt lgkmcnt(6)
	v_mfma_f32_16x16x32_bf16 v[192:195], v[48:51], v[120:123], v[192:195]
	s_waitcnt lgkmcnt(4)
	v_mfma_f32_16x16x32_bf16 v[196:199], v[48:51], v[124:127], v[196:199]
	s_waitcnt lgkmcnt(2)
	v_mfma_f32_16x16x32_bf16 v[200:203], v[48:51], v[128:131], v[200:203]
	s_waitcnt lgkmcnt(0)
	v_mfma_f32_16x16x32_bf16 v[204:207], v[48:51], v[132:135], v[204:207]
	s_nop 7
	s_mov_b32 exec_lo, -1
	s_mov_b32 exec_hi, 0
	v_cvt_pk_bf16_f32 v165, v176, 0
	ds_write_b16 v158, v165 offset:0
	v_cvt_pk_bf16_f32 v166, v177, 0
	ds_write_b16 v158, v166 offset:256
	v_cvt_pk_bf16_f32 v167, v178, 0
	ds_write_b16 v158, v167 offset:512
	v_cvt_pk_bf16_f32 v168, v179, 0
	ds_write_b16 v158, v168 offset:768
	v_cvt_pk_bf16_f32 v165, v180, 0
	ds_write_b16 v158, v165 offset:32
	v_cvt_pk_bf16_f32 v166, v181, 0
	ds_write_b16 v158, v166 offset:288
	v_cvt_pk_bf16_f32 v167, v182, 0
	ds_write_b16 v158, v167 offset:544
	v_cvt_pk_bf16_f32 v168, v183, 0
	ds_write_b16 v158, v168 offset:800
	v_cvt_pk_bf16_f32 v165, v184, 0
	ds_write_b16 v158, v165 offset:64
	v_cvt_pk_bf16_f32 v166, v185, 0
	ds_write_b16 v158, v166 offset:320
	v_cvt_pk_bf16_f32 v167, v186, 0
	ds_write_b16 v158, v167 offset:576
	v_cvt_pk_bf16_f32 v168, v187, 0
	ds_write_b16 v158, v168 offset:832
	v_cvt_pk_bf16_f32 v165, v188, 0
	ds_write_b16 v158, v165 offset:96
	v_cvt_pk_bf16_f32 v166, v189, 0
	ds_write_b16 v158, v166 offset:352
	v_cvt_pk_bf16_f32 v167, v190, 0
	ds_write_b16 v158, v167 offset:608
	v_cvt_pk_bf16_f32 v168, v191, 0
	ds_write_b16 v158, v168 offset:864
	v_cvt_pk_bf16_f32 v165, v192, 0
	ds_write_b16 v158, v165 offset:128
	v_cvt_pk_bf16_f32 v166, v193, 0
	ds_write_b16 v158, v166 offset:384
	v_cvt_pk_bf16_f32 v167, v194, 0
	ds_write_b16 v158, v167 offset:640
	v_cvt_pk_bf16_f32 v168, v195, 0
	ds_write_b16 v158, v168 offset:896
	v_cvt_pk_bf16_f32 v165, v196, 0
	ds_write_b16 v158, v165 offset:160
	v_cvt_pk_bf16_f32 v166, v197, 0
	ds_write_b16 v158, v166 offset:416
	v_cvt_pk_bf16_f32 v167, v198, 0
	ds_write_b16 v158, v167 offset:672
	v_cvt_pk_bf16_f32 v168, v199, 0
	ds_write_b16 v158, v168 offset:928
	v_cvt_pk_bf16_f32 v165, v200, 0
	ds_write_b16 v158, v165 offset:192
	v_cvt_pk_bf16_f32 v166, v201, 0
	ds_write_b16 v158, v166 offset:448
	v_cvt_pk_bf16_f32 v167, v202, 0
	ds_write_b16 v158, v167 offset:704
	v_cvt_pk_bf16_f32 v168, v203, 0
	ds_write_b16 v158, v168 offset:960
	v_cvt_pk_bf16_f32 v165, v204, 0
	ds_write_b16 v158, v165 offset:224
	v_cvt_pk_bf16_f32 v166, v205, 0
	ds_write_b16 v158, v166 offset:480
	v_cvt_pk_bf16_f32 v167, v206, 0
	ds_write_b16 v158, v167 offset:736
	v_cvt_pk_bf16_f32 v168, v207, 0
	ds_write_b16 v158, v168 offset:992
	s_mov_b64 exec, -1
	s_waitcnt lgkmcnt(0)
	ds_read_b128 v[104:107], v159
	ds_read_b128 v[108:111], v159 offset:1024
	s_lshl_b32 s13, s12, 12
	v_add_u32_e32 v162, s13, v160
	s_waitcnt lgkmcnt(1)
	global_store_dwordx4 v162, v[104:107], s[6:7]
	s_waitcnt lgkmcnt(0)
	global_store_dwordx4 v162, v[108:111], s[6:7] offset:1024
	s_add_i32 s11, s11, 1
	s_add_i32 s12, s12, 1
	s_addk_i32 s14, 0x200
	s_cmp_lt_u32 s11, 2
	s_cbranch_scc1 .Lattn_q4
	s_branch .Lattn_done
.Lattn_q2:
	s_add_i32 s18, s14, 64
	s_mov_b64 s[16:17], s[2:3]
	v_add_u32_e32 v161, s18, v156
	ds_read_u16 v0, v161 offset:0
	ds_read_u16 v1, v161 offset:8
	ds_read_u16 v2, v161 offset:16
	ds_read_u16 v3, v161 offset:24
	ds_read_u16 v4, v161 offset:32
	ds_read_u16 v5, v161 offset:40
	ds_read_u16 v6, v161 offset:48
	ds_read_u16 v7, v161 offset:56
	s_waitcnt lgkmcnt(7)
	s_add_i32 m0, s8, 0x2000
	v_lshl_add_u32 v8, v0, 8, v10
	global_load_lds_dwordx4 v8, s[16:17]
	s_waitcnt lgkmcnt(6)
	s_add_i32 m0, s8, 0x2400
	v_lshl_add_u32 v9, v1, 8, v11
	global_load_lds_dwordx4 v9, s[16:17]
	s_waitcnt lgkmcnt(5)
	s_add_i32 m0, s8, 0x2800
	v_lshl_add_u32 v8, v2, 8, v12
	global_load_lds_dwordx4 v8, s[16:17]
	s_waitcnt lgkmcnt(4)
	s_add_i32 m0, s8, 0x2c00
	v_lshl_add_u32 v9, v3, 8, v13
	global_load_lds_dwordx4 v9, s[16:17]
	s_waitcnt lgkmcnt(3)
	s_add_i32 m0, s8, 0x3000
	v_lshl_add_u32 v8, v4, 8, v10
	global_load_lds_dwordx4 v8, s[16:17]
	s_waitcnt lgkmcnt(2)
	s_add_i32 m0, s8, 0x3400
	v_lshl_add_u32 v9, v5, 8, v11
	global_load_lds_dwordx4 v9, s[16:17]
	s_waitcnt lgkmcnt(1)
	s_add_i32 m0, s8, 0x3800
	v_lshl_add_u32 v8, v6, 8, v12
	global_load_lds_dwordx4 v8, s[16:17]
	s_waitcnt lgkmcnt(0)
	s_add_i32 m0, s8, 0x3c00
	v_lshl_add_u32 v9, v7, 8, v13
	global_load_lds_dwordx4 v9, s[16:17]
	s_waitcnt vmcnt(8)
	ds_read_b128 v[104:107], v18 offset:0
	ds_read_b128 v[108:111], v19 offset:0
	ds_read_b128 v[112:115], v20 offset:0
	ds_read_b128 v[116:119], v21 offset:0
	ds_read_b128 v[120:123], v18 offset:4096
	ds_read_b128 v[124:127], v19 offset:4096
	ds_read_b128 v[128:131], v20 offset:4096
	ds_read_b128 v[132:135], v21 offset:4096
	s_waitcnt lgkmcnt(7)
	v_mfma_f32_16x16x32_bf16 v[136:139], v[104:107], v[88:91], 0
	s_waitcnt lgkmcnt(6)
	v_mfma_f32_16x16x32_bf16 v[136:139], v[108:111], v[92:95], v[136:139]
	s_waitcnt lgkmcnt(5)
	v_mfma_f32_16x16x32_bf16 v[136:139], v[112:115], v[96:99], v[136:139]
	s_waitcnt lgkmcnt(4)
	v_mfma_f32_16x16x32_bf16 v[136:139], v[116:119], v[100:103], v[136:139]
	s_waitcnt lgkmcnt(3)
	v_mfma_f32_16x16x32_bf16 v[140:143], v[120:123], v[88:91], 0
	s_waitcnt lgkmcnt(2)
	v_mfma_f32_16x16x32_bf16 v[140:143], v[124:127], v[92:95], v[140:143]
	s_waitcnt lgkmcnt(1)
	v_mfma_f32_16x16x32_bf16 v[140:143], v[128:131], v[96:99], v[140:143]
	s_waitcnt lgkmcnt(0)
	v_mfma_f32_16x16x32_bf16 v[140:143], v[132:135], v[100:103], v[140:143]
	v_mul_f32_e32 v24, 0x3db504f3, v136
	v_mul_f32_e32 v25, 0x3db504f3, v137
	v_mul_f32_e32 v26, 0x3db504f3, v138
	v_mul_f32_e32 v27, 0x3db504f3, v139
	s_nop 3
	v_mul_f32_e32 v28, 0x3db504f3, v140
	v_mul_f32_e32 v29, 0x3db504f3, v141
	v_mul_f32_e32 v30, 0x3db504f3, v142
	v_mul_f32_e32 v31, 0x3db504f3, v143
	s_mov_b32 s18, s14
	s_mov_b64 s[16:17], s[4:5]
	v_add_u32_e32 v161, s18, v156
	ds_read_u16 v0, v161 offset:0
	ds_read_u16 v1, v161 offset:8
	ds_read_u16 v2, v161 offset:16
	ds_read_u16 v3, v161 offset:24
	ds_read_u16 v4, v161 offset:32
	ds_read_u16 v5, v161 offset:40
	ds_read_u16 v6, v161 offset:48
	ds_read_u16 v7, v161 offset:56
	s_waitcnt lgkmcnt(7)
	s_add_i32 m0, s8, 0x0
	v_lshl_add_u32 v8, v0, 8, v10
	global_load_lds_dwordx4 v8, s[16:17]
	s_waitcnt lgkmcnt(6)
	s_add_i32 m0, s8, 0x400
	v_lshl_add_u32 v9, v1, 8, v11
	global_load_lds_dwordx4 v9, s[16:17]
	s_waitcnt lgkmcnt(5)
	s_add_i32 m0, s8, 0x800
	v_lshl_add_u32 v8, v2, 8, v12
	global_load_lds_dwordx4 v8, s[16:17]
	s_waitcnt lgkmcnt(4)
	s_add_i32 m0, s8, 0xc00
	v_lshl_add_u32 v9, v3, 8, v13
	global_load_lds_dwordx4 v9, s[16:17]
	s_waitcnt lgkmcnt(3)
	s_add_i32 m0, s8, 0x1000
	v_lshl_add_u32 v8, v4, 8, v10
	global_load_lds_dwordx4 v8, s[16:17]
	s_waitcnt lgkmcnt(2)
	s_add_i32 m0, s8, 0x1400
	v_lshl_add_u32 v9, v5, 8, v11
	global_load_lds_dwordx4 v9, s[16:17]
	s_waitcnt lgkmcnt(1)
	s_add_i32 m0, s8, 0x1800
	v_lshl_add_u32 v8, v6, 8, v12
	global_load_lds_dwordx4 v8, s[16:17]
	s_waitcnt lgkmcnt(0)
	s_add_i32 m0, s8, 0x1c00
	v_lshl_add_u32 v9, v7, 8, v13
	global_load_lds_dwordx4 v9, s[16:17]
	s_waitcnt vmcnt(8)
	ds_read_b128 v[104:107], v18 offset:8192
	ds_read_b128 v[108:111], v19 offset:8192
	ds_read_b128 v[112:115], v20 offset:8192
	ds_read_b128 v[116:119], v21 offset:8192
	ds_read_b128 v[120:123], v18 offset:12288
	ds_read_b128 v[124:127], v19 offset:12288
	ds_read_b128 v[128:131], v20 offset:12288
	ds_read_b128 v[132:135], v21 offset:12288
	s_waitcnt lgkmcnt(7)
	v_mfma_f32_16x16x32_bf16 v[136:139], v[104:107], v[88:91], 0
	s_waitcnt lgkmcnt(6)
	v_mfma_f32_16x16x32_bf16 v[136:139], v[108:111], v[92:95], v[136:139]
	s_waitcnt lgkmcnt(5)
	v_mfma_f32_16x16x32_bf16 v[136:139], v[112:115], v[96:99], v[136:139]
	s_waitcnt lgkmcnt(4)
	v_mfma_f32_16x16x32_bf16 v[136:139], v[116:119], v[100:103], v[136:139]
	s_waitcnt lgkmcnt(3)
	v_mfma_f32_16x16x32_bf16 v[140:143], v[120:123], v[88:91], 0
	s_waitcnt lgkmcnt(2)
	v_mfma_f32_16x16x32_bf16 v[140:143], v[124:127], v[92:95], v[140:143]
	s_waitcnt lgkmcnt(1)
	v_mfma_f32_16x16x32_bf16 v[140:143], v[128:131], v[96:99], v[140:143]
	s_waitcnt lgkmcnt(0)
	v_mfma_f32_16x16x32_bf16 v[140:143], v[132:135], v[100:103], v[140:143]
	v_mul_f32_e32 v32, 0x3db504f3, v136
	v_mul_f32_e32 v33, 0x3db504f3, v137
	v_mul_f32_e32 v34, 0x3db504f3, v138
	v_mul_f32_e32 v35, 0x3db504f3, v139
	s_nop 3
	v_mul_f32_e32 v36, 0x3db504f3, v140
	v_mul_f32_e32 v37, 0x3db504f3, v141
	v_mul_f32_e32 v38, 0x3db504f3, v142
	v_mul_f32_e32 v39, 0x3db504f3, v143
	v_max3_f32 v163, v24, v25, v26
	v_max3_f32 v163, v163, v27, v28
	v_max3_f32 v163, v163, v29, v30
	v_max3_f32 v163, v163, v31, v32
	v_max3_f32 v163, v163, v33, v34
	v_max3_f32 v163, v163, v35, v36
	v_max3_f32 v163, v163, v37, v38
	v_max_f32_e32 v163, v163, v39
	s_nop 0
	ds_bpermute_b32 v165, v147, v163
	s_waitcnt lgkmcnt(0)
	v_max_f32_e32 v163, v163, v165
	s_nop 0
	ds_bpermute_b32 v165, v146, v163
	s_waitcnt lgkmcnt(0)
	v_max_f32_e32 v163, v163, v165
	v_sub_f32_e32 v165, v24, v163
	v_mul_f32_e32 v165, 0x3fb8aa3b, v165
	v_exp_f32_e32 v24, v165
	v_sub_f32_e32 v166, v25, v163
	v_mul_f32_e32 v166, 0x3fb8aa3b, v166
	v_exp_f32_e32 v25, v166
	v_sub_f32_e32 v167, v26, v163
	v_mul_f32_e32 v167, 0x3fb8aa3b, v167
	v_exp_f32_e32 v26, v167
	v_add_f32_e32 v164, 0, v24
	v_sub_f32_e32 v168, v27, v163
	v_mul_f32_e32 v168, 0x3fb8aa3b, v168
	v_exp_f32_e32 v27, v168
	v_add_f32_e32 v164, v164, v25
	v_sub_f32_e32 v165, v28, v163
	v_mul_f32_e32 v165, 0x3fb8aa3b, v165
	v_exp_f32_e32 v28, v165
	v_add_f32_e32 v164, v164, v26
	v_sub_f32_e32 v166, v29, v163
	v_mul_f32_e32 v166, 0x3fb8aa3b, v166
	v_exp_f32_e32 v29, v166
	v_add_f32_e32 v164, v164, v27
	v_sub_f32_e32 v167, v30, v163
	v_mul_f32_e32 v167, 0x3fb8aa3b, v167
	v_exp_f32_e32 v30, v167
	v_add_f32_e32 v164, v164, v28
	v_sub_f32_e32 v168, v31, v163
	v_mul_f32_e32 v168, 0x3fb8aa3b, v168
	v_exp_f32_e32 v31, v168
	v_add_f32_e32 v164, v164, v29
	v_sub_f32_e32 v165, v32, v163
	v_mul_f32_e32 v165, 0x3fb8aa3b, v165
	v_exp_f32_e32 v32, v165
	v_add_f32_e32 v164, v164, v30
	v_sub_f32_e32 v166, v33, v163
	v_mul_f32_e32 v166, 0x3fb8aa3b, v166
	v_exp_f32_e32 v33, v166
	v_add_f32_e32 v164, v164, v31
	v_sub_f32_e32 v167, v34, v163
	v_mul_f32_e32 v167, 0x3fb8aa3b, v167
	v_exp_f32_e32 v34, v167
	v_add_f32_e32 v164, v164, v32
	v_sub_f32_e32 v168, v35, v163
	v_mul_f32_e32 v168, 0x3fb8aa3b, v168
	v_exp_f32_e32 v35, v168
	v_add_f32_e32 v164, v164, v33
	v_sub_f32_e32 v165, v36, v163
	v_mul_f32_e32 v165, 0x3fb8aa3b, v165
	v_exp_f32_e32 v36, v165
	v_add_f32_e32 v164, v164, v34
	v_sub_f32_e32 v166, v37, v163
	v_mul_f32_e32 v166, 0x3fb8aa3b, v166
	v_exp_f32_e32 v37, v166
	v_add_f32_e32 v164, v164, v35
	v_sub_f32_e32 v167, v38, v163
	v_mul_f32_e32 v167, 0x3fb8aa3b, v167
	v_exp_f32_e32 v38, v167
	v_add_f32_e32 v164, v164, v36
	v_sub_f32_e32 v168, v39, v163
	v_mul_f32_e32 v168, 0x3fb8aa3b, v168
	v_exp_f32_e32 v39, v168
	v_add_f32_e32 v164, v164, v37
	s_nop 0
	v_add_f32_e32 v164, v164, v38
	v_add_f32_e32 v164, v164, v39
	s_nop 0
	ds_bpermute_b32 v165, v147, v164
	s_waitcnt lgkmcnt(0)
	v_add_f32_e32 v164, v164, v165
	s_nop 0
	ds_bpermute_b32 v165, v146, v164
	s_waitcnt lgkmcnt(0)
	v_add_f32_e32 v164, v164, v165
	v_div_scale_f32 v170, s[74:75], v164, v164, 1.0
	v_rcp_f32_e32 v171, v170
	s_nop 0
	v_fma_f32 v172, -v170, v171, 1.0
	v_fmac_f32_e32 v171, v172, v171
	v_div_scale_f32 v172, vcc, 1.0, v164, 1.0
	v_mul_f32_e32 v173, v172, v171
	v_fma_f32 v169, -v170, v173, v172
	v_fmac_f32_e32 v173, v169, v171
	v_fma_f32 v170, -v170, v173, v172
	v_div_fmas_f32 v170, v170, v171, v173
	v_div_fixup_f32 v169, v170, v164, 1.0
	v_mul_f32_e32 v165, v24, v169
	v_mul_f32_e32 v166, v25, v169
	v_cvt_pk_bf16_f32 v24, v165, v166
	v_mul_f32_e32 v167, v26, v169
	v_mul_f32_e32 v168, v27, v169
	v_cvt_pk_bf16_f32 v25, v167, v168
	v_mul_f32_e32 v165, v28, v169
	v_mul_f32_e32 v166, v29, v169
	v_cvt_pk_bf16_f32 v26, v165, v166
	v_mul_f32_e32 v167, v30, v169
	v_mul_f32_e32 v168, v31, v169
	v_cvt_pk_bf16_f32 v27, v167, v168
	v_mul_f32_e32 v165, v32, v169
	v_mul_f32_e32 v166, v33, v169
	v_cvt_pk_bf16_f32 v32, v165, v166
	v_mul_f32_e32 v167, v34, v169
	v_mul_f32_e32 v168, v35, v169
	v_cvt_pk_bf16_f32 v33, v167, v168
	v_mul_f32_e32 v165, v36, v169
	v_mul_f32_e32 v166, v37, v169
	v_cvt_pk_bf16_f32 v34, v165, v166
	v_mul_f32_e32 v167, v38, v169
	v_mul_f32_e32 v168, v39, v169
	v_cvt_pk_bf16_f32 v35, v167, v168
	s_cmp_eq_u32 s11, 1
	s_cbranch_scc1 .Lattn_noq2
	s_add_i32 s15, s12, 1
	s_lshl_b32 s13, s15, 12
	v_add_u32_e32 v162, s13, v157
	global_load_dwordx4 v[88:91], v162, s[6:7] offset:0
	global_load_dwordx4 v[92:95], v162, s[6:7] offset:64
	global_load_dwordx4 v[96:99], v162, s[6:7] offset:128
	global_load_dwordx4 v[100:103], v162, s[6:7] offset:192
.Lattn_noq2:
	s_add_i32 s18, s14, 64
	s_mov_b64 s[16:17], s[4:5]
	v_add_u32_e32 v161, s18, v156
	ds_read_u16 v0, v161 offset:0
	ds_read_u16 v1, v161 offset:8
	ds_read_u16 v2, v161 offset:16
	ds_read_u16 v3, v161 offset:24
	ds_read_u16 v4, v161 offset:32
	ds_read_u16 v5, v161 offset:40
	ds_read_u16 v6, v161 offset:48
	ds_read_u16 v7, v161 offset:56
	s_waitcnt lgkmcnt(7)
	s_add_i32 m0, s8, 0x2000
	v_lshl_add_u32 v8, v0, 8, v10
	global_load_lds_dwordx4 v8, s[16:17]
	s_waitcnt lgkmcnt(6)
	s_add_i32 m0, s8, 0x2400
	v_lshl_add_u32 v9, v1, 8, v11
	global_load_lds_dwordx4 v9, s[16:17]
	s_waitcnt lgkmcnt(5)
	s_add_i32 m0, s8, 0x2800
	v_lshl_add_u32 v8, v2, 8, v12
	global_load_lds_dwordx4 v8, s[16:17]
	s_waitcnt lgkmcnt(4)
	s_add_i32 m0, s8, 0x2c00
	v_lshl_add_u32 v9, v3, 8, v13
	global_load_lds_dwordx4 v9, s[16:17]
	s_waitcnt lgkmcnt(3)
	s_add_i32 m0, s8, 0x3000
	v_lshl_add_u32 v8, v4, 8, v10
	global_load_lds_dwordx4 v8, s[16:17]
	s_waitcnt lgkmcnt(2)
	s_add_i32 m0, s8, 0x3400
	v_lshl_add_u32 v9, v5, 8, v11
	global_load_lds_dwordx4 v9, s[16:17]
	s_waitcnt lgkmcnt(1)
	s_add_i32 m0, s8, 0x3800
	v_lshl_add_u32 v8, v6, 8, v12
	global_load_lds_dwordx4 v8, s[16:17]
	s_waitcnt lgkmcnt(0)
	s_add_i32 m0, s8, 0x3c00
	v_lshl_add_u32 v9, v7, 8, v13
	global_load_lds_dwordx4 v9, s[16:17]
	s_waitcnt vmcnt(8)
	ds_read_b64_tr_b16 v[104:105], v148 offset:0
	ds_read_b64_tr_b16 v[106:107], v148 offset:4096
	ds_read_b64_tr_b16 v[108:109], v149 offset:0
	ds_read_b64_tr_b16 v[110:111], v149 offset:4096
	ds_read_b64_tr_b16 v[112:113], v150 offset:0
	ds_read_b64_tr_b16 v[114:115], v150 offset:4096
	ds_read_b64_tr_b16 v[116:117], v151 offset:0
	ds_read_b64_tr_b16 v[118:119], v151 offset:4096
	ds_read_b64_tr_b16 v[120:121], v152 offset:0
	ds_read_b64_tr_b16 v[122:123], v152 offset:4096
	ds_read_b64_tr_b16 v[124:125], v153 offset:0
	ds_read_b64_tr_b16 v[126:127], v153 offset:4096
	ds_read_b64_tr_b16 v[128:129], v154 offset:0
	ds_read_b64_tr_b16 v[130:131], v154 offset:4096
	s_waitcnt lgkmcnt(12)
	v_mfma_f32_16x16x32_bf16 v[176:179], v[24:27], v[104:107], 0
	ds_read_b64_tr_b16 v[132:133], v155 offset:0
	ds_read_b64_tr_b16 v[134:135], v155 offset:4096
	s_waitcnt lgkmcnt(12)
	v_mfma_f32_16x16x32_bf16 v[180:183], v[24:27], v[108:111], 0
	s_waitcnt lgkmcnt(10)
	v_mfma_f32_16x16x32_bf16 v[184:187], v[24:27], v[112:115], 0
	s_waitcnt lgkmcnt(8)
	v_mfma_f32_16x16x32_bf16 v[188:191], v[24:27], v[116:119], 0
	s_waitcnt lgkmcnt(6)
	v_mfma_f32_16x16x32_bf16 v[192:195], v[24:27], v[120:123], 0
	s_waitcnt lgkmcnt(4)
	v_mfma_f32_16x16x32_bf16 v[196:199], v[24:27], v[124:127], 0
	s_waitcnt lgkmcnt(2)
	v_mfma_f32_16x16x32_bf16 v[200:203], v[24:27], v[128:131], 0
	s_waitcnt lgkmcnt(0)
	v_mfma_f32_16x16x32_bf16 v[204:207], v[24:27], v[132:135], 0
	s_cmp_eq_u32 s11, 1
	s_cbranch_scc1 .Lattn_lastv2
	s_add_i32 s18, s14, 512
	s_mov_b64 s[16:17], s[2:3]
	v_add_u32_e32 v161, s18, v156
	ds_read_u16 v0, v161 offset:0
	ds_read_u16 v1, v161 offset:8
	ds_read_u16 v2, v161 offset:16
	ds_read_u16 v3, v161 offset:24
	ds_read_u16 v4, v161 offset:32
	ds_read_u16 v5, v161 offset:40
	ds_read_u16 v6, v161 offset:48
	ds_read_u16 v7, v161 offset:56
	s_waitcnt lgkmcnt(7)
	s_add_i32 m0, s8, 0x0
	v_lshl_add_u32 v8, v0, 8, v10
	global_load_lds_dwordx4 v8, s[16:17]
	s_waitcnt lgkmcnt(6)
	s_add_i32 m0, s8, 0x400
	v_lshl_add_u32 v9, v1, 8, v11
	global_load_lds_dwordx4 v9, s[16:17]
	s_waitcnt lgkmcnt(5)
	s_add_i32 m0, s8, 0x800
	v_lshl_add_u32 v8, v2, 8, v12
	global_load_lds_dwordx4 v8, s[16:17]
	s_waitcnt lgkmcnt(4)
	s_add_i32 m0, s8, 0xc00
	v_lshl_add_u32 v9, v3, 8, v13
	global_load_lds_dwordx4 v9, s[16:17]
	s_waitcnt lgkmcnt(3)
	s_add_i32 m0, s8, 0x1000
	v_lshl_add_u32 v8, v4, 8, v10
	global_load_lds_dwordx4 v8, s[16:17]
	s_waitcnt lgkmcnt(2)
	s_add_i32 m0, s8, 0x1400
	v_lshl_add_u32 v9, v5, 8, v11
	global_load_lds_dwordx4 v9, s[16:17]
	s_waitcnt lgkmcnt(1)
	s_add_i32 m0, s8, 0x1800
	v_lshl_add_u32 v8, v6, 8, v12
	global_load_lds_dwordx4 v8, s[16:17]
	s_waitcnt lgkmcnt(0)
	s_add_i32 m0, s8, 0x1c00
	v_lshl_add_u32 v9, v7, 8, v13
	global_load_lds_dwordx4 v9, s[16:17]
	s_waitcnt vmcnt(8)
	s_branch .Lattn_lastj2

.Lattn_lastj2:
	ds_read_b64_tr_b16 v[104:105], v148 offset:8192
	ds_read_b64_tr_b16 v[106:107], v148 offset:12288
	ds_read_b64_tr_b16 v[108:109], v149 offset:8192
	ds_read_b64_tr_b16 v[110:111], v149 offset:12288
	ds_read_b64_tr_b16 v[112:113], v150 offset:8192
	ds_read_b64_tr_b16 v[114:115], v150 offset:12288
	ds_read_b64_tr_b16 v[116:117], v151 offset:8192
	ds_read_b64_tr_b16 v[118:119], v151 offset:12288
	ds_read_b64_tr_b16 v[120:121], v152 offset:8192
	ds_read_b64_tr_b16 v[122:123], v152 offset:12288
	ds_read_b64_tr_b16 v[124:125], v153 offset:8192
	ds_read_b64_tr_b16 v[126:127], v153 offset:12288
	ds_read_b64_tr_b16 v[128:129], v154 offset:8192
	ds_read_b64_tr_b16 v[130:131], v154 offset:12288
	s_waitcnt lgkmcnt(12)
	v_mfma_f32_16x16x32_bf16 v[176:179], v[32:35], v[104:107], v[176:179]
	ds_read_b64_tr_b16 v[132:133], v155 offset:8192
	ds_read_b64_tr_b16 v[134:135], v155 offset:12288
	s_waitcnt lgkmcnt(12)
	v_mfma_f32_16x16x32_bf16 v[180:183], v[32:35], v[108:111], v[180:183]
	s_waitcnt lgkmcnt(10)
	v_mfma_f32_16x16x32_bf16 v[184:187], v[32:35], v[112:115], v[184:187]
	s_waitcnt lgkmcnt(8)
	v_mfma_f32_16x16x32_bf16 v[188:191], v[32:35], v[116:119], v[188:191]
	s_waitcnt lgkmcnt(6)
	v_mfma_f32_16x16x32_bf16 v[192:195], v[32:35], v[120:123], v[192:195]
	s_waitcnt lgkmcnt(4)
	v_mfma_f32_16x16x32_bf16 v[196:199], v[32:35], v[124:127], v[196:199]
	s_waitcnt lgkmcnt(2)
	v_mfma_f32_16x16x32_bf16 v[200:203], v[32:35], v[128:131], v[200:203]
	s_waitcnt lgkmcnt(0)
	v_mfma_f32_16x16x32_bf16 v[204:207], v[32:35], v[132:135], v[204:207]
	s_nop 7
	s_mov_b32 exec_lo, -1
	s_mov_b32 exec_hi, 0
	v_cvt_pk_bf16_f32 v165, v176, 0
	ds_write_b16 v158, v165 offset:0
	v_cvt_pk_bf16_f32 v166, v177, 0
	ds_write_b16 v158, v166 offset:256
	v_cvt_pk_bf16_f32 v167, v178, 0
	ds_write_b16 v158, v167 offset:512
	v_cvt_pk_bf16_f32 v168, v179, 0
	ds_write_b16 v158, v168 offset:768
	v_cvt_pk_bf16_f32 v165, v180, 0
	ds_write_b16 v158, v165 offset:32
	v_cvt_pk_bf16_f32 v166, v181, 0
	ds_write_b16 v158, v166 offset:288
	v_cvt_pk_bf16_f32 v167, v182, 0
	ds_write_b16 v158, v167 offset:544
	v_cvt_pk_bf16_f32 v168, v183, 0
	ds_write_b16 v158, v168 offset:800
	v_cvt_pk_bf16_f32 v165, v184, 0
	ds_write_b16 v158, v165 offset:64
	v_cvt_pk_bf16_f32 v166, v185, 0
	ds_write_b16 v158, v166 offset:320
	v_cvt_pk_bf16_f32 v167, v186, 0
	ds_write_b16 v158, v167 offset:576
	v_cvt_pk_bf16_f32 v168, v187, 0
	ds_write_b16 v158, v168 offset:832
	v_cvt_pk_bf16_f32 v165, v188, 0
	ds_write_b16 v158, v165 offset:96
	v_cvt_pk_bf16_f32 v166, v189, 0
	ds_write_b16 v158, v166 offset:352
	v_cvt_pk_bf16_f32 v167, v190, 0
	ds_write_b16 v158, v167 offset:608
	v_cvt_pk_bf16_f32 v168, v191, 0
	ds_write_b16 v158, v168 offset:864
	v_cvt_pk_bf16_f32 v165, v192, 0
	ds_write_b16 v158, v165 offset:128
	v_cvt_pk_bf16_f32 v166, v193, 0
	ds_write_b16 v158, v166 offset:384
	v_cvt_pk_bf16_f32 v167, v194, 0
	ds_write_b16 v158, v167 offset:640
	v_cvt_pk_bf16_f32 v168, v195, 0
	ds_write_b16 v158, v168 offset:896
	v_cvt_pk_bf16_f32 v165, v196, 0
	ds_write_b16 v158, v165 offset:160
	v_cvt_pk_bf16_f32 v166, v197, 0
	ds_write_b16 v158, v166 offset:416
	v_cvt_pk_bf16_f32 v167, v198, 0
	ds_write_b16 v158, v167 offset:672
	v_cvt_pk_bf16_f32 v168, v199, 0
	ds_write_b16 v158, v168 offset:928
	v_cvt_pk_bf16_f32 v165, v200, 0
	ds_write_b16 v158, v165 offset:192
	v_cvt_pk_bf16_f32 v166, v201, 0
	ds_write_b16 v158, v166 offset:448
	v_cvt_pk_bf16_f32 v167, v202, 0
	ds_write_b16 v158, v167 offset:704
	v_cvt_pk_bf16_f32 v168, v203, 0
	ds_write_b16 v158, v168 offset:960
	v_cvt_pk_bf16_f32 v165, v204, 0
	ds_write_b16 v158, v165 offset:224
	v_cvt_pk_bf16_f32 v166, v205, 0
	ds_write_b16 v158, v166 offset:480
	v_cvt_pk_bf16_f32 v167, v206, 0
	ds_write_b16 v158, v167 offset:736
	v_cvt_pk_bf16_f32 v168, v207, 0
	ds_write_b16 v158, v168 offset:992
	s_mov_b64 exec, -1
	s_waitcnt lgkmcnt(0)
	ds_read_b128 v[104:107], v159
	ds_read_b128 v[108:111], v159 offset:1024
	s_lshl_b32 s13, s12, 12
	v_add_u32_e32 v162, s13, v160
	s_waitcnt lgkmcnt(1)
	global_store_dwordx4 v162, v[104:107], s[6:7]
	s_waitcnt lgkmcnt(0)
	global_store_dwordx4 v162, v[108:111], s[6:7] offset:1024
	s_add_i32 s11, s11, 1
	s_add_i32 s12, s12, 1
	s_addk_i32 s14, 0x200
	s_cmp_lt_u32 s11, 2
	s_cbranch_scc1 .Lattn_q2
	s_branch .Lattn_done
.Lattn_done:
	s_branch .LBB0_185
.LBB0_539:
	v_readlane_b32 s0, v252, 7
	s_waitcnt vmcnt(0)
	s_barrier
	s_nop 0
	v_or_b32_e32 v0, s0, v11
	v_readlane_b32 s0, v252, 20
	v_readlane_b32 s1, v252, 21
	s_andn2_b64 vcc, exec, s[0:1]
	v_readfirstlane_b32 s4, v0
	s_cbranch_vccnz .LBB0_639
	v_lshlrev_b32_e32 v1, 4, v0
	v_add_u32_e32 v2, 0x2000, v1
	v_ashrrev_i32_e32 v3, 31, v2
	v_lshrrev_b32_e32 v3, 22, v3
	v_add_u32_e32 v3, v2, v3
	v_ashrrev_i32_e32 v8, 10, v3
	v_mul_i32_i24_e32 v3, 0x400, v8
	v_sub_u32_e32 v2, v2, v3
	v_lshrrev_b32_e32 v3, 4, v2
	v_bitop3_b32 v2, v3, v2, 32 bitop3:0x6c
	v_ashrrev_i32_e32 v3, 31, v2
	v_lshrrev_b32_e32 v3, 26, v3
	v_add_u32_e32 v3, v2, v3
	v_lshlrev_b32_e32 v4, 3, v8
	v_ashrrev_i32_e32 v9, 6, v3
	v_and_b32_e32 v4, -16, v4
	v_add_u32_e32 v4, v9, v4
	v_and_b32_e32 v5, 3, v9
	s_mov_b32 s2, 0x3fffe0
	v_lshrrev_b32_e32 v6, 2, v4
	v_lshlrev_b32_e32 v7, 1, v4
	v_and_or_b32 v5, v4, s2, v5
	v_and_b32_e32 v6, 4, v6
	v_and_b32_e32 v7, 24, v7
	v_and_b32_e32 v3, 0xc0, v3
	v_or3_b32 v5, v5, v6, v7
	v_sub_u32_e32 v2, v2, v3
	v_mov_b32_e32 v7, 1
	v_lshlrev_b32_e32 v6, 5, v8
	v_ashrrev_i16_sdwa v2, v7, sext(v2) dst_sel:DWORD dst_unused:UNUSED_PAD src0_sel:DWORD src1_sel:BYTE_0
	v_and_b32_e32 v6, 32, v6
	v_bfe_i32 v10, v2, 0, 16
	v_add_lshl_u32 v2, v6, v10, 1
	v_lshl_add_u32 v158, v5, 10, v2
	v_lshl_add_u32 v160, v4, 10, v2
	v_bfe_i32 v2, v0, 27, 1
	v_lshrrev_b32_e32 v2, 22, v2
	v_add_u32_e32 v2, v1, v2
	v_readlane_b32 s0, v253, 56
	v_and_b32_e32 v2, 0xfffffc00, v2
	v_readlane_b32 s1, v253, 57
	v_sub_u32_e32 v1, v1, v2
	s_load_dwordx16 s[8:23], s[0:1], 0xc8
	v_lshrrev_b32_e32 v2, 4, v1
	v_ashrrev_i32_e32 v3, 31, v0
	v_bitop3_b32 v1, v2, v1, 32 bitop3:0x6c
	v_lshrrev_b32_e32 v3, 26, v3
	v_ashrrev_i32_e32 v2, 31, v1
	v_add_u32_e32 v0, v0, v3
	v_lshrrev_b32_e32 v2, 26, v2
	v_ashrrev_i32_e32 v13, 6, v0
	v_add_u32_e32 v2, v1, v2
	v_lshlrev_b32_e32 v0, 3, v13
	s_waitcnt lgkmcnt(0)
	s_add_u32 s0, s22, 0x7a00000
	v_ashrrev_i32_e32 v12, 6, v2
	v_and_b32_e32 v0, -16, v0
	s_addc_u32 s1, s23, 0
	v_add_u32_e32 v0, v12, v0
	s_add_u32 s28, s22, 0x7880000
	v_and_b32_e32 v3, 3, v12
	v_lshrrev_b32_e32 v4, 2, v0
	v_lshlrev_b32_e32 v5, 1, v0
	v_and_b32_e32 v2, 0xc0, v2
	s_addc_u32 s29, s23, 0
	s_ashr_i32 s14, s4, 6
	v_and_or_b32 v3, v0, s2, v3
	v_and_b32_e32 v4, 4, v4
	v_and_b32_e32 v5, 24, v5
	v_sub_u32_e32 v1, v1, v2
	s_ashr_i32 s5, s4, 8
	s_lshl_b32 s30, s14, 10
	v_or3_b32 v3, v3, v4, v5
	v_lshlrev_b32_e32 v4, 5, v13
	v_ashrrev_i16_sdwa v1, v7, sext(v1) dst_sel:DWORD dst_unused:UNUSED_PAD src0_sel:DWORD src1_sel:BYTE_0
	v_readlane_b32 s2, v252, 63
	v_and_b32_e32 v4, 32, v4
	v_bfe_i32 v14, v1, 0, 16
	v_readlane_b32 s3, v253, 0
	s_add_u32 s8, s28, s2
	v_add_lshl_u32 v1, v4, v14, 1
	s_addc_u32 s9, s29, s3
	s_add_i32 s31, s30, 0
	v_lshl_add_u32 v2, v3, 10, v1
	s_add_i32 m0, s31, 0x10000
	v_readlane_b32 s2, v252, 59
	global_load_lds_dwordx4 v2, s[8:9]
	s_add_i32 m0, s31, 0x12000
	v_readlane_b32 s3, v252, 60
	s_add_u32 s6, s0, s2
	s_addc_u32 s7, s1, s3
	s_add_u32 s2, s8, 0x20000
	global_load_lds_dwordx4 v158, s[8:9]
	s_addc_u32 s3, s9, 0
	s_add_i32 m0, s31, 0x14000
	v_lshl_add_u32 v162, v0, 10, v1
	global_load_lds_dwordx4 v2, s[2:3]
	s_add_i32 m0, s31, 0x16000
	v_mov_b32_e32 v16, v2
	global_load_lds_dwordx4 v158, s[2:3]
	v_readlane_b32 s2, v252, 62
	s_add_u32 s6, s6, s2
	s_addc_u32 s7, s7, 0
	s_add_i32 s34, s31, 0x2000
	s_mov_b32 m0, s31
	s_add_u32 s2, s6, 0x20000
	global_load_lds_dwordx4 v162, s[6:7]
	s_mov_b32 m0, s34
	s_addc_u32 s3, s7, 0
	s_add_i32 s35, s31, 0x4000
	global_load_lds_dwordx4 v160, s[6:7]
	s_mov_b32 m0, s35
	s_add_i32 s36, s31, 0x6000
	global_load_lds_dwordx4 v162, s[2:3]
	s_mov_b32 m0, s36
	v_mov_b32_e32 v159, v17
	global_load_lds_dwordx4 v160, s[2:3]
	v_mov_b32_e32 v163, v17
	v_mov_b32_e32 v161, v17
	s_cmp_eq_u32 s5, 1
	v_lshl_add_u64 v[6:7], s[8:9], 0, v[16:17]
	v_lshl_add_u64 v[4:5], s[8:9], 0, v[158:159]
	v_lshl_add_u64 v[0:1], s[6:7], 0, v[162:163]
	s_cselect_b64 s[2:3], -1, 0
	s_cmp_lg_u32 s5, 1
	v_lshl_add_u64 v[2:3], s[6:7], 0, v[160:161]
	s_cbranch_scc1 .LBB0_542
	s_barrier
